# GEMM K loops start from literal-zero accumulators (no zeroing pass); row2 x ring 10 deep
# baseline (speedup 1.0000x reference)
; DI void wait_vm0() { asm volatile("s_waitcnt vmcnt(0)" ::: "memory"); }
; DI f4 mfma16(h8 a, h8 b, f4 c) { return __builtin_amdgcn_mfma_f32_16x16x32_f16(a, b, c, 0, 0, 0); }
; DI h8 lds128(unsigned a) { h8 r; asm volatile("ds_read_b128 %0, %1" : "=v"(r) : "v"(a)); return r; }
; DI void tie(h8& x) { asm volatile("" : "+v"(x)); }
; DI unsigned lds_addr(const void* p) { return (unsigned)(size_t)p; }
; #define WAIT_LGKM(n) asm volatile("s_waitcnt lgkmcnt(" #n ")" ::: "memory")
; DI void raw_barrier() { asm volatile("" ::: "memory"); __builtin_amdgcn_s_barrier(); asm volatile("" ::: "memory"); }
; template <bool PRE = false, class AF, class BF>
; DI void gemm256(AF aptr, BF bptr, int nk, char* smem, f4 (&acc)[8][4]) {
;     ...
;   auto issue = [&](int kt, int st) {
;     char* d = smem + st * 49152 + tid * 16;
; #pragma unroll
;     for (int i = 0; i < 8; i++) glds16(aptr(i) + kt * 64, d + i * 4096);
; #pragma unroll
;     for (int i = 0; i < 4; i++) glds16(bptr(i) + kt * 64, d + 32768 + i * 4096);
;   };
;   const unsigned sw = (unsigned)((fq ^ (fr >> 1)) << 4);
;   const unsigned offA = (wr * 128 + fr) * 128 + sw, offB = 32768 + (wc * 64 + fr) * 128 + sw;
;   const unsigned sbase = lds_addr(smem);
;   if (!PRE) { issue(0, 0); if (nk > 1) issue(1, 1); }
;   int st = 0;
; #pragma unroll 1
;   for (int kt = 0; kt < nk; kt++) {
;     if (kt + 1 < nk) asm volatile("s_waitcnt vmcnt(12)" ::: "memory"); else wait_vm0();
;     raw_barrier();
;     if (kt + 2 < nk) issue(kt + 2, st == 0 ? 2 : st - 1);
;     const unsigned base = sbase + st * 49152;
;     st = st == 2 ? 0 : st + 1;
;     h8 a0[8], b0[4], a1[8], b1[4];
; #pragma unroll
;     for (int m = 0; m < 8; m++) a0[m] = lds128(base + offA + m * 2048);
; #pragma unroll
;     for (int n = 0; n < 4; n++) b0[n] = lds128(base + offB + n * 2048);
; #pragma unroll
;     for (int m = 0; m < 8; m++) a1[m] = lds128(base + (offA ^ 64) + m * 2048);
; #pragma unroll
;     for (int n = 0; n < 4; n++) b1[n] = lds128(base + (offB ^ 64) + n * 2048);
;     WAIT_LGKM(12);
; #pragma unroll
;     for (int m = 0; m < 8; m++) tie(a0[m]);
; #pragma unroll
;     for (int n = 0; n < 4; n++) tie(b0[n]);
; #pragma unroll
;     for (int m = 0; m < 8; m++)
; #pragma unroll
;       for (int n = 0; n < 4; n++) acc[m][n] = mfma16(a0[m], b0[n], acc[m][n]);
.LBB0_225:
	v_mov_b32_e32 v0, v172
	s_mov_b32 s2, 0x8040
	v_lshlrev_b32_e32 v1, 3, v0
	v_and_b32_e32 v2, 48, v0
	v_bitop3_b32 v1, v1, v2, s36 bitop3:0x6c
	v_lshlrev_b32_e32 v2, 7, v0
	v_and_b32_e32 v3, 0xffffc780, v2
	v_and_b32_e32 v2, 0x2780, v2
	v_or_b32_e32 v4, v1, v2
	s_mov_b32 s22, s28
	v_or_b32_e32 v24, v1, v3
	v_or_b32_e32 v25, 0x8000, v4
	v_lshlrev_b32_e32 v26, 4, v0
	v_bitop3_b32 v27, v1, 64, v3 bitop3:0x36
	v_bitop3_b32 v28, v1, s2, v2 bitop3:0x36
	s_mov_b32 s6, 0
	s_mov_b64 s[2:3], 0
	s_mov_b32 s7, 0
	v_readfirstlane_b32 s100, v26
	s_waitcnt vmcnt(12)
	s_barrier
	s_add_u32 s101, s100, 0x18000
	v_lshl_add_u64 v[10:11], v[96:97], 0, s[2:3]
	s_add_u32 m0, s101, 0x0
	v_lshl_add_u64 v[14:15], v[10:11], 0, s[74:75]
	global_load_lds_dwordx4 v[14:15], off
	s_add_u32 m0, s101, 0x1000
	v_lshl_add_u64 v[14:15], v[10:11], 0, s[76:77]
	global_load_lds_dwordx4 v[14:15], off
	s_add_u32 m0, s101, 0x2000
	v_lshl_add_u64 v[14:15], v[10:11], 0, s[86:87]
	global_load_lds_dwordx4 v[14:15], off
	s_add_u32 m0, s101, 0x3000
	v_lshl_add_u64 v[14:15], v[10:11], 0, s[80:81]
	global_load_lds_dwordx4 v[14:15], off
	s_add_u32 m0, s101, 0x4000
	v_lshl_add_u64 v[14:15], v[10:11], 0, s[72:73]
	global_load_lds_dwordx4 v[14:15], off
	s_add_u32 m0, s101, 0x5000
	v_lshl_add_u64 v[14:15], v[10:11], 0, s[96:97]
	global_load_lds_dwordx4 v[14:15], off
	ds_read_b128 v[62:65], v25 offset:0
	ds_read_b128 v[66:69], v25 offset:2048
	ds_read_b128 v[70:73], v25 offset:4096
	ds_read_b128 v[74:77], v25 offset:6144
	ds_read_b128 v[30:33], v24 offset:0
	ds_read_b128 v[34:37], v24 offset:2048
	ds_read_b128 v[38:41], v24 offset:4096
	ds_read_b128 v[42:45], v24 offset:6144
	ds_read_b128 v[46:49], v24 offset:8192
	ds_read_b128 v[50:53], v24 offset:10240
	ds_read_b128 v[54:57], v24 offset:12288
	ds_read_b128 v[58:61], v24 offset:14336
	s_mul_i32 s9, s7, 0xc000
	v_add_u32_e32 v8, s9, v27
	v_add_u32_e32 v9, s9, v28
	s_add_u32 s101, s7, 2
	s_sub_u32 s8, s101, 3
	s_cmp_lt_u32 s101, 3
	s_cselect_b32 s101, s101, s8
	s_mul_i32 s101, s101, 0xc000
	s_add_u32 s101, s101, s100
	s_waitcnt lgkmcnt(0)
	v_mfma_f32_16x16x32_f16 a[0:3], v[30:33], v[62:65], 0
	ds_read_b128 a[200:203], v9 offset:0
	v_mfma_f32_16x16x32_f16 a[4:7], v[30:33], v[66:69], 0
	v_lshl_add_u64 v[10:11], v[96:97], 0, s[2:3]
	s_add_u32 m0, s101, 0x6000
	v_lshl_add_u64 v[14:15], v[10:11], 0, s[12:13]
	global_load_lds_dwordx4 v[14:15], off
	v_mfma_f32_16x16x32_f16 a[8:11], v[30:33], v[70:73], 0
	ds_read_b128 a[204:207], v9 offset:2048
	v_mfma_f32_16x16x32_f16 a[12:15], v[30:33], v[74:77], 0
	v_mfma_f32_16x16x32_f16 a[16:19], v[34:37], v[62:65], 0
	ds_read_b128 a[208:211], v9 offset:4096
	v_mfma_f32_16x16x32_f16 a[28:31], v[34:37], v[66:69], 0
	s_add_u32 m0, s101, 0x7000
	v_lshl_add_u64 v[14:15], v[10:11], 0, s[16:17]
	global_load_lds_dwordx4 v[14:15], off
	v_mfma_f32_16x16x32_f16 a[52:55], v[34:37], v[70:73], 0
	ds_read_b128 a[212:215], v9 offset:6144
	v_mfma_f32_16x16x32_f16 a[68:71], v[34:37], v[74:77], 0
	v_mfma_f32_16x16x32_f16 a[88:91], v[38:41], v[62:65], 0
	ds_read_b128 v[78:81], v8 offset:0
	v_mfma_f32_16x16x32_f16 a[108:111], v[38:41], v[66:69], 0
	v_lshl_add_u64 v[12:13], v[94:95], 0, s[2:3]
	s_add_u32 m0, s101, 0x8000
	v_lshl_add_u64 v[14:15], v[12:13], 0, s[74:75]
	global_load_lds_dwordx4 v[14:15], off
	v_mfma_f32_16x16x32_f16 a[124:127], v[38:41], v[70:73], 0
	ds_read_b128 v[82:85], v8 offset:2048
	v_mfma_f32_16x16x32_f16 a[120:123], v[38:41], v[74:77], 0
	v_mfma_f32_16x16x32_f16 a[116:119], v[42:45], v[62:65], 0
	ds_read_b128 v[0:3], v8 offset:4096
	v_mfma_f32_16x16x32_f16 a[112:115], v[42:45], v[66:69], 0
	s_add_u32 m0, s101, 0x9000
	v_lshl_add_u64 v[14:15], v[12:13], 0, s[76:77]
	global_load_lds_dwordx4 v[14:15], off
	v_mfma_f32_16x16x32_f16 a[104:107], v[42:45], v[70:73], 0
	ds_read_b128 v[4:7], v8 offset:6144
	v_mfma_f32_16x16x32_f16 a[100:103], v[42:45], v[74:77], 0
	v_mfma_f32_16x16x32_f16 a[96:99], v[46:49], v[62:65], 0
	ds_read_b128 v[86:89], v8 offset:8192
	v_mfma_f32_16x16x32_f16 a[92:95], v[46:49], v[66:69], 0
	s_add_u32 m0, s101, 0xa000
	v_lshl_add_u64 v[14:15], v[12:13], 0, s[86:87]
	global_load_lds_dwordx4 v[14:15], off
	v_mfma_f32_16x16x32_f16 a[84:87], v[46:49], v[70:73], 0
	ds_read_b128 v[90:93], v8 offset:10240
	v_mfma_f32_16x16x32_f16 a[80:83], v[46:49], v[74:77], 0
	v_mfma_f32_16x16x32_f16 a[76:79], v[50:53], v[62:65], 0
	ds_read_b128 v[100:103], v8 offset:12288
	v_mfma_f32_16x16x32_f16 a[72:75], v[50:53], v[66:69], 0
	s_add_u32 m0, s101, 0xb000
	v_lshl_add_u64 v[14:15], v[12:13], 0, s[80:81]
	global_load_lds_dwordx4 v[14:15], off
	v_mfma_f32_16x16x32_f16 a[64:67], v[50:53], v[70:73], 0
	ds_read_b128 v[104:107], v8 offset:14336
	v_mfma_f32_16x16x32_f16 a[60:63], v[50:53], v[74:77], 0
	v_mfma_f32_16x16x32_f16 a[56:59], v[54:57], v[62:65], 0
	v_mfma_f32_16x16x32_f16 a[48:51], v[54:57], v[66:69], 0
	s_add_u32 s8, s7, 1
	v_mfma_f32_16x16x32_f16 a[44:47], v[54:57], v[70:73], 0
	s_cmp_eq_u32 s8, 3
	v_mfma_f32_16x16x32_f16 a[40:43], v[54:57], v[74:77], 0
	s_cselect_b32 s8, 0, s8
	v_mfma_f32_16x16x32_f16 a[36:39], v[58:61], v[62:65], 0
	s_mul_i32 s9, s8, 0xc000
	v_mfma_f32_16x16x32_f16 a[32:35], v[58:61], v[66:69], 0
	v_add_u32_e32 v22, s9, v24
	v_mfma_f32_16x16x32_f16 a[24:27], v[58:61], v[70:73], 0
	v_add_u32_e32 v23, s9, v25
	v_mfma_f32_16x16x32_f16 a[20:23], v[58:61], v[74:77], 0
	s_branch .Lg_gin_mid

; #define TIDX tid_opaque()
; DI void wait_vm0() { asm volatile("s_waitcnt vmcnt(0)" ::: "memory"); }
; DI f4 mfma16(h8 a, h8 b, f4 c) { return __builtin_amdgcn_mfma_f32_16x16x32_f16(a, b, c, 0, 0, 0); }
; DI h8 lds128(unsigned a) { h8 r; asm volatile("ds_read_b128 %0, %1" : "=v"(r) : "v"(a)); return r; }
; DI void tie(h8& x) { asm volatile("" : "+v"(x)); }
; DI unsigned lds_addr(const void* p) { return (unsigned)(size_t)p; }
; template <bool PRE = false, class AF, class BF>
; DI void gemm256(AF aptr, BF bptr, int nk, char* smem, f4 (&acc)[8][4]) {
;   const int tid = TIDX, lane = tid & 63, wave = tid >> 6, fr = lane & 15, fq = lane >> 4, wr = wave >> 1, wc = wave & 1;
; #pragma unroll
;   for (int m = 0; m < 8; m++)
; #pragma unroll
;     for (int n = 0; n < 4; n++) acc[m][n] = (f4){0.f, 0.f, 0.f, 0.f};
;   auto issue = [&](int kt, int st) {
;     char* d = smem + st * 49152 + tid * 16;
; #pragma unroll
;     for (int i = 0; i < 8; i++) glds16(aptr(i) + kt * 64, d + i * 4096);
; #pragma unroll
;     for (int i = 0; i < 4; i++) glds16(bptr(i) + kt * 64, d + 32768 + i * 4096);
;   };
;   const unsigned sw = (unsigned)((fq ^ (fr >> 1)) << 4);
;   const unsigned offA = (wr * 128 + fr) * 128 + sw, offB = 32768 + (wc * 64 + fr) * 128 + sw;
;   const unsigned sbase = lds_addr(smem);
;   if (!PRE) { issue(0, 0); if (nk > 1) issue(1, 1); }
;   int st = 0;
; #pragma unroll 1
;   for (int kt = 0; kt < nk; kt++) {
;     if (kt + 1 < nk) asm volatile("s_waitcnt vmcnt(12)" ::: "memory"); else wait_vm0();
;     raw_barrier();
;     if (kt + 2 < nk) issue(kt + 2, st == 0 ? 2 : st - 1);
;     const unsigned base = sbase + st * 49152;
;     st = st == 2 ? 0 : st + 1;
;     h8 a0[8], b0[4], a1[8], b1[4];
; #pragma unroll
;     for (int m = 0; m < 8; m++) a0[m] = lds128(base + offA + m * 2048);
; #pragma unroll
;     for (int n = 0; n < 4; n++) b0[n] = lds128(base + offB + n * 2048);
; #pragma unroll
;     for (int m = 0; m < 8; m++) a1[m] = lds128(base + (offA ^ 64) + m * 2048);
; #pragma unroll
;     for (int n = 0; n < 4; n++) b1[n] = lds128(base + (offB ^ 64) + n * 2048);
;     WAIT_LGKM(12);
; #pragma unroll
;     for (int m = 0; m < 8; m++) tie(a0[m]);
; #pragma unroll
;     for (int n = 0; n < 4; n++) tie(b0[n]);
; #pragma unroll
;     for (int m = 0; m < 8; m++)
; #pragma unroll
;       for (int n = 0; n < 4; n++) acc[m][n] = mfma16(a0[m], b0[n], acc[m][n]);
.LBB0_513:
	s_nop 0
	v_mov_b32_e32 v2, v172
	s_mov_b32 s0, 0x8040
	v_lshlrev_b32_e32 v0, 3, v2
	v_and_b32_e32 v1, 48, v2
	v_bitop3_b32 v4, v0, v1, s37 bitop3:0x6c
	v_lshlrev_b32_e32 v1, 7, v2
	v_and_b32_e32 v5, 0x2780, v1
	v_and_b32_e32 v3, 0xffffc780, v1
	v_or_b32_e32 v1, v4, v5
	v_or_b32_e32 v0, v4, v3
	v_or_b32_e32 v1, 0x8000, v1
	v_lshlrev_b32_e32 v2, 4, v2
	v_bitop3_b32 v3, v4, 64, v3 bitop3:0x36
	v_bitop3_b32 v4, v4, s0, v5 bitop3:0x36
	s_mov_b32 s10, 0
	s_mov_b64 s[0:1], 0
	s_mov_b32 s11, 0
	v_readfirstlane_b32 s100, v2
	s_waitcnt vmcnt(12)
	s_barrier
	s_add_u32 s101, s100, 0x18000
	v_lshl_add_u64 v[88:89], v[132:133], 0, s[0:1]
	s_add_u32 m0, s101, 0x0
	v_lshl_add_u64 v[92:93], v[88:89], 0, s[74:75]
	global_load_lds_dwordx4 v[92:93], off
	s_add_u32 m0, s101, 0x1000
	v_lshl_add_u64 v[92:93], v[88:89], 0, s[76:77]
	global_load_lds_dwordx4 v[92:93], off
	s_add_u32 m0, s101, 0x2000
	v_lshl_add_u64 v[92:93], v[88:89], 0, s[86:87]
	global_load_lds_dwordx4 v[92:93], off
	s_add_u32 m0, s101, 0x3000
	v_lshl_add_u64 v[92:93], v[88:89], 0, s[80:81]
	global_load_lds_dwordx4 v[92:93], off
	s_add_u32 m0, s101, 0x4000
	v_lshl_add_u64 v[92:93], v[88:89], 0, s[72:73]
	global_load_lds_dwordx4 v[92:93], off
	s_add_u32 m0, s101, 0x5000
	v_lshl_add_u64 v[92:93], v[88:89], 0, s[96:97]
	global_load_lds_dwordx4 v[92:93], off
	ds_read_b128 v[38:41], v1 offset:0
	ds_read_b128 v[42:45], v1 offset:2048
	ds_read_b128 v[46:49], v1 offset:4096
	ds_read_b128 v[50:53], v1 offset:6144
	ds_read_b128 v[6:9], v0 offset:0
	ds_read_b128 v[10:13], v0 offset:2048
	ds_read_b128 v[14:17], v0 offset:4096
	ds_read_b128 v[18:21], v0 offset:6144
	ds_read_b128 v[22:25], v0 offset:8192
	ds_read_b128 v[26:29], v0 offset:10240
	ds_read_b128 v[30:33], v0 offset:12288
	ds_read_b128 v[34:37], v0 offset:14336
	s_mul_i32 s21, s11, 0xc000
	v_add_u32_e32 v86, s21, v3
	v_add_u32_e32 v87, s21, v4
	s_add_u32 s101, s11, 2
	s_sub_u32 s20, s101, 3
	s_cmp_lt_u32 s101, 3
	s_cselect_b32 s101, s101, s20
	s_mul_i32 s101, s101, 0xc000
	s_add_u32 s101, s101, s100
	s_waitcnt lgkmcnt(0)
	v_mfma_f32_16x16x32_f16 a[124:127], v[6:9], v[38:41], 0
	ds_read_b128 a[200:203], v87 offset:0
	v_mfma_f32_16x16x32_f16 a[120:123], v[6:9], v[42:45], 0
	v_lshl_add_u64 v[88:89], v[132:133], 0, s[0:1]
	s_add_u32 m0, s101, 0x6000
	v_lshl_add_u64 v[92:93], v[88:89], 0, s[12:13]
	global_load_lds_dwordx4 v[92:93], off
	v_mfma_f32_16x16x32_f16 a[116:119], v[6:9], v[46:49], 0
	ds_read_b128 a[204:207], v87 offset:2048
	v_mfma_f32_16x16x32_f16 a[112:115], v[6:9], v[50:53], 0
	v_mfma_f32_16x16x32_f16 a[108:111], v[10:13], v[38:41], 0
	ds_read_b128 a[208:211], v87 offset:4096
	v_mfma_f32_16x16x32_f16 a[104:107], v[10:13], v[42:45], 0
	s_add_u32 m0, s101, 0x7000
	v_lshl_add_u64 v[92:93], v[88:89], 0, s[16:17]
	global_load_lds_dwordx4 v[92:93], off
	v_mfma_f32_16x16x32_f16 a[100:103], v[10:13], v[46:49], 0
	ds_read_b128 a[212:215], v87 offset:6144
	v_mfma_f32_16x16x32_f16 a[96:99], v[10:13], v[50:53], 0
	v_mfma_f32_16x16x32_f16 a[92:95], v[14:17], v[38:41], 0
	ds_read_b128 v[54:57], v86 offset:0
	v_mfma_f32_16x16x32_f16 a[88:91], v[14:17], v[42:45], 0
	v_lshl_add_u64 v[90:91], v[134:135], 0, s[0:1]
	s_add_u32 m0, s101, 0x8000
	v_lshl_add_u64 v[92:93], v[90:91], 0, s[74:75]
	global_load_lds_dwordx4 v[92:93], off
	v_mfma_f32_16x16x32_f16 a[84:87], v[14:17], v[46:49], 0
	ds_read_b128 v[58:61], v86 offset:2048
	v_mfma_f32_16x16x32_f16 a[80:83], v[14:17], v[50:53], 0
	v_mfma_f32_16x16x32_f16 a[76:79], v[18:21], v[38:41], 0
	ds_read_b128 v[62:65], v86 offset:4096
	v_mfma_f32_16x16x32_f16 a[72:75], v[18:21], v[42:45], 0
	s_add_u32 m0, s101, 0x9000
	v_lshl_add_u64 v[92:93], v[90:91], 0, s[76:77]
	global_load_lds_dwordx4 v[92:93], off
	v_mfma_f32_16x16x32_f16 a[68:71], v[18:21], v[46:49], 0
	ds_read_b128 v[66:69], v86 offset:6144
	v_mfma_f32_16x16x32_f16 a[64:67], v[18:21], v[50:53], 0
	v_mfma_f32_16x16x32_f16 a[60:63], v[22:25], v[38:41], 0
	ds_read_b128 v[70:73], v86 offset:8192
	v_mfma_f32_16x16x32_f16 a[56:59], v[22:25], v[42:45], 0
	s_add_u32 m0, s101, 0xa000
	v_lshl_add_u64 v[92:93], v[90:91], 0, s[86:87]
	global_load_lds_dwordx4 v[92:93], off
	v_mfma_f32_16x16x32_f16 a[52:55], v[22:25], v[46:49], 0
	ds_read_b128 v[74:77], v86 offset:10240
	v_mfma_f32_16x16x32_f16 a[48:51], v[22:25], v[50:53], 0
	v_mfma_f32_16x16x32_f16 a[44:47], v[26:29], v[38:41], 0
	ds_read_b128 v[78:81], v86 offset:12288
	v_mfma_f32_16x16x32_f16 a[40:43], v[26:29], v[42:45], 0
	s_add_u32 m0, s101, 0xb000
	v_lshl_add_u64 v[92:93], v[90:91], 0, s[80:81]
	global_load_lds_dwordx4 v[92:93], off
	v_mfma_f32_16x16x32_f16 a[36:39], v[26:29], v[46:49], 0
	ds_read_b128 v[82:85], v86 offset:14336
	v_mfma_f32_16x16x32_f16 a[32:35], v[26:29], v[50:53], 0
	v_mfma_f32_16x16x32_f16 a[28:31], v[30:33], v[38:41], 0
	v_mfma_f32_16x16x32_f16 a[24:27], v[30:33], v[42:45], 0
	s_add_u32 s20, s11, 1
	v_mfma_f32_16x16x32_f16 a[20:23], v[30:33], v[46:49], 0
	s_cmp_eq_u32 s20, 3
	v_mfma_f32_16x16x32_f16 a[16:19], v[30:33], v[50:53], 0
	s_cselect_b32 s20, 0, s20
	v_mfma_f32_16x16x32_f16 a[8:11], v[34:37], v[38:41], 0
	s_mul_i32 s21, s20, 0xc000
	v_mfma_f32_16x16x32_f16 a[0:3], v[34:37], v[42:45], 0
	v_add_u32_e32 v100, s21, v0
	v_mfma_f32_16x16x32_f16 a[4:7], v[34:37], v[46:49], 0
	v_add_u32_e32 v101, s21, v1
	v_mfma_f32_16x16x32_f16 a[12:15], v[34:37], v[50:53], 0
	s_branch .Lg_gout_mid

; DI f4 mfma16(h8 a, h8 b, f4 c) { return __builtin_amdgcn_mfma_f32_16x16x32_f16(a, b, c, 0, 0, 0); }
; DI void row2_phase(const Params& P, int l, int r_begin, char* smem) {
;     ...
;     half_t* hxo = P.hx + (size_t)row * D + fq * 8;
; #pragma unroll 4
;     for (int kk = 0; kk < 32; kk++) {
;       const int k0 = kk * 32;
;       float x[8], g[8], s1[8], s0[8];
;       *(float4*)&x[0] = *(const float4*)(xm + k0); *(float4*)&x[4] = *(const float4*)(xm + k0 + 4);
;       *(float4*)&g[0] = *(const float4*)(gam + fq * 8 + k0); *(float4*)&g[4] = *(const float4*)(gam + fq * 8 + k0 + 4);
;       *(float4*)&s1[0] = *(const float4*)(sc + k0); *(float4*)&s1[4] = *(const float4*)(sc + k0 + 4);
;       *(float4*)&s0[0] = *(const float4*)(sh + k0); *(float4*)&s0[4] = *(const float4*)(sh + k0 + 4);
;       h8 hi, lo;
; #pragma unroll
;       for (int i = 0; i < 8; i++) {
;         float v = x[i] * rstd * g[i] * (1.f + s1[i]) + s0[i];
;         hi[i] = (half_t)v; lo[i] = (half_t)(v - (float)hi[i]);
;       }
;       *(h8*)(hxo + k0) = hi;
; #pragma unroll
;       for (int n3 = 0; n3 < 3; n3++) {
;         h8 bh = *(const h8*)(Whi + (size_t)(n3 * 16 + fr) * 1024 + k0 + fq * 8);
;         h8 bl = *(const h8*)(Wlo + (size_t)(n3 * 16 + fr) * 1024 + k0 + fq * 8);
;         acc[n3] = mfma16(hi, bh, acc[n3]); acc[n3] = mfma16(lo, bh, acc[n3]); acc[n3] = mfma16(hi, bl, acc[n3]);
;       }
;     }
.Lr2_tabok:
	global_load_dwordx4 a[16:19], v[22:23], off offset:0
	global_load_dwordx4 a[20:23], v[22:23], off offset:16
	global_load_dwordx4 a[24:27], v[22:23], off offset:128
	global_load_dwordx4 a[28:31], v[22:23], off offset:144
	global_load_dwordx4 a[32:35], v[22:23], off offset:256
	global_load_dwordx4 a[36:39], v[22:23], off offset:272
	global_load_dwordx4 a[40:43], v[22:23], off offset:384
	global_load_dwordx4 a[44:47], v[22:23], off offset:400
	global_load_dwordx4 a[48:51], v[22:23], off offset:512
	global_load_dwordx4 a[52:55], v[22:23], off offset:528
	global_load_dwordx4 a[56:59], v[22:23], off offset:640
	global_load_dwordx4 a[60:63], v[22:23], off offset:656
	global_load_dwordx4 a[64:67], v[22:23], off offset:768
	global_load_dwordx4 a[68:71], v[22:23], off offset:784
	global_load_dwordx4 a[72:75], v[22:23], off offset:896
	global_load_dwordx4 a[76:79], v[22:23], off offset:912
	global_load_dwordx4 a[180:183], v[22:23], off offset:1024
	global_load_dwordx4 a[184:187], v[22:23], off offset:1040
	global_load_dwordx4 a[196:199], v[22:23], off offset:1152
	global_load_dwordx4 a[200:203], v[22:23], off offset:1168
	global_load_dwordx4 a[80:83], v[90:91], off offset:0
	global_load_dwordx4 a[84:87], v[92:93], off offset:0
	global_load_dwordx4 a[88:91], v[94:95], off offset:0
	global_load_dwordx4 a[92:95], v[96:97], off offset:0
	global_load_dwordx4 a[96:99], v[98:99], off offset:0
	global_load_dwordx4 a[100:103], v[100:101], off offset:0
	global_load_dwordx4 a[104:107], v[90:91], off offset:64
	global_load_dwordx4 a[108:111], v[92:93], off offset:64
	global_load_dwordx4 a[112:115], v[94:95], off offset:64
	global_load_dwordx4 a[116:119], v[96:97], off offset:64
	global_load_dwordx4 a[120:123], v[98:99], off offset:64
	global_load_dwordx4 a[124:127], v[100:101], off offset:64
	global_load_dwordx4 a[128:131], v[90:91], off offset:128
	global_load_dwordx4 a[132:135], v[92:93], off offset:128
	global_load_dwordx4 a[136:139], v[94:95], off offset:128
	global_load_dwordx4 a[140:143], v[96:97], off offset:128
	global_load_dwordx4 a[144:147], v[98:99], off offset:128
	global_load_dwordx4 a[148:151], v[100:101], off offset:128
	global_load_dwordx4 a[152:155], v[90:91], off offset:192
	global_load_dwordx4 a[156:159], v[92:93], off offset:192
	global_load_dwordx4 a[160:163], v[94:95], off offset:192
	global_load_dwordx4 a[164:167], v[96:97], off offset:192
	global_load_dwordx4 a[168:171], v[98:99], off offset:192
	global_load_dwordx4 a[172:175], v[100:101], off offset:192
	global_load_dwordx4 a[204:207], v[90:91], off offset:256
	global_load_dwordx4 a[208:211], v[92:93], off offset:256
	global_load_dwordx4 a[212:215], v[94:95], off offset:256
	global_load_dwordx4 a[216:219], v[96:97], off offset:256
	global_load_dwordx4 a[220:223], v[98:99], off offset:256
	global_load_dwordx4 a[224:227], v[100:101], off offset:256
	global_load_dwordx4 a[228:231], v[90:91], off offset:320
	global_load_dwordx4 a[232:235], v[92:93], off offset:320
	global_load_dwordx4 a[236:239], v[94:95], off offset:320
	global_load_dwordx4 a[240:243], v[96:97], off offset:320
	global_load_dwordx4 a[244:247], v[98:99], off offset:320
	global_load_dwordx4 a[248:251], v[100:101], off offset:320
	ds_read_b128 v[32:35], v102 offset:0
	ds_read_b128 v[36:39], v102 offset:16
	ds_read_b128 v[40:43], v102 offset:4096
	ds_read_b128 v[44:47], v102 offset:4112
	ds_read_b128 v[58:61], v102 offset:8192
	ds_read_b128 v[62:65], v102 offset:8208
	s_waitcnt vmcnt(54)
	v_accvgpr_read_b32 v0, a16
	v_accvgpr_read_b32 v1, a17
	v_accvgpr_read_b32 v2, a18
	v_accvgpr_read_b32 v3, a19
	v_accvgpr_read_b32 v4, a20
	v_accvgpr_read_b32 v5, a21
	v_accvgpr_read_b32 v6, a22
	v_accvgpr_read_b32 v7, a23
	global_load_dwordx4 a[16:19], v[22:23], off offset:1280
	global_load_dwordx4 a[20:23], v[22:23], off offset:1296
	v_pk_mul_f32 v[0:1], v[28:29], v[0:1]
	v_pk_mul_f32 v[2:3], v[28:29], v[2:3]
	v_pk_mul_f32 v[4:5], v[28:29], v[4:5]
	v_pk_mul_f32 v[6:7], v[28:29], v[6:7]
	s_waitcnt lgkmcnt(0)
	v_pk_mul_f32 v[0:1], v[0:1], v[32:33]
	v_pk_mul_f32 v[2:3], v[2:3], v[34:35]
	v_pk_mul_f32 v[4:5], v[4:5], v[36:37]
	v_pk_mul_f32 v[6:7], v[6:7], v[38:39]
	v_pk_add_f32 v[40:41], v[40:41], 1.0 op_sel_hi:[1,0]
	v_pk_add_f32 v[42:43], v[42:43], 1.0 op_sel_hi:[1,0]
	v_pk_add_f32 v[44:45], v[44:45], 1.0 op_sel_hi:[1,0]
	v_pk_add_f32 v[46:47], v[46:47], 1.0 op_sel_hi:[1,0]
	v_pk_fma_f32 v[0:1], v[0:1], v[40:41], v[58:59]
	v_pk_fma_f32 v[2:3], v[2:3], v[42:43], v[60:61]
	v_pk_fma_f32 v[4:5], v[4:5], v[44:45], v[62:63]
	v_pk_fma_f32 v[6:7], v[6:7], v[46:47], v[64:65]
	ds_read_b128 v[32:35], v102 offset:128
	ds_read_b128 v[36:39], v102 offset:144
	ds_read_b128 v[40:43], v102 offset:4224
	ds_read_b128 v[44:47], v102 offset:4240
	ds_read_b128 v[58:61], v102 offset:8320
	ds_read_b128 v[62:65], v102 offset:8336
	v_cvt_pk_f16_f32 v74, v0, v1
	v_cvt_pk_f16_f32 v75, v2, v3
	v_cvt_pk_f16_f32 v76, v4, v5
	v_cvt_pk_f16_f32 v77, v6, v7
	v_cvt_f32_f16_e32 v66, v74
	v_cvt_f32_f16_sdwa v67, v74 dst_sel:DWORD dst_unused:UNUSED_PAD src0_sel:WORD_1
	v_cvt_f32_f16_e32 v68, v75
	v_cvt_f32_f16_sdwa v69, v75 dst_sel:DWORD dst_unused:UNUSED_PAD src0_sel:WORD_1
	v_cvt_f32_f16_e32 v70, v76
	v_cvt_f32_f16_sdwa v71, v76 dst_sel:DWORD dst_unused:UNUSED_PAD src0_sel:WORD_1
	v_cvt_f32_f16_e32 v72, v77
	v_cvt_f32_f16_sdwa v73, v77 dst_sel:DWORD dst_unused:UNUSED_PAD src0_sel:WORD_1
	v_pk_add_f32 v[0:1], v[0:1], v[66:67] neg_lo:[0,1] neg_hi:[0,1]
	v_pk_add_f32 v[2:3], v[2:3], v[68:69] neg_lo:[0,1] neg_hi:[0,1]
	v_pk_add_f32 v[4:5], v[4:5], v[70:71] neg_lo:[0,1] neg_hi:[0,1]
	v_pk_add_f32 v[6:7], v[6:7], v[72:73] neg_lo:[0,1] neg_hi:[0,1]
	s_nop 0
	v_cvt_pk_f16_f32 v78, v0, v1
	v_cvt_pk_f16_f32 v79, v2, v3
	v_cvt_pk_f16_f32 v80, v4, v5
	v_cvt_pk_f16_f32 v81, v6, v7
	global_store_dwordx4 v[88:89], v[74:77], off offset:0
	s_waitcnt vmcnt(33)
; DI f4 mfma16(h8 a, h8 b, f4 c) { return __builtin_amdgcn_mfma_f32_16x16x32_f16(a, b, c, 0, 0, 0); }
; DI void row2_phase(const Params& P, int l, int r_begin, char* smem) {
;     ...
; #pragma unroll 4
;     for (int kk = 0; kk < 32; kk++) {
;       const int k0 = kk * 32;
;       float x[8], g[8], s1[8], s0[8];
;       *(float4*)&x[0] = *(const float4*)(xm + k0); *(float4*)&x[4] = *(const float4*)(xm + k0 + 4);
;       *(float4*)&g[0] = *(const float4*)(gam + fq * 8 + k0); *(float4*)&g[4] = *(const float4*)(gam + fq * 8 + k0 + 4);
;       *(float4*)&s1[0] = *(const float4*)(sc + k0); *(float4*)&s1[4] = *(const float4*)(sc + k0 + 4);
;       *(float4*)&s0[0] = *(const float4*)(sh + k0); *(float4*)&s0[4] = *(const float4*)(sh + k0 + 4);
;       h8 hi, lo;
; #pragma unroll
;       for (int i = 0; i < 8; i++) {
;         float v = x[i] * rstd * g[i] * (1.f + s1[i]) + s0[i];
;         hi[i] = (half_t)v; lo[i] = (half_t)(v - (float)hi[i]);
;       }
;       *(h8*)(hxo + k0) = hi;
; #pragma unroll
;       for (int n3 = 0; n3 < 3; n3++) {
;         h8 bh = *(const h8*)(Whi + (size_t)(n3 * 16 + fr) * 1024 + k0 + fq * 8);
;         h8 bl = *(const h8*)(Wlo + (size_t)(n3 * 16 + fr) * 1024 + k0 + fq * 8);
;         acc[n3] = mfma16(hi, bh, acc[n3]); acc[n3] = mfma16(lo, bh, acc[n3]); acc[n3] = mfma16(hi, bl, acc[n3]);
;       }
;     }
	v_mfma_f32_16x16x32_f16 a[8:11], v[74:77], a[80:83], a[8:11]
	v_mfma_f32_16x16x32_f16 a[8:11], v[78:81], a[80:83], a[8:11]
	v_mfma_f32_16x16x32_f16 a[8:11], v[74:77], a[84:87], a[8:11]
	v_mfma_f32_16x16x32_f16 a[4:7], v[74:77], a[88:91], a[4:7]
	v_mfma_f32_16x16x32_f16 a[4:7], v[78:81], a[88:91], a[4:7]
	v_mfma_f32_16x16x32_f16 a[4:7], v[74:77], a[92:95], a[4:7]
	v_mfma_f32_16x16x32_f16 a[0:3], v[74:77], a[96:99], a[0:3]
	v_mfma_f32_16x16x32_f16 a[0:3], v[78:81], a[96:99], a[0:3]
	v_mfma_f32_16x16x32_f16 a[0:3], v[74:77], a[100:103], a[0:3]
	global_load_dwordx4 a[80:83], v[90:91], off offset:384
	global_load_dwordx4 a[84:87], v[92:93], off offset:384
	global_load_dwordx4 a[88:91], v[94:95], off offset:384
	global_load_dwordx4 a[92:95], v[96:97], off offset:384
	global_load_dwordx4 a[96:99], v[98:99], off offset:384
	global_load_dwordx4 a[100:103], v[100:101], off offset:384
	s_waitcnt vmcnt(39)
	v_accvgpr_read_b32 v0, a24
	v_accvgpr_read_b32 v1, a25
	v_accvgpr_read_b32 v2, a26
	v_accvgpr_read_b32 v3, a27
	v_accvgpr_read_b32 v4, a28
	v_accvgpr_read_b32 v5, a29
	v_accvgpr_read_b32 v6, a30
	v_accvgpr_read_b32 v7, a31
	global_load_dwordx4 a[24:27], v[22:23], off offset:1408
	global_load_dwordx4 a[28:31], v[22:23], off offset:1424
	v_pk_mul_f32 v[0:1], v[28:29], v[0:1]
	v_pk_mul_f32 v[2:3], v[28:29], v[2:3]
	v_pk_mul_f32 v[4:5], v[28:29], v[4:5]
	v_pk_mul_f32 v[6:7], v[28:29], v[6:7]
	s_waitcnt lgkmcnt(0)
	v_pk_mul_f32 v[0:1], v[0:1], v[32:33]
	v_pk_mul_f32 v[2:3], v[2:3], v[34:35]
	v_pk_mul_f32 v[4:5], v[4:5], v[36:37]
	v_pk_mul_f32 v[6:7], v[6:7], v[38:39]
	v_pk_add_f32 v[40:41], v[40:41], 1.0 op_sel_hi:[1,0]
	v_pk_add_f32 v[42:43], v[42:43], 1.0 op_sel_hi:[1,0]
	v_pk_add_f32 v[44:45], v[44:45], 1.0 op_sel_hi:[1,0]
	v_pk_add_f32 v[46:47], v[46:47], 1.0 op_sel_hi:[1,0]
	v_pk_fma_f32 v[0:1], v[0:1], v[40:41], v[58:59]
	v_pk_fma_f32 v[2:3], v[2:3], v[42:43], v[60:61]
	v_pk_fma_f32 v[4:5], v[4:5], v[44:45], v[62:63]
	v_pk_fma_f32 v[6:7], v[6:7], v[46:47], v[64:65]
	ds_read_b128 v[32:35], v102 offset:256
	ds_read_b128 v[36:39], v102 offset:272
	ds_read_b128 v[40:43], v102 offset:4352
	ds_read_b128 v[44:47], v102 offset:4368
	ds_read_b128 v[58:61], v102 offset:8448
	ds_read_b128 v[62:65], v102 offset:8464
	v_cvt_pk_f16_f32 v74, v0, v1
	v_cvt_pk_f16_f32 v75, v2, v3
	v_cvt_pk_f16_f32 v76, v4, v5
	v_cvt_pk_f16_f32 v77, v6, v7
	v_cvt_f32_f16_e32 v66, v74
	v_cvt_f32_f16_sdwa v67, v74 dst_sel:DWORD dst_unused:UNUSED_PAD src0_sel:WORD_1
	v_cvt_f32_f16_e32 v68, v75
	v_cvt_f32_f16_sdwa v69, v75 dst_sel:DWORD dst_unused:UNUSED_PAD src0_sel:WORD_1
	v_cvt_f32_f16_e32 v70, v76
	v_cvt_f32_f16_sdwa v71, v76 dst_sel:DWORD dst_unused:UNUSED_PAD src0_sel:WORD_1
	v_cvt_f32_f16_e32 v72, v77
	v_cvt_f32_f16_sdwa v73, v77 dst_sel:DWORD dst_unused:UNUSED_PAD src0_sel:WORD_1
	v_pk_add_f32 v[0:1], v[0:1], v[66:67] neg_lo:[0,1] neg_hi:[0,1]
	v_pk_add_f32 v[2:3], v[2:3], v[68:69] neg_lo:[0,1] neg_hi:[0,1]
	v_pk_add_f32 v[4:5], v[4:5], v[70:71] neg_lo:[0,1] neg_hi:[0,1]
	v_pk_add_f32 v[6:7], v[6:7], v[72:73] neg_lo:[0,1] neg_hi:[0,1]
	s_nop 0
	v_cvt_pk_f16_f32 v78, v0, v1
	v_cvt_pk_f16_f32 v79, v2, v3
	v_cvt_pk_f16_f32 v80, v4, v5
	v_cvt_pk_f16_f32 v81, v6, v7
	global_store_dwordx4 v[88:89], v[74:77], off offset:64
	s_waitcnt vmcnt(36)
	v_mfma_f32_16x16x32_f16 a[8:11], v[74:77], a[104:107], a[8:11]
	v_mfma_f32_16x16x32_f16 a[8:11], v[78:81], a[104:107], a[8:11]
	v_mfma_f32_16x16x32_f16 a[8:11], v[74:77], a[108:111], a[8:11]
	v_mfma_f32_16x16x32_f16 a[4:7], v[74:77], a[112:115], a[4:7]
	v_mfma_f32_16x16x32_f16 a[4:7], v[78:81], a[112:115], a[4:7]
	v_mfma_f32_16x16x32_f16 a[4:7], v[74:77], a[116:119], a[4:7]
	v_mfma_f32_16x16x32_f16 a[0:3], v[74:77], a[120:123], a[0:3]
	v_mfma_f32_16x16x32_f16 a[0:3], v[78:81], a[120:123], a[0:3]
	v_mfma_f32_16x16x32_f16 a[0:3], v[74:77], a[124:127], a[0:3]
	global_load_dwordx4 a[104:107], v[90:91], off offset:448
	global_load_dwordx4 a[108:111], v[92:93], off offset:448
	global_load_dwordx4 a[112:115], v[94:95], off offset:448
	global_load_dwordx4 a[116:119], v[96:97], off offset:448
	global_load_dwordx4 a[120:123], v[98:99], off offset:448
	global_load_dwordx4 a[124:127], v[100:101], off offset:448
	s_waitcnt vmcnt(42)
	v_accvgpr_read_b32 v0, a32
	v_accvgpr_read_b32 v1, a33
	v_accvgpr_read_b32 v2, a34
	v_accvgpr_read_b32 v3, a35
	v_accvgpr_read_b32 v4, a36
	v_accvgpr_read_b32 v5, a37
	v_accvgpr_read_b32 v6, a38
	v_accvgpr_read_b32 v7, a39
	global_load_dwordx4 a[32:35], v[22:23], off offset:1536
	global_load_dwordx4 a[36:39], v[22:23], off offset:1552
	v_pk_mul_f32 v[0:1], v[28:29], v[0:1]
	v_pk_mul_f32 v[2:3], v[28:29], v[2:3]
	v_pk_mul_f32 v[4:5], v[28:29], v[4:5]
	v_pk_mul_f32 v[6:7], v[28:29], v[6:7]
	s_waitcnt lgkmcnt(0)
	v_pk_mul_f32 v[0:1], v[0:1], v[32:33]
	v_pk_mul_f32 v[2:3], v[2:3], v[34:35]
	v_pk_mul_f32 v[4:5], v[4:5], v[36:37]
	v_pk_mul_f32 v[6:7], v[6:7], v[38:39]
	v_pk_add_f32 v[40:41], v[40:41], 1.0 op_sel_hi:[1,0]
	v_pk_add_f32 v[42:43], v[42:43], 1.0 op_sel_hi:[1,0]
	v_pk_add_f32 v[44:45], v[44:45], 1.0 op_sel_hi:[1,0]
	v_pk_add_f32 v[46:47], v[46:47], 1.0 op_sel_hi:[1,0]
	v_pk_fma_f32 v[0:1], v[0:1], v[40:41], v[58:59]
	v_pk_fma_f32 v[2:3], v[2:3], v[42:43], v[60:61]
	v_pk_fma_f32 v[4:5], v[4:5], v[44:45], v[62:63]
	v_pk_fma_f32 v[6:7], v[6:7], v[46:47], v[64:65]
	ds_read_b128 v[32:35], v102 offset:384
	ds_read_b128 v[36:39], v102 offset:400
	ds_read_b128 v[40:43], v102 offset:4480
	ds_read_b128 v[44:47], v102 offset:4496
	ds_read_b128 v[58:61], v102 offset:8576
	ds_read_b128 v[62:65], v102 offset:8592
	v_cvt_pk_f16_f32 v74, v0, v1
	v_cvt_pk_f16_f32 v75, v2, v3
	v_cvt_pk_f16_f32 v76, v4, v5
	v_cvt_pk_f16_f32 v77, v6, v7
	v_cvt_f32_f16_e32 v66, v74
	v_cvt_f32_f16_sdwa v67, v74 dst_sel:DWORD dst_unused:UNUSED_PAD src0_sel:WORD_1
	v_cvt_f32_f16_e32 v68, v75
	v_cvt_f32_f16_sdwa v69, v75 dst_sel:DWORD dst_unused:UNUSED_PAD src0_sel:WORD_1
	v_cvt_f32_f16_e32 v70, v76
	v_cvt_f32_f16_sdwa v71, v76 dst_sel:DWORD dst_unused:UNUSED_PAD src0_sel:WORD_1
	v_cvt_f32_f16_e32 v72, v77
	v_cvt_f32_f16_sdwa v73, v77 dst_sel:DWORD dst_unused:UNUSED_PAD src0_sel:WORD_1
	v_pk_add_f32 v[0:1], v[0:1], v[66:67] neg_lo:[0,1] neg_hi:[0,1]
	v_pk_add_f32 v[2:3], v[2:3], v[68:69] neg_lo:[0,1] neg_hi:[0,1]
	v_pk_add_f32 v[4:5], v[4:5], v[70:71] neg_lo:[0,1] neg_hi:[0,1]
	v_pk_add_f32 v[6:7], v[6:7], v[72:73] neg_lo:[0,1] neg_hi:[0,1]
	s_nop 0
	v_cvt_pk_f16_f32 v78, v0, v1
	v_cvt_pk_f16_f32 v79, v2, v3
	v_cvt_pk_f16_f32 v80, v4, v5
	v_cvt_pk_f16_f32 v81, v6, v7
	global_store_dwordx4 v[88:89], v[74:77], off offset:128
	s_waitcnt vmcnt(39)
; DI f4 mfma16(h8 a, h8 b, f4 c) { return __builtin_amdgcn_mfma_f32_16x16x32_f16(a, b, c, 0, 0, 0); }
; DI void row2_phase(const Params& P, int l, int r_begin, char* smem) {
;     ...
; #pragma unroll 4
;     for (int kk = 0; kk < 32; kk++) {
;       const int k0 = kk * 32;
;       float x[8], g[8], s1[8], s0[8];
;       *(float4*)&x[0] = *(const float4*)(xm + k0); *(float4*)&x[4] = *(const float4*)(xm + k0 + 4);
;       *(float4*)&g[0] = *(const float4*)(gam + fq * 8 + k0); *(float4*)&g[4] = *(const float4*)(gam + fq * 8 + k0 + 4);
;       *(float4*)&s1[0] = *(const float4*)(sc + k0); *(float4*)&s1[4] = *(const float4*)(sc + k0 + 4);
;       *(float4*)&s0[0] = *(const float4*)(sh + k0); *(float4*)&s0[4] = *(const float4*)(sh + k0 + 4);
;       h8 hi, lo;
; #pragma unroll
;       for (int i = 0; i < 8; i++) {
;         float v = x[i] * rstd * g[i] * (1.f + s1[i]) + s0[i];
;         hi[i] = (half_t)v; lo[i] = (half_t)(v - (float)hi[i]);
;       }
;       *(h8*)(hxo + k0) = hi;
; #pragma unroll
;       for (int n3 = 0; n3 < 3; n3++) {
;         h8 bh = *(const h8*)(Whi + (size_t)(n3 * 16 + fr) * 1024 + k0 + fq * 8);
;         h8 bl = *(const h8*)(Wlo + (size_t)(n3 * 16 + fr) * 1024 + k0 + fq * 8);
;         acc[n3] = mfma16(hi, bh, acc[n3]); acc[n3] = mfma16(lo, bh, acc[n3]); acc[n3] = mfma16(hi, bl, acc[n3]);
;       }
;     }
	v_mfma_f32_16x16x32_f16 a[8:11], v[74:77], a[128:131], a[8:11]
	v_mfma_f32_16x16x32_f16 a[8:11], v[78:81], a[128:131], a[8:11]
	v_mfma_f32_16x16x32_f16 a[8:11], v[74:77], a[132:135], a[8:11]
	v_mfma_f32_16x16x32_f16 a[4:7], v[74:77], a[136:139], a[4:7]
	v_mfma_f32_16x16x32_f16 a[4:7], v[78:81], a[136:139], a[4:7]
	v_mfma_f32_16x16x32_f16 a[4:7], v[74:77], a[140:143], a[4:7]
	v_mfma_f32_16x16x32_f16 a[0:3], v[74:77], a[144:147], a[0:3]
	v_mfma_f32_16x16x32_f16 a[0:3], v[78:81], a[144:147], a[0:3]
	v_mfma_f32_16x16x32_f16 a[0:3], v[74:77], a[148:151], a[0:3]
	global_load_dwordx4 a[128:131], v[90:91], off offset:512
	global_load_dwordx4 a[132:135], v[92:93], off offset:512
	global_load_dwordx4 a[136:139], v[94:95], off offset:512
	global_load_dwordx4 a[140:143], v[96:97], off offset:512
	global_load_dwordx4 a[144:147], v[98:99], off offset:512
	global_load_dwordx4 a[148:151], v[100:101], off offset:512
	s_waitcnt vmcnt(45)
	v_accvgpr_read_b32 v0, a40
	v_accvgpr_read_b32 v1, a41
	v_accvgpr_read_b32 v2, a42
	v_accvgpr_read_b32 v3, a43
	v_accvgpr_read_b32 v4, a44
	v_accvgpr_read_b32 v5, a45
	v_accvgpr_read_b32 v6, a46
	v_accvgpr_read_b32 v7, a47
	global_load_dwordx4 a[40:43], v[22:23], off offset:1664
	global_load_dwordx4 a[44:47], v[22:23], off offset:1680
	v_pk_mul_f32 v[0:1], v[28:29], v[0:1]
	v_pk_mul_f32 v[2:3], v[28:29], v[2:3]
	v_pk_mul_f32 v[4:5], v[28:29], v[4:5]
	v_pk_mul_f32 v[6:7], v[28:29], v[6:7]
	s_waitcnt lgkmcnt(0)
	v_pk_mul_f32 v[0:1], v[0:1], v[32:33]
	v_pk_mul_f32 v[2:3], v[2:3], v[34:35]
	v_pk_mul_f32 v[4:5], v[4:5], v[36:37]
	v_pk_mul_f32 v[6:7], v[6:7], v[38:39]
	v_pk_add_f32 v[40:41], v[40:41], 1.0 op_sel_hi:[1,0]
	v_pk_add_f32 v[42:43], v[42:43], 1.0 op_sel_hi:[1,0]
	v_pk_add_f32 v[44:45], v[44:45], 1.0 op_sel_hi:[1,0]
	v_pk_add_f32 v[46:47], v[46:47], 1.0 op_sel_hi:[1,0]
	v_pk_fma_f32 v[0:1], v[0:1], v[40:41], v[58:59]
	v_pk_fma_f32 v[2:3], v[2:3], v[42:43], v[60:61]
	v_pk_fma_f32 v[4:5], v[4:5], v[44:45], v[62:63]
	v_pk_fma_f32 v[6:7], v[6:7], v[46:47], v[64:65]
	ds_read_b128 v[32:35], v102 offset:512
	ds_read_b128 v[36:39], v102 offset:528
	ds_read_b128 v[40:43], v102 offset:4608
	ds_read_b128 v[44:47], v102 offset:4624
	ds_read_b128 v[58:61], v102 offset:8704
	ds_read_b128 v[62:65], v102 offset:8720
	v_cvt_pk_f16_f32 v74, v0, v1
	v_cvt_pk_f16_f32 v75, v2, v3
	v_cvt_pk_f16_f32 v76, v4, v5
	v_cvt_pk_f16_f32 v77, v6, v7
	v_cvt_f32_f16_e32 v66, v74
	v_cvt_f32_f16_sdwa v67, v74 dst_sel:DWORD dst_unused:UNUSED_PAD src0_sel:WORD_1
	v_cvt_f32_f16_e32 v68, v75
	v_cvt_f32_f16_sdwa v69, v75 dst_sel:DWORD dst_unused:UNUSED_PAD src0_sel:WORD_1
	v_cvt_f32_f16_e32 v70, v76
	v_cvt_f32_f16_sdwa v71, v76 dst_sel:DWORD dst_unused:UNUSED_PAD src0_sel:WORD_1
	v_cvt_f32_f16_e32 v72, v77
	v_cvt_f32_f16_sdwa v73, v77 dst_sel:DWORD dst_unused:UNUSED_PAD src0_sel:WORD_1
	v_pk_add_f32 v[0:1], v[0:1], v[66:67] neg_lo:[0,1] neg_hi:[0,1]
	v_pk_add_f32 v[2:3], v[2:3], v[68:69] neg_lo:[0,1] neg_hi:[0,1]
	v_pk_add_f32 v[4:5], v[4:5], v[70:71] neg_lo:[0,1] neg_hi:[0,1]
	v_pk_add_f32 v[6:7], v[6:7], v[72:73] neg_lo:[0,1] neg_hi:[0,1]
	s_nop 0
	v_cvt_pk_f16_f32 v78, v0, v1
	v_cvt_pk_f16_f32 v79, v2, v3
	v_cvt_pk_f16_f32 v80, v4, v5
	v_cvt_pk_f16_f32 v81, v6, v7
	global_store_dwordx4 v[88:89], v[74:77], off offset:192
	s_waitcnt vmcnt(42)
	v_mfma_f32_16x16x32_f16 a[8:11], v[74:77], a[152:155], a[8:11]
	v_mfma_f32_16x16x32_f16 a[8:11], v[78:81], a[152:155], a[8:11]
	v_mfma_f32_16x16x32_f16 a[8:11], v[74:77], a[156:159], a[8:11]
	v_mfma_f32_16x16x32_f16 a[4:7], v[74:77], a[160:163], a[4:7]
	v_mfma_f32_16x16x32_f16 a[4:7], v[78:81], a[160:163], a[4:7]
	v_mfma_f32_16x16x32_f16 a[4:7], v[74:77], a[164:167], a[4:7]
	v_mfma_f32_16x16x32_f16 a[0:3], v[74:77], a[168:171], a[0:3]
	v_mfma_f32_16x16x32_f16 a[0:3], v[78:81], a[168:171], a[0:3]
	v_mfma_f32_16x16x32_f16 a[0:3], v[74:77], a[172:175], a[0:3]
	global_load_dwordx4 a[152:155], v[90:91], off offset:576
	global_load_dwordx4 a[156:159], v[92:93], off offset:576
	global_load_dwordx4 a[160:163], v[94:95], off offset:576
	global_load_dwordx4 a[164:167], v[96:97], off offset:576
	global_load_dwordx4 a[168:171], v[98:99], off offset:576
	global_load_dwordx4 a[172:175], v[100:101], off offset:576
	s_waitcnt vmcnt(48)
	v_accvgpr_read_b32 v0, a48
	v_accvgpr_read_b32 v1, a49
	v_accvgpr_read_b32 v2, a50
	v_accvgpr_read_b32 v3, a51
	v_accvgpr_read_b32 v4, a52
	v_accvgpr_read_b32 v5, a53
	v_accvgpr_read_b32 v6, a54
	v_accvgpr_read_b32 v7, a55
	global_load_dwordx4 a[48:51], v[22:23], off offset:1792
	global_load_dwordx4 a[52:55], v[22:23], off offset:1808
	v_pk_mul_f32 v[0:1], v[28:29], v[0:1]
	v_pk_mul_f32 v[2:3], v[28:29], v[2:3]
	v_pk_mul_f32 v[4:5], v[28:29], v[4:5]
	v_pk_mul_f32 v[6:7], v[28:29], v[6:7]
	s_waitcnt lgkmcnt(0)
; DI f4 mfma16(h8 a, h8 b, f4 c) { return __builtin_amdgcn_mfma_f32_16x16x32_f16(a, b, c, 0, 0, 0); }
; DI void row2_phase(const Params& P, int l, int r_begin, char* smem) {
;     ...
; #pragma unroll 4
;     for (int kk = 0; kk < 32; kk++) {
;       const int k0 = kk * 32;
;       float x[8], g[8], s1[8], s0[8];
;       *(float4*)&x[0] = *(const float4*)(xm + k0); *(float4*)&x[4] = *(const float4*)(xm + k0 + 4);
;       *(float4*)&g[0] = *(const float4*)(gam + fq * 8 + k0); *(float4*)&g[4] = *(const float4*)(gam + fq * 8 + k0 + 4);
;       *(float4*)&s1[0] = *(const float4*)(sc + k0); *(float4*)&s1[4] = *(const float4*)(sc + k0 + 4);
;       *(float4*)&s0[0] = *(const float4*)(sh + k0); *(float4*)&s0[4] = *(const float4*)(sh + k0 + 4);
;       h8 hi, lo;
; #pragma unroll
;       for (int i = 0; i < 8; i++) {
;         float v = x[i] * rstd * g[i] * (1.f + s1[i]) + s0[i];
;         hi[i] = (half_t)v; lo[i] = (half_t)(v - (float)hi[i]);
;       }
;       *(h8*)(hxo + k0) = hi;
; #pragma unroll
;       for (int n3 = 0; n3 < 3; n3++) {
;         h8 bh = *(const h8*)(Whi + (size_t)(n3 * 16 + fr) * 1024 + k0 + fq * 8);
;         h8 bl = *(const h8*)(Wlo + (size_t)(n3 * 16 + fr) * 1024 + k0 + fq * 8);
;         acc[n3] = mfma16(hi, bh, acc[n3]); acc[n3] = mfma16(lo, bh, acc[n3]); acc[n3] = mfma16(hi, bl, acc[n3]);
;       }
;     }
	v_pk_mul_f32 v[0:1], v[0:1], v[32:33]
	v_pk_mul_f32 v[2:3], v[2:3], v[34:35]
	v_pk_mul_f32 v[4:5], v[4:5], v[36:37]
	v_pk_mul_f32 v[6:7], v[6:7], v[38:39]
	v_pk_add_f32 v[40:41], v[40:41], 1.0 op_sel_hi:[1,0]
	v_pk_add_f32 v[42:43], v[42:43], 1.0 op_sel_hi:[1,0]
	v_pk_add_f32 v[44:45], v[44:45], 1.0 op_sel_hi:[1,0]
	v_pk_add_f32 v[46:47], v[46:47], 1.0 op_sel_hi:[1,0]
	v_pk_fma_f32 v[0:1], v[0:1], v[40:41], v[58:59]
	v_pk_fma_f32 v[2:3], v[2:3], v[42:43], v[60:61]
	v_pk_fma_f32 v[4:5], v[4:5], v[44:45], v[62:63]
	v_pk_fma_f32 v[6:7], v[6:7], v[46:47], v[64:65]
	ds_read_b128 v[32:35], v102 offset:640
	ds_read_b128 v[36:39], v102 offset:656
	ds_read_b128 v[40:43], v102 offset:4736
	ds_read_b128 v[44:47], v102 offset:4752
	ds_read_b128 v[58:61], v102 offset:8832
	ds_read_b128 v[62:65], v102 offset:8848
	v_cvt_pk_f16_f32 v74, v0, v1
	v_cvt_pk_f16_f32 v75, v2, v3
	v_cvt_pk_f16_f32 v76, v4, v5
	v_cvt_pk_f16_f32 v77, v6, v7
	v_cvt_f32_f16_e32 v66, v74
	v_cvt_f32_f16_sdwa v67, v74 dst_sel:DWORD dst_unused:UNUSED_PAD src0_sel:WORD_1
	v_cvt_f32_f16_e32 v68, v75
	v_cvt_f32_f16_sdwa v69, v75 dst_sel:DWORD dst_unused:UNUSED_PAD src0_sel:WORD_1
	v_cvt_f32_f16_e32 v70, v76
	v_cvt_f32_f16_sdwa v71, v76 dst_sel:DWORD dst_unused:UNUSED_PAD src0_sel:WORD_1
	v_cvt_f32_f16_e32 v72, v77
	v_cvt_f32_f16_sdwa v73, v77 dst_sel:DWORD dst_unused:UNUSED_PAD src0_sel:WORD_1
	v_pk_add_f32 v[0:1], v[0:1], v[66:67] neg_lo:[0,1] neg_hi:[0,1]
	v_pk_add_f32 v[2:3], v[2:3], v[68:69] neg_lo:[0,1] neg_hi:[0,1]
	v_pk_add_f32 v[4:5], v[4:5], v[70:71] neg_lo:[0,1] neg_hi:[0,1]
	v_pk_add_f32 v[6:7], v[6:7], v[72:73] neg_lo:[0,1] neg_hi:[0,1]
	s_nop 0
	v_cvt_pk_f16_f32 v78, v0, v1
	v_cvt_pk_f16_f32 v79, v2, v3
	v_cvt_pk_f16_f32 v80, v4, v5
	v_cvt_pk_f16_f32 v81, v6, v7
	global_store_dwordx4 v[88:89], v[74:77], off offset:256
	s_waitcnt vmcnt(45)
	v_mfma_f32_16x16x32_f16 a[8:11], v[74:77], a[204:207], a[8:11]
	v_mfma_f32_16x16x32_f16 a[8:11], v[78:81], a[204:207], a[8:11]
	v_mfma_f32_16x16x32_f16 a[8:11], v[74:77], a[208:211], a[8:11]
	v_mfma_f32_16x16x32_f16 a[4:7], v[74:77], a[212:215], a[4:7]
	v_mfma_f32_16x16x32_f16 a[4:7], v[78:81], a[212:215], a[4:7]
	v_mfma_f32_16x16x32_f16 a[4:7], v[74:77], a[216:219], a[4:7]
	v_mfma_f32_16x16x32_f16 a[0:3], v[74:77], a[220:223], a[0:3]
	v_mfma_f32_16x16x32_f16 a[0:3], v[78:81], a[220:223], a[0:3]
	v_mfma_f32_16x16x32_f16 a[0:3], v[74:77], a[224:227], a[0:3]
	global_load_dwordx4 a[204:207], v[90:91], off offset:640
	global_load_dwordx4 a[208:211], v[92:93], off offset:640
	global_load_dwordx4 a[212:215], v[94:95], off offset:640
	global_load_dwordx4 a[216:219], v[96:97], off offset:640
	global_load_dwordx4 a[220:223], v[98:99], off offset:640
	global_load_dwordx4 a[224:227], v[100:101], off offset:640
	s_waitcnt vmcnt(51)
	v_accvgpr_read_b32 v0, a56
	v_accvgpr_read_b32 v1, a57
	v_accvgpr_read_b32 v2, a58
	v_accvgpr_read_b32 v3, a59
	v_accvgpr_read_b32 v4, a60
	v_accvgpr_read_b32 v5, a61
	v_accvgpr_read_b32 v6, a62
	v_accvgpr_read_b32 v7, a63
	global_load_dwordx4 a[56:59], v[22:23], off offset:1920
	global_load_dwordx4 a[60:63], v[22:23], off offset:1936
	v_pk_mul_f32 v[0:1], v[28:29], v[0:1]
	v_pk_mul_f32 v[2:3], v[28:29], v[2:3]
	v_pk_mul_f32 v[4:5], v[28:29], v[4:5]
	v_pk_mul_f32 v[6:7], v[28:29], v[6:7]
	s_waitcnt lgkmcnt(0)
	v_pk_mul_f32 v[0:1], v[0:1], v[32:33]
	v_pk_mul_f32 v[2:3], v[2:3], v[34:35]
	v_pk_mul_f32 v[4:5], v[4:5], v[36:37]
	v_pk_mul_f32 v[6:7], v[6:7], v[38:39]
	v_pk_add_f32 v[40:41], v[40:41], 1.0 op_sel_hi:[1,0]
	v_pk_add_f32 v[42:43], v[42:43], 1.0 op_sel_hi:[1,0]
	v_pk_add_f32 v[44:45], v[44:45], 1.0 op_sel_hi:[1,0]
	v_pk_add_f32 v[46:47], v[46:47], 1.0 op_sel_hi:[1,0]
	v_pk_fma_f32 v[0:1], v[0:1], v[40:41], v[58:59]
	v_pk_fma_f32 v[2:3], v[2:3], v[42:43], v[60:61]
	v_pk_fma_f32 v[4:5], v[4:5], v[44:45], v[62:63]
	v_pk_fma_f32 v[6:7], v[6:7], v[46:47], v[64:65]
	ds_read_b128 v[32:35], v102 offset:768
	ds_read_b128 v[36:39], v102 offset:784
	ds_read_b128 v[40:43], v102 offset:4864
	ds_read_b128 v[44:47], v102 offset:4880
	ds_read_b128 v[58:61], v102 offset:8960
	ds_read_b128 v[62:65], v102 offset:8976
	v_cvt_pk_f16_f32 v74, v0, v1
	v_cvt_pk_f16_f32 v75, v2, v3
	v_cvt_pk_f16_f32 v76, v4, v5
	v_cvt_pk_f16_f32 v77, v6, v7
	v_cvt_f32_f16_e32 v66, v74
	v_cvt_f32_f16_sdwa v67, v74 dst_sel:DWORD dst_unused:UNUSED_PAD src0_sel:WORD_1
	v_cvt_f32_f16_e32 v68, v75
	v_cvt_f32_f16_sdwa v69, v75 dst_sel:DWORD dst_unused:UNUSED_PAD src0_sel:WORD_1
	v_cvt_f32_f16_e32 v70, v76
	v_cvt_f32_f16_sdwa v71, v76 dst_sel:DWORD dst_unused:UNUSED_PAD src0_sel:WORD_1
	v_cvt_f32_f16_e32 v72, v77
	v_cvt_f32_f16_sdwa v73, v77 dst_sel:DWORD dst_unused:UNUSED_PAD src0_sel:WORD_1
	v_pk_add_f32 v[0:1], v[0:1], v[66:67] neg_lo:[0,1] neg_hi:[0,1]
	v_pk_add_f32 v[2:3], v[2:3], v[68:69] neg_lo:[0,1] neg_hi:[0,1]
	v_pk_add_f32 v[4:5], v[4:5], v[70:71] neg_lo:[0,1] neg_hi:[0,1]
	v_pk_add_f32 v[6:7], v[6:7], v[72:73] neg_lo:[0,1] neg_hi:[0,1]
	s_nop 0
	v_cvt_pk_f16_f32 v78, v0, v1
	v_cvt_pk_f16_f32 v79, v2, v3
	v_cvt_pk_f16_f32 v80, v4, v5
	v_cvt_pk_f16_f32 v81, v6, v7
	global_store_dwordx4 v[88:89], v[74:77], off offset:320
	s_waitcnt vmcnt(48)
	v_mfma_f32_16x16x32_f16 a[8:11], v[74:77], a[228:231], a[8:11]
	v_mfma_f32_16x16x32_f16 a[8:11], v[78:81], a[228:231], a[8:11]
	v_mfma_f32_16x16x32_f16 a[8:11], v[74:77], a[232:235], a[8:11]
	v_mfma_f32_16x16x32_f16 a[4:7], v[74:77], a[236:239], a[4:7]
	v_mfma_f32_16x16x32_f16 a[4:7], v[78:81], a[236:239], a[4:7]
	v_mfma_f32_16x16x32_f16 a[4:7], v[74:77], a[240:243], a[4:7]
	v_mfma_f32_16x16x32_f16 a[0:3], v[74:77], a[244:247], a[0:3]
	v_mfma_f32_16x16x32_f16 a[0:3], v[78:81], a[244:247], a[0:3]
	v_mfma_f32_16x16x32_f16 a[0:3], v[74:77], a[248:251], a[0:3]
	global_load_dwordx4 a[228:231], v[90:91], off offset:704
	global_load_dwordx4 a[232:235], v[92:93], off offset:704
	global_load_dwordx4 a[236:239], v[94:95], off offset:704
	global_load_dwordx4 a[240:243], v[96:97], off offset:704
	global_load_dwordx4 a[244:247], v[98:99], off offset:704
	global_load_dwordx4 a[248:251], v[100:101], off offset:704
	s_waitcnt vmcnt(54)
; DI f4 mfma16(h8 a, h8 b, f4 c) { return __builtin_amdgcn_mfma_f32_16x16x32_f16(a, b, c, 0, 0, 0); }
; DI void row2_phase(const Params& P, int l, int r_begin, char* smem) {
;     ...
; #pragma unroll 4
;     for (int kk = 0; kk < 32; kk++) {
;       const int k0 = kk * 32;
;       float x[8], g[8], s1[8], s0[8];
;       *(float4*)&x[0] = *(const float4*)(xm + k0); *(float4*)&x[4] = *(const float4*)(xm + k0 + 4);
;       *(float4*)&g[0] = *(const float4*)(gam + fq * 8 + k0); *(float4*)&g[4] = *(const float4*)(gam + fq * 8 + k0 + 4);
;       *(float4*)&s1[0] = *(const float4*)(sc + k0); *(float4*)&s1[4] = *(const float4*)(sc + k0 + 4);
;       *(float4*)&s0[0] = *(const float4*)(sh + k0); *(float4*)&s0[4] = *(const float4*)(sh + k0 + 4);
;       h8 hi, lo;
; #pragma unroll
;       for (int i = 0; i < 8; i++) {
;         float v = x[i] * rstd * g[i] * (1.f + s1[i]) + s0[i];
;         hi[i] = (half_t)v; lo[i] = (half_t)(v - (float)hi[i]);
;       }
;       *(h8*)(hxo + k0) = hi;
; #pragma unroll
;       for (int n3 = 0; n3 < 3; n3++) {
;         h8 bh = *(const h8*)(Whi + (size_t)(n3 * 16 + fr) * 1024 + k0 + fq * 8);
;         h8 bl = *(const h8*)(Wlo + (size_t)(n3 * 16 + fr) * 1024 + k0 + fq * 8);
;         acc[n3] = mfma16(hi, bh, acc[n3]); acc[n3] = mfma16(lo, bh, acc[n3]); acc[n3] = mfma16(hi, bl, acc[n3]);
;       }
;     }
	v_accvgpr_read_b32 v0, a64
	v_accvgpr_read_b32 v1, a65
	v_accvgpr_read_b32 v2, a66
	v_accvgpr_read_b32 v3, a67
	v_accvgpr_read_b32 v4, a68
	v_accvgpr_read_b32 v5, a69
	v_accvgpr_read_b32 v6, a70
	v_accvgpr_read_b32 v7, a71
	global_load_dwordx4 a[64:67], v[22:23], off offset:2048
	global_load_dwordx4 a[68:71], v[22:23], off offset:2064
	v_pk_mul_f32 v[0:1], v[28:29], v[0:1]
	v_pk_mul_f32 v[2:3], v[28:29], v[2:3]
	v_pk_mul_f32 v[4:5], v[28:29], v[4:5]
	v_pk_mul_f32 v[6:7], v[28:29], v[6:7]
	s_waitcnt lgkmcnt(0)
	v_pk_mul_f32 v[0:1], v[0:1], v[32:33]
	v_pk_mul_f32 v[2:3], v[2:3], v[34:35]
	v_pk_mul_f32 v[4:5], v[4:5], v[36:37]
	v_pk_mul_f32 v[6:7], v[6:7], v[38:39]
	v_pk_add_f32 v[40:41], v[40:41], 1.0 op_sel_hi:[1,0]
	v_pk_add_f32 v[42:43], v[42:43], 1.0 op_sel_hi:[1,0]
	v_pk_add_f32 v[44:45], v[44:45], 1.0 op_sel_hi:[1,0]
	v_pk_add_f32 v[46:47], v[46:47], 1.0 op_sel_hi:[1,0]
	v_pk_fma_f32 v[0:1], v[0:1], v[40:41], v[58:59]
	v_pk_fma_f32 v[2:3], v[2:3], v[42:43], v[60:61]
	v_pk_fma_f32 v[4:5], v[4:5], v[44:45], v[62:63]
	v_pk_fma_f32 v[6:7], v[6:7], v[46:47], v[64:65]
	ds_read_b128 v[32:35], v102 offset:896
	ds_read_b128 v[36:39], v102 offset:912
	ds_read_b128 v[40:43], v102 offset:4992
	ds_read_b128 v[44:47], v102 offset:5008
	ds_read_b128 v[58:61], v102 offset:9088
	ds_read_b128 v[62:65], v102 offset:9104
	v_cvt_pk_f16_f32 v74, v0, v1
	v_cvt_pk_f16_f32 v75, v2, v3
	v_cvt_pk_f16_f32 v76, v4, v5
	v_cvt_pk_f16_f32 v77, v6, v7
	v_cvt_f32_f16_e32 v66, v74
	v_cvt_f32_f16_sdwa v67, v74 dst_sel:DWORD dst_unused:UNUSED_PAD src0_sel:WORD_1
	v_cvt_f32_f16_e32 v68, v75
	v_cvt_f32_f16_sdwa v69, v75 dst_sel:DWORD dst_unused:UNUSED_PAD src0_sel:WORD_1
	v_cvt_f32_f16_e32 v70, v76
	v_cvt_f32_f16_sdwa v71, v76 dst_sel:DWORD dst_unused:UNUSED_PAD src0_sel:WORD_1
	v_cvt_f32_f16_e32 v72, v77
	v_cvt_f32_f16_sdwa v73, v77 dst_sel:DWORD dst_unused:UNUSED_PAD src0_sel:WORD_1
	v_pk_add_f32 v[0:1], v[0:1], v[66:67] neg_lo:[0,1] neg_hi:[0,1]
	v_pk_add_f32 v[2:3], v[2:3], v[68:69] neg_lo:[0,1] neg_hi:[0,1]
	v_pk_add_f32 v[4:5], v[4:5], v[70:71] neg_lo:[0,1] neg_hi:[0,1]
	v_pk_add_f32 v[6:7], v[6:7], v[72:73] neg_lo:[0,1] neg_hi:[0,1]
	s_nop 0
	v_cvt_pk_f16_f32 v78, v0, v1
	v_cvt_pk_f16_f32 v79, v2, v3
	v_cvt_pk_f16_f32 v80, v4, v5
	v_cvt_pk_f16_f32 v81, v6, v7
	global_store_dwordx4 v[88:89], v[74:77], off offset:384
	s_waitcnt vmcnt(48)
	v_mfma_f32_16x16x32_f16 a[8:11], v[74:77], a[80:83], a[8:11]
	v_mfma_f32_16x16x32_f16 a[8:11], v[78:81], a[80:83], a[8:11]
	v_mfma_f32_16x16x32_f16 a[8:11], v[74:77], a[84:87], a[8:11]
	v_mfma_f32_16x16x32_f16 a[4:7], v[74:77], a[88:91], a[4:7]
	v_mfma_f32_16x16x32_f16 a[4:7], v[78:81], a[88:91], a[4:7]
	v_mfma_f32_16x16x32_f16 a[4:7], v[74:77], a[92:95], a[4:7]
	v_mfma_f32_16x16x32_f16 a[0:3], v[74:77], a[96:99], a[0:3]
	v_mfma_f32_16x16x32_f16 a[0:3], v[78:81], a[96:99], a[0:3]
	v_mfma_f32_16x16x32_f16 a[0:3], v[74:77], a[100:103], a[0:3]
	global_load_dwordx4 a[80:83], v[90:91], off offset:768
	global_load_dwordx4 a[84:87], v[92:93], off offset:768
	global_load_dwordx4 a[88:91], v[94:95], off offset:768
	global_load_dwordx4 a[92:95], v[96:97], off offset:768
	global_load_dwordx4 a[96:99], v[98:99], off offset:768
	global_load_dwordx4 a[100:103], v[100:101], off offset:768
	s_waitcnt vmcnt(54)
	v_accvgpr_read_b32 v0, a72
	v_accvgpr_read_b32 v1, a73
	v_accvgpr_read_b32 v2, a74
	v_accvgpr_read_b32 v3, a75
	v_accvgpr_read_b32 v4, a76
	v_accvgpr_read_b32 v5, a77
	v_accvgpr_read_b32 v6, a78
	v_accvgpr_read_b32 v7, a79
	global_load_dwordx4 a[72:75], v[22:23], off offset:2176
	global_load_dwordx4 a[76:79], v[22:23], off offset:2192
	v_pk_mul_f32 v[0:1], v[28:29], v[0:1]
	v_pk_mul_f32 v[2:3], v[28:29], v[2:3]
	v_pk_mul_f32 v[4:5], v[28:29], v[4:5]
	v_pk_mul_f32 v[6:7], v[28:29], v[6:7]
	s_waitcnt lgkmcnt(0)
	v_pk_mul_f32 v[0:1], v[0:1], v[32:33]
	v_pk_mul_f32 v[2:3], v[2:3], v[34:35]
	v_pk_mul_f32 v[4:5], v[4:5], v[36:37]
	v_pk_mul_f32 v[6:7], v[6:7], v[38:39]
	v_pk_add_f32 v[40:41], v[40:41], 1.0 op_sel_hi:[1,0]
	v_pk_add_f32 v[42:43], v[42:43], 1.0 op_sel_hi:[1,0]
	v_pk_add_f32 v[44:45], v[44:45], 1.0 op_sel_hi:[1,0]
	v_pk_add_f32 v[46:47], v[46:47], 1.0 op_sel_hi:[1,0]
	v_pk_fma_f32 v[0:1], v[0:1], v[40:41], v[58:59]
	v_pk_fma_f32 v[2:3], v[2:3], v[42:43], v[60:61]
	v_pk_fma_f32 v[4:5], v[4:5], v[44:45], v[62:63]
	v_pk_fma_f32 v[6:7], v[6:7], v[46:47], v[64:65]
	ds_read_b128 v[32:35], v102 offset:1024
	ds_read_b128 v[36:39], v102 offset:1040
	ds_read_b128 v[40:43], v102 offset:5120
	ds_read_b128 v[44:47], v102 offset:5136
	ds_read_b128 v[58:61], v102 offset:9216
	ds_read_b128 v[62:65], v102 offset:9232
	v_cvt_pk_f16_f32 v74, v0, v1
	v_cvt_pk_f16_f32 v75, v2, v3
	v_cvt_pk_f16_f32 v76, v4, v5
	v_cvt_pk_f16_f32 v77, v6, v7
	v_cvt_f32_f16_e32 v66, v74
	v_cvt_f32_f16_sdwa v67, v74 dst_sel:DWORD dst_unused:UNUSED_PAD src0_sel:WORD_1
	v_cvt_f32_f16_e32 v68, v75
	v_cvt_f32_f16_sdwa v69, v75 dst_sel:DWORD dst_unused:UNUSED_PAD src0_sel:WORD_1
	v_cvt_f32_f16_e32 v70, v76
	v_cvt_f32_f16_sdwa v71, v76 dst_sel:DWORD dst_unused:UNUSED_PAD src0_sel:WORD_1
	v_cvt_f32_f16_e32 v72, v77
	v_cvt_f32_f16_sdwa v73, v77 dst_sel:DWORD dst_unused:UNUSED_PAD src0_sel:WORD_1
	v_pk_add_f32 v[0:1], v[0:1], v[66:67] neg_lo:[0,1] neg_hi:[0,1]
	v_pk_add_f32 v[2:3], v[2:3], v[68:69] neg_lo:[0,1] neg_hi:[0,1]
	v_pk_add_f32 v[4:5], v[4:5], v[70:71] neg_lo:[0,1] neg_hi:[0,1]
	v_pk_add_f32 v[6:7], v[6:7], v[72:73] neg_lo:[0,1] neg_hi:[0,1]
	s_nop 0
	v_cvt_pk_f16_f32 v78, v0, v1
	v_cvt_pk_f16_f32 v79, v2, v3
	v_cvt_pk_f16_f32 v80, v4, v5
	v_cvt_pk_f16_f32 v81, v6, v7
	global_store_dwordx4 v[88:89], v[74:77], off offset:448
	s_waitcnt vmcnt(48)
; DI f4 mfma16(h8 a, h8 b, f4 c) { return __builtin_amdgcn_mfma_f32_16x16x32_f16(a, b, c, 0, 0, 0); }
; DI void row2_phase(const Params& P, int l, int r_begin, char* smem) {
;     ...
; #pragma unroll 4
;     for (int kk = 0; kk < 32; kk++) {
;       const int k0 = kk * 32;
;       float x[8], g[8], s1[8], s0[8];
;       *(float4*)&x[0] = *(const float4*)(xm + k0); *(float4*)&x[4] = *(const float4*)(xm + k0 + 4);
;       *(float4*)&g[0] = *(const float4*)(gam + fq * 8 + k0); *(float4*)&g[4] = *(const float4*)(gam + fq * 8 + k0 + 4);
;       *(float4*)&s1[0] = *(const float4*)(sc + k0); *(float4*)&s1[4] = *(const float4*)(sc + k0 + 4);
;       *(float4*)&s0[0] = *(const float4*)(sh + k0); *(float4*)&s0[4] = *(const float4*)(sh + k0 + 4);
;       h8 hi, lo;
; #pragma unroll
;       for (int i = 0; i < 8; i++) {
;         float v = x[i] * rstd * g[i] * (1.f + s1[i]) + s0[i];
;         hi[i] = (half_t)v; lo[i] = (half_t)(v - (float)hi[i]);
;       }
;       *(h8*)(hxo + k0) = hi;
; #pragma unroll
;       for (int n3 = 0; n3 < 3; n3++) {
;         h8 bh = *(const h8*)(Whi + (size_t)(n3 * 16 + fr) * 1024 + k0 + fq * 8);
;         h8 bl = *(const h8*)(Wlo + (size_t)(n3 * 16 + fr) * 1024 + k0 + fq * 8);
;         acc[n3] = mfma16(hi, bh, acc[n3]); acc[n3] = mfma16(lo, bh, acc[n3]); acc[n3] = mfma16(hi, bl, acc[n3]);
;       }
;     }
	v_mfma_f32_16x16x32_f16 a[8:11], v[74:77], a[104:107], a[8:11]
	v_mfma_f32_16x16x32_f16 a[8:11], v[78:81], a[104:107], a[8:11]
	v_mfma_f32_16x16x32_f16 a[8:11], v[74:77], a[108:111], a[8:11]
	v_mfma_f32_16x16x32_f16 a[4:7], v[74:77], a[112:115], a[4:7]
	v_mfma_f32_16x16x32_f16 a[4:7], v[78:81], a[112:115], a[4:7]
	v_mfma_f32_16x16x32_f16 a[4:7], v[74:77], a[116:119], a[4:7]
	v_mfma_f32_16x16x32_f16 a[0:3], v[74:77], a[120:123], a[0:3]
	v_mfma_f32_16x16x32_f16 a[0:3], v[78:81], a[120:123], a[0:3]
	v_mfma_f32_16x16x32_f16 a[0:3], v[74:77], a[124:127], a[0:3]
	global_load_dwordx4 a[104:107], v[90:91], off offset:832
	global_load_dwordx4 a[108:111], v[92:93], off offset:832
	global_load_dwordx4 a[112:115], v[94:95], off offset:832
	global_load_dwordx4 a[116:119], v[96:97], off offset:832
	global_load_dwordx4 a[120:123], v[98:99], off offset:832
	global_load_dwordx4 a[124:127], v[100:101], off offset:832
	s_waitcnt vmcnt(54)
	v_accvgpr_read_b32 v0, a180
	v_accvgpr_read_b32 v1, a181
	v_accvgpr_read_b32 v2, a182
	v_accvgpr_read_b32 v3, a183
	v_accvgpr_read_b32 v4, a184
	v_accvgpr_read_b32 v5, a185
	v_accvgpr_read_b32 v6, a186
	v_accvgpr_read_b32 v7, a187
	global_load_dwordx4 a[180:183], v[22:23], off offset:2304
	global_load_dwordx4 a[184:187], v[22:23], off offset:2320
	v_pk_mul_f32 v[0:1], v[28:29], v[0:1]
	v_pk_mul_f32 v[2:3], v[28:29], v[2:3]
	v_pk_mul_f32 v[4:5], v[28:29], v[4:5]
	v_pk_mul_f32 v[6:7], v[28:29], v[6:7]
	s_waitcnt lgkmcnt(0)
	v_pk_mul_f32 v[0:1], v[0:1], v[32:33]
	v_pk_mul_f32 v[2:3], v[2:3], v[34:35]
	v_pk_mul_f32 v[4:5], v[4:5], v[36:37]
	v_pk_mul_f32 v[6:7], v[6:7], v[38:39]
	v_pk_add_f32 v[40:41], v[40:41], 1.0 op_sel_hi:[1,0]
	v_pk_add_f32 v[42:43], v[42:43], 1.0 op_sel_hi:[1,0]
	v_pk_add_f32 v[44:45], v[44:45], 1.0 op_sel_hi:[1,0]
	v_pk_add_f32 v[46:47], v[46:47], 1.0 op_sel_hi:[1,0]
	v_pk_fma_f32 v[0:1], v[0:1], v[40:41], v[58:59]
	v_pk_fma_f32 v[2:3], v[2:3], v[42:43], v[60:61]
	v_pk_fma_f32 v[4:5], v[4:5], v[44:45], v[62:63]
	v_pk_fma_f32 v[6:7], v[6:7], v[46:47], v[64:65]
	ds_read_b128 v[32:35], v102 offset:1152
	ds_read_b128 v[36:39], v102 offset:1168
	ds_read_b128 v[40:43], v102 offset:5248
	ds_read_b128 v[44:47], v102 offset:5264
	ds_read_b128 v[58:61], v102 offset:9344
	ds_read_b128 v[62:65], v102 offset:9360
	v_cvt_pk_f16_f32 v74, v0, v1
	v_cvt_pk_f16_f32 v75, v2, v3
	v_cvt_pk_f16_f32 v76, v4, v5
	v_cvt_pk_f16_f32 v77, v6, v7
	v_cvt_f32_f16_e32 v66, v74
	v_cvt_f32_f16_sdwa v67, v74 dst_sel:DWORD dst_unused:UNUSED_PAD src0_sel:WORD_1
	v_cvt_f32_f16_e32 v68, v75
	v_cvt_f32_f16_sdwa v69, v75 dst_sel:DWORD dst_unused:UNUSED_PAD src0_sel:WORD_1
	v_cvt_f32_f16_e32 v70, v76
	v_cvt_f32_f16_sdwa v71, v76 dst_sel:DWORD dst_unused:UNUSED_PAD src0_sel:WORD_1
	v_cvt_f32_f16_e32 v72, v77
	v_cvt_f32_f16_sdwa v73, v77 dst_sel:DWORD dst_unused:UNUSED_PAD src0_sel:WORD_1
	v_pk_add_f32 v[0:1], v[0:1], v[66:67] neg_lo:[0,1] neg_hi:[0,1]
	v_pk_add_f32 v[2:3], v[2:3], v[68:69] neg_lo:[0,1] neg_hi:[0,1]
	v_pk_add_f32 v[4:5], v[4:5], v[70:71] neg_lo:[0,1] neg_hi:[0,1]
	v_pk_add_f32 v[6:7], v[6:7], v[72:73] neg_lo:[0,1] neg_hi:[0,1]
	s_nop 0
	v_cvt_pk_f16_f32 v78, v0, v1
	v_cvt_pk_f16_f32 v79, v2, v3
	v_cvt_pk_f16_f32 v80, v4, v5
	v_cvt_pk_f16_f32 v81, v6, v7
	global_store_dwordx4 v[88:89], v[74:77], off offset:512
	s_waitcnt vmcnt(48)
	v_mfma_f32_16x16x32_f16 a[8:11], v[74:77], a[128:131], a[8:11]
	v_mfma_f32_16x16x32_f16 a[8:11], v[78:81], a[128:131], a[8:11]
	v_mfma_f32_16x16x32_f16 a[8:11], v[74:77], a[132:135], a[8:11]
	v_mfma_f32_16x16x32_f16 a[4:7], v[74:77], a[136:139], a[4:7]
	v_mfma_f32_16x16x32_f16 a[4:7], v[78:81], a[136:139], a[4:7]
	v_mfma_f32_16x16x32_f16 a[4:7], v[74:77], a[140:143], a[4:7]
	v_mfma_f32_16x16x32_f16 a[0:3], v[74:77], a[144:147], a[0:3]
	v_mfma_f32_16x16x32_f16 a[0:3], v[78:81], a[144:147], a[0:3]
	v_mfma_f32_16x16x32_f16 a[0:3], v[74:77], a[148:151], a[0:3]
	global_load_dwordx4 a[128:131], v[90:91], off offset:896
	global_load_dwordx4 a[132:135], v[92:93], off offset:896
	global_load_dwordx4 a[136:139], v[94:95], off offset:896
	global_load_dwordx4 a[140:143], v[96:97], off offset:896
	global_load_dwordx4 a[144:147], v[98:99], off offset:896
	global_load_dwordx4 a[148:151], v[100:101], off offset:896
	s_waitcnt vmcnt(54)
	v_accvgpr_read_b32 v0, a196
	v_accvgpr_read_b32 v1, a197
	v_accvgpr_read_b32 v2, a198
	v_accvgpr_read_b32 v3, a199
	v_accvgpr_read_b32 v4, a200
	v_accvgpr_read_b32 v5, a201
	v_accvgpr_read_b32 v6, a202
	v_accvgpr_read_b32 v7, a203
	global_load_dwordx4 a[196:199], v[22:23], off offset:2432
	global_load_dwordx4 a[200:203], v[22:23], off offset:2448
	v_pk_mul_f32 v[0:1], v[28:29], v[0:1]
	v_pk_mul_f32 v[2:3], v[28:29], v[2:3]
	v_pk_mul_f32 v[4:5], v[28:29], v[4:5]
	v_pk_mul_f32 v[6:7], v[28:29], v[6:7]
	s_waitcnt lgkmcnt(0)
; DI f4 mfma16(h8 a, h8 b, f4 c) { return __builtin_amdgcn_mfma_f32_16x16x32_f16(a, b, c, 0, 0, 0); }
; DI void row2_phase(const Params& P, int l, int r_begin, char* smem) {
;     ...
; #pragma unroll 4
;     for (int kk = 0; kk < 32; kk++) {
;       const int k0 = kk * 32;
;       float x[8], g[8], s1[8], s0[8];
;       *(float4*)&x[0] = *(const float4*)(xm + k0); *(float4*)&x[4] = *(const float4*)(xm + k0 + 4);
;       *(float4*)&g[0] = *(const float4*)(gam + fq * 8 + k0); *(float4*)&g[4] = *(const float4*)(gam + fq * 8 + k0 + 4);
;       *(float4*)&s1[0] = *(const float4*)(sc + k0); *(float4*)&s1[4] = *(const float4*)(sc + k0 + 4);
;       *(float4*)&s0[0] = *(const float4*)(sh + k0); *(float4*)&s0[4] = *(const float4*)(sh + k0 + 4);
;       h8 hi, lo;
; #pragma unroll
;       for (int i = 0; i < 8; i++) {
;         float v = x[i] * rstd * g[i] * (1.f + s1[i]) + s0[i];
;         hi[i] = (half_t)v; lo[i] = (half_t)(v - (float)hi[i]);
;       }
;       *(h8*)(hxo + k0) = hi;
; #pragma unroll
;       for (int n3 = 0; n3 < 3; n3++) {
;         h8 bh = *(const h8*)(Whi + (size_t)(n3 * 16 + fr) * 1024 + k0 + fq * 8);
;         h8 bl = *(const h8*)(Wlo + (size_t)(n3 * 16 + fr) * 1024 + k0 + fq * 8);
;         acc[n3] = mfma16(hi, bh, acc[n3]); acc[n3] = mfma16(lo, bh, acc[n3]); acc[n3] = mfma16(hi, bl, acc[n3]);
;       }
;     }
	v_pk_mul_f32 v[0:1], v[0:1], v[32:33]
	v_pk_mul_f32 v[2:3], v[2:3], v[34:35]
	v_pk_mul_f32 v[4:5], v[4:5], v[36:37]
	v_pk_mul_f32 v[6:7], v[6:7], v[38:39]
	v_pk_add_f32 v[40:41], v[40:41], 1.0 op_sel_hi:[1,0]
	v_pk_add_f32 v[42:43], v[42:43], 1.0 op_sel_hi:[1,0]
	v_pk_add_f32 v[44:45], v[44:45], 1.0 op_sel_hi:[1,0]
	v_pk_add_f32 v[46:47], v[46:47], 1.0 op_sel_hi:[1,0]
	v_pk_fma_f32 v[0:1], v[0:1], v[40:41], v[58:59]
	v_pk_fma_f32 v[2:3], v[2:3], v[42:43], v[60:61]
	v_pk_fma_f32 v[4:5], v[4:5], v[44:45], v[62:63]
	v_pk_fma_f32 v[6:7], v[6:7], v[46:47], v[64:65]
	ds_read_b128 v[32:35], v102 offset:1280
	ds_read_b128 v[36:39], v102 offset:1296
	ds_read_b128 v[40:43], v102 offset:5376
	ds_read_b128 v[44:47], v102 offset:5392
	ds_read_b128 v[58:61], v102 offset:9472
	ds_read_b128 v[62:65], v102 offset:9488
	v_cvt_pk_f16_f32 v74, v0, v1
	v_cvt_pk_f16_f32 v75, v2, v3
	v_cvt_pk_f16_f32 v76, v4, v5
	v_cvt_pk_f16_f32 v77, v6, v7
	v_cvt_f32_f16_e32 v66, v74
	v_cvt_f32_f16_sdwa v67, v74 dst_sel:DWORD dst_unused:UNUSED_PAD src0_sel:WORD_1
	v_cvt_f32_f16_e32 v68, v75
	v_cvt_f32_f16_sdwa v69, v75 dst_sel:DWORD dst_unused:UNUSED_PAD src0_sel:WORD_1
	v_cvt_f32_f16_e32 v70, v76
	v_cvt_f32_f16_sdwa v71, v76 dst_sel:DWORD dst_unused:UNUSED_PAD src0_sel:WORD_1
	v_cvt_f32_f16_e32 v72, v77
	v_cvt_f32_f16_sdwa v73, v77 dst_sel:DWORD dst_unused:UNUSED_PAD src0_sel:WORD_1
	v_pk_add_f32 v[0:1], v[0:1], v[66:67] neg_lo:[0,1] neg_hi:[0,1]
	v_pk_add_f32 v[2:3], v[2:3], v[68:69] neg_lo:[0,1] neg_hi:[0,1]
	v_pk_add_f32 v[4:5], v[4:5], v[70:71] neg_lo:[0,1] neg_hi:[0,1]
	v_pk_add_f32 v[6:7], v[6:7], v[72:73] neg_lo:[0,1] neg_hi:[0,1]
	s_nop 0
	v_cvt_pk_f16_f32 v78, v0, v1
	v_cvt_pk_f16_f32 v79, v2, v3
	v_cvt_pk_f16_f32 v80, v4, v5
	v_cvt_pk_f16_f32 v81, v6, v7
	global_store_dwordx4 v[88:89], v[74:77], off offset:576
	s_waitcnt vmcnt(48)
	v_mfma_f32_16x16x32_f16 a[8:11], v[74:77], a[152:155], a[8:11]
	v_mfma_f32_16x16x32_f16 a[8:11], v[78:81], a[152:155], a[8:11]
	v_mfma_f32_16x16x32_f16 a[8:11], v[74:77], a[156:159], a[8:11]
	v_mfma_f32_16x16x32_f16 a[4:7], v[74:77], a[160:163], a[4:7]
	v_mfma_f32_16x16x32_f16 a[4:7], v[78:81], a[160:163], a[4:7]
	v_mfma_f32_16x16x32_f16 a[4:7], v[74:77], a[164:167], a[4:7]
	v_mfma_f32_16x16x32_f16 a[0:3], v[74:77], a[168:171], a[0:3]
	v_mfma_f32_16x16x32_f16 a[0:3], v[78:81], a[168:171], a[0:3]
	v_mfma_f32_16x16x32_f16 a[0:3], v[74:77], a[172:175], a[0:3]
	global_load_dwordx4 a[152:155], v[90:91], off offset:960
	global_load_dwordx4 a[156:159], v[92:93], off offset:960
	global_load_dwordx4 a[160:163], v[94:95], off offset:960
	global_load_dwordx4 a[164:167], v[96:97], off offset:960
	global_load_dwordx4 a[168:171], v[98:99], off offset:960
	global_load_dwordx4 a[172:175], v[100:101], off offset:960
	s_waitcnt vmcnt(54)
	v_accvgpr_read_b32 v0, a16
	v_accvgpr_read_b32 v1, a17
	v_accvgpr_read_b32 v2, a18
	v_accvgpr_read_b32 v3, a19
	v_accvgpr_read_b32 v4, a20
	v_accvgpr_read_b32 v5, a21
	v_accvgpr_read_b32 v6, a22
	v_accvgpr_read_b32 v7, a23
	global_load_dwordx4 a[16:19], v[22:23], off offset:2560
	global_load_dwordx4 a[20:23], v[22:23], off offset:2576
	v_pk_mul_f32 v[0:1], v[28:29], v[0:1]
	v_pk_mul_f32 v[2:3], v[28:29], v[2:3]
	v_pk_mul_f32 v[4:5], v[28:29], v[4:5]
	v_pk_mul_f32 v[6:7], v[28:29], v[6:7]
	s_waitcnt lgkmcnt(0)
	v_pk_mul_f32 v[0:1], v[0:1], v[32:33]
	v_pk_mul_f32 v[2:3], v[2:3], v[34:35]
	v_pk_mul_f32 v[4:5], v[4:5], v[36:37]
	v_pk_mul_f32 v[6:7], v[6:7], v[38:39]
	v_pk_add_f32 v[40:41], v[40:41], 1.0 op_sel_hi:[1,0]
	v_pk_add_f32 v[42:43], v[42:43], 1.0 op_sel_hi:[1,0]
	v_pk_add_f32 v[44:45], v[44:45], 1.0 op_sel_hi:[1,0]
	v_pk_add_f32 v[46:47], v[46:47], 1.0 op_sel_hi:[1,0]
	v_pk_fma_f32 v[0:1], v[0:1], v[40:41], v[58:59]
	v_pk_fma_f32 v[2:3], v[2:3], v[42:43], v[60:61]
	v_pk_fma_f32 v[4:5], v[4:5], v[44:45], v[62:63]
	v_pk_fma_f32 v[6:7], v[6:7], v[46:47], v[64:65]
	ds_read_b128 v[32:35], v102 offset:1408
	ds_read_b128 v[36:39], v102 offset:1424
	ds_read_b128 v[40:43], v102 offset:5504
	ds_read_b128 v[44:47], v102 offset:5520
	ds_read_b128 v[58:61], v102 offset:9600
	ds_read_b128 v[62:65], v102 offset:9616
	v_cvt_pk_f16_f32 v74, v0, v1
	v_cvt_pk_f16_f32 v75, v2, v3
	v_cvt_pk_f16_f32 v76, v4, v5
	v_cvt_pk_f16_f32 v77, v6, v7
	v_cvt_f32_f16_e32 v66, v74
	v_cvt_f32_f16_sdwa v67, v74 dst_sel:DWORD dst_unused:UNUSED_PAD src0_sel:WORD_1
	v_cvt_f32_f16_e32 v68, v75
	v_cvt_f32_f16_sdwa v69, v75 dst_sel:DWORD dst_unused:UNUSED_PAD src0_sel:WORD_1
	v_cvt_f32_f16_e32 v70, v76
	v_cvt_f32_f16_sdwa v71, v76 dst_sel:DWORD dst_unused:UNUSED_PAD src0_sel:WORD_1
	v_cvt_f32_f16_e32 v72, v77
	v_cvt_f32_f16_sdwa v73, v77 dst_sel:DWORD dst_unused:UNUSED_PAD src0_sel:WORD_1
	v_pk_add_f32 v[0:1], v[0:1], v[66:67] neg_lo:[0,1] neg_hi:[0,1]
	v_pk_add_f32 v[2:3], v[2:3], v[68:69] neg_lo:[0,1] neg_hi:[0,1]
	v_pk_add_f32 v[4:5], v[4:5], v[70:71] neg_lo:[0,1] neg_hi:[0,1]
	v_pk_add_f32 v[6:7], v[6:7], v[72:73] neg_lo:[0,1] neg_hi:[0,1]
	s_nop 0
	v_cvt_pk_f16_f32 v78, v0, v1
	v_cvt_pk_f16_f32 v79, v2, v3
	v_cvt_pk_f16_f32 v80, v4, v5
	v_cvt_pk_f16_f32 v81, v6, v7
	global_store_dwordx4 v[88:89], v[74:77], off offset:640
	s_waitcnt vmcnt(48)
	v_mfma_f32_16x16x32_f16 a[8:11], v[74:77], a[204:207], a[8:11]
	v_mfma_f32_16x16x32_f16 a[8:11], v[78:81], a[204:207], a[8:11]
	v_mfma_f32_16x16x32_f16 a[8:11], v[74:77], a[208:211], a[8:11]
	v_mfma_f32_16x16x32_f16 a[4:7], v[74:77], a[212:215], a[4:7]
	v_mfma_f32_16x16x32_f16 a[4:7], v[78:81], a[212:215], a[4:7]
	v_mfma_f32_16x16x32_f16 a[4:7], v[74:77], a[216:219], a[4:7]
	v_mfma_f32_16x16x32_f16 a[0:3], v[74:77], a[220:223], a[0:3]
	v_mfma_f32_16x16x32_f16 a[0:3], v[78:81], a[220:223], a[0:3]
	v_mfma_f32_16x16x32_f16 a[0:3], v[74:77], a[224:227], a[0:3]
	global_load_dwordx4 a[204:207], v[90:91], off offset:1024
	global_load_dwordx4 a[208:211], v[92:93], off offset:1024
	global_load_dwordx4 a[212:215], v[94:95], off offset:1024
	global_load_dwordx4 a[216:219], v[96:97], off offset:1024
	global_load_dwordx4 a[220:223], v[98:99], off offset:1024
	global_load_dwordx4 a[224:227], v[100:101], off offset:1024
	s_waitcnt vmcnt(54)
; DI f4 mfma16(h8 a, h8 b, f4 c) { return __builtin_amdgcn_mfma_f32_16x16x32_f16(a, b, c, 0, 0, 0); }
; DI void row2_phase(const Params& P, int l, int r_begin, char* smem) {
;     ...
; #pragma unroll 4
;     for (int kk = 0; kk < 32; kk++) {
;       const int k0 = kk * 32;
;       float x[8], g[8], s1[8], s0[8];
;       *(float4*)&x[0] = *(const float4*)(xm + k0); *(float4*)&x[4] = *(const float4*)(xm + k0 + 4);
;       *(float4*)&g[0] = *(const float4*)(gam + fq * 8 + k0); *(float4*)&g[4] = *(const float4*)(gam + fq * 8 + k0 + 4);
;       *(float4*)&s1[0] = *(const float4*)(sc + k0); *(float4*)&s1[4] = *(const float4*)(sc + k0 + 4);
;       *(float4*)&s0[0] = *(const float4*)(sh + k0); *(float4*)&s0[4] = *(const float4*)(sh + k0 + 4);
;       h8 hi, lo;
; #pragma unroll
;       for (int i = 0; i < 8; i++) {
;         float v = x[i] * rstd * g[i] * (1.f + s1[i]) + s0[i];
;         hi[i] = (half_t)v; lo[i] = (half_t)(v - (float)hi[i]);
;       }
;       *(h8*)(hxo + k0) = hi;
; #pragma unroll
;       for (int n3 = 0; n3 < 3; n3++) {
;         h8 bh = *(const h8*)(Whi + (size_t)(n3 * 16 + fr) * 1024 + k0 + fq * 8);
;         h8 bl = *(const h8*)(Wlo + (size_t)(n3 * 16 + fr) * 1024 + k0 + fq * 8);
;         acc[n3] = mfma16(hi, bh, acc[n3]); acc[n3] = mfma16(lo, bh, acc[n3]); acc[n3] = mfma16(hi, bl, acc[n3]);
;       }
;     }
	v_accvgpr_read_b32 v0, a24
	v_accvgpr_read_b32 v1, a25
	v_accvgpr_read_b32 v2, a26
	v_accvgpr_read_b32 v3, a27
	v_accvgpr_read_b32 v4, a28
	v_accvgpr_read_b32 v5, a29
	v_accvgpr_read_b32 v6, a30
	v_accvgpr_read_b32 v7, a31
	global_load_dwordx4 a[24:27], v[22:23], off offset:2688
	global_load_dwordx4 a[28:31], v[22:23], off offset:2704
	v_pk_mul_f32 v[0:1], v[28:29], v[0:1]
	v_pk_mul_f32 v[2:3], v[28:29], v[2:3]
	v_pk_mul_f32 v[4:5], v[28:29], v[4:5]
	v_pk_mul_f32 v[6:7], v[28:29], v[6:7]
	s_waitcnt lgkmcnt(0)
	v_pk_mul_f32 v[0:1], v[0:1], v[32:33]
	v_pk_mul_f32 v[2:3], v[2:3], v[34:35]
	v_pk_mul_f32 v[4:5], v[4:5], v[36:37]
	v_pk_mul_f32 v[6:7], v[6:7], v[38:39]
	v_pk_add_f32 v[40:41], v[40:41], 1.0 op_sel_hi:[1,0]
	v_pk_add_f32 v[42:43], v[42:43], 1.0 op_sel_hi:[1,0]
	v_pk_add_f32 v[44:45], v[44:45], 1.0 op_sel_hi:[1,0]
	v_pk_add_f32 v[46:47], v[46:47], 1.0 op_sel_hi:[1,0]
	v_pk_fma_f32 v[0:1], v[0:1], v[40:41], v[58:59]
	v_pk_fma_f32 v[2:3], v[2:3], v[42:43], v[60:61]
	v_pk_fma_f32 v[4:5], v[4:5], v[44:45], v[62:63]
	v_pk_fma_f32 v[6:7], v[6:7], v[46:47], v[64:65]
	ds_read_b128 v[32:35], v102 offset:1536
	ds_read_b128 v[36:39], v102 offset:1552
	ds_read_b128 v[40:43], v102 offset:5632
	ds_read_b128 v[44:47], v102 offset:5648
	ds_read_b128 v[58:61], v102 offset:9728
	ds_read_b128 v[62:65], v102 offset:9744
	v_cvt_pk_f16_f32 v74, v0, v1
	v_cvt_pk_f16_f32 v75, v2, v3
	v_cvt_pk_f16_f32 v76, v4, v5
	v_cvt_pk_f16_f32 v77, v6, v7
	v_cvt_f32_f16_e32 v66, v74
	v_cvt_f32_f16_sdwa v67, v74 dst_sel:DWORD dst_unused:UNUSED_PAD src0_sel:WORD_1
	v_cvt_f32_f16_e32 v68, v75
	v_cvt_f32_f16_sdwa v69, v75 dst_sel:DWORD dst_unused:UNUSED_PAD src0_sel:WORD_1
	v_cvt_f32_f16_e32 v70, v76
	v_cvt_f32_f16_sdwa v71, v76 dst_sel:DWORD dst_unused:UNUSED_PAD src0_sel:WORD_1
	v_cvt_f32_f16_e32 v72, v77
	v_cvt_f32_f16_sdwa v73, v77 dst_sel:DWORD dst_unused:UNUSED_PAD src0_sel:WORD_1
	v_pk_add_f32 v[0:1], v[0:1], v[66:67] neg_lo:[0,1] neg_hi:[0,1]
	v_pk_add_f32 v[2:3], v[2:3], v[68:69] neg_lo:[0,1] neg_hi:[0,1]
	v_pk_add_f32 v[4:5], v[4:5], v[70:71] neg_lo:[0,1] neg_hi:[0,1]
	v_pk_add_f32 v[6:7], v[6:7], v[72:73] neg_lo:[0,1] neg_hi:[0,1]
	s_nop 0
	v_cvt_pk_f16_f32 v78, v0, v1
	v_cvt_pk_f16_f32 v79, v2, v3
	v_cvt_pk_f16_f32 v80, v4, v5
	v_cvt_pk_f16_f32 v81, v6, v7
	global_store_dwordx4 v[88:89], v[74:77], off offset:704
	s_waitcnt vmcnt(48)
	v_mfma_f32_16x16x32_f16 a[8:11], v[74:77], a[228:231], a[8:11]
	v_mfma_f32_16x16x32_f16 a[8:11], v[78:81], a[228:231], a[8:11]
	v_mfma_f32_16x16x32_f16 a[8:11], v[74:77], a[232:235], a[8:11]
	v_mfma_f32_16x16x32_f16 a[4:7], v[74:77], a[236:239], a[4:7]
	v_mfma_f32_16x16x32_f16 a[4:7], v[78:81], a[236:239], a[4:7]
	v_mfma_f32_16x16x32_f16 a[4:7], v[74:77], a[240:243], a[4:7]
	v_mfma_f32_16x16x32_f16 a[0:3], v[74:77], a[244:247], a[0:3]
	v_mfma_f32_16x16x32_f16 a[0:3], v[78:81], a[244:247], a[0:3]
	v_mfma_f32_16x16x32_f16 a[0:3], v[74:77], a[248:251], a[0:3]
	global_load_dwordx4 a[228:231], v[90:91], off offset:1088
	global_load_dwordx4 a[232:235], v[92:93], off offset:1088
	global_load_dwordx4 a[236:239], v[94:95], off offset:1088
	global_load_dwordx4 a[240:243], v[96:97], off offset:1088
	global_load_dwordx4 a[244:247], v[98:99], off offset:1088
	global_load_dwordx4 a[248:251], v[100:101], off offset:1088
	s_waitcnt vmcnt(54)
	v_accvgpr_read_b32 v0, a32
	v_accvgpr_read_b32 v1, a33
	v_accvgpr_read_b32 v2, a34
	v_accvgpr_read_b32 v3, a35
	v_accvgpr_read_b32 v4, a36
	v_accvgpr_read_b32 v5, a37
	v_accvgpr_read_b32 v6, a38
	v_accvgpr_read_b32 v7, a39
	global_load_dwordx4 a[32:35], v[22:23], off offset:2816
	global_load_dwordx4 a[36:39], v[22:23], off offset:2832
	v_pk_mul_f32 v[0:1], v[28:29], v[0:1]
	v_pk_mul_f32 v[2:3], v[28:29], v[2:3]
	v_pk_mul_f32 v[4:5], v[28:29], v[4:5]
	v_pk_mul_f32 v[6:7], v[28:29], v[6:7]
	s_waitcnt lgkmcnt(0)
	v_pk_mul_f32 v[0:1], v[0:1], v[32:33]
	v_pk_mul_f32 v[2:3], v[2:3], v[34:35]
	v_pk_mul_f32 v[4:5], v[4:5], v[36:37]
	v_pk_mul_f32 v[6:7], v[6:7], v[38:39]
	v_pk_add_f32 v[40:41], v[40:41], 1.0 op_sel_hi:[1,0]
	v_pk_add_f32 v[42:43], v[42:43], 1.0 op_sel_hi:[1,0]
	v_pk_add_f32 v[44:45], v[44:45], 1.0 op_sel_hi:[1,0]
	v_pk_add_f32 v[46:47], v[46:47], 1.0 op_sel_hi:[1,0]
	v_pk_fma_f32 v[0:1], v[0:1], v[40:41], v[58:59]
	v_pk_fma_f32 v[2:3], v[2:3], v[42:43], v[60:61]
	v_pk_fma_f32 v[4:5], v[4:5], v[44:45], v[62:63]
	v_pk_fma_f32 v[6:7], v[6:7], v[46:47], v[64:65]
	ds_read_b128 v[32:35], v102 offset:1664
	ds_read_b128 v[36:39], v102 offset:1680
	ds_read_b128 v[40:43], v102 offset:5760
	ds_read_b128 v[44:47], v102 offset:5776
	ds_read_b128 v[58:61], v102 offset:9856
	ds_read_b128 v[62:65], v102 offset:9872
	v_cvt_pk_f16_f32 v74, v0, v1
	v_cvt_pk_f16_f32 v75, v2, v3
	v_cvt_pk_f16_f32 v76, v4, v5
	v_cvt_pk_f16_f32 v77, v6, v7
	v_cvt_f32_f16_e32 v66, v74
	v_cvt_f32_f16_sdwa v67, v74 dst_sel:DWORD dst_unused:UNUSED_PAD src0_sel:WORD_1
	v_cvt_f32_f16_e32 v68, v75
	v_cvt_f32_f16_sdwa v69, v75 dst_sel:DWORD dst_unused:UNUSED_PAD src0_sel:WORD_1
	v_cvt_f32_f16_e32 v70, v76
	v_cvt_f32_f16_sdwa v71, v76 dst_sel:DWORD dst_unused:UNUSED_PAD src0_sel:WORD_1
	v_cvt_f32_f16_e32 v72, v77
	v_cvt_f32_f16_sdwa v73, v77 dst_sel:DWORD dst_unused:UNUSED_PAD src0_sel:WORD_1
	v_pk_add_f32 v[0:1], v[0:1], v[66:67] neg_lo:[0,1] neg_hi:[0,1]
	v_pk_add_f32 v[2:3], v[2:3], v[68:69] neg_lo:[0,1] neg_hi:[0,1]
	v_pk_add_f32 v[4:5], v[4:5], v[70:71] neg_lo:[0,1] neg_hi:[0,1]
	v_pk_add_f32 v[6:7], v[6:7], v[72:73] neg_lo:[0,1] neg_hi:[0,1]
	s_nop 0
	v_cvt_pk_f16_f32 v78, v0, v1
	v_cvt_pk_f16_f32 v79, v2, v3
	v_cvt_pk_f16_f32 v80, v4, v5
	v_cvt_pk_f16_f32 v81, v6, v7
	global_store_dwordx4 v[88:89], v[74:77], off offset:768
	s_waitcnt vmcnt(48)
; DI f4 mfma16(h8 a, h8 b, f4 c) { return __builtin_amdgcn_mfma_f32_16x16x32_f16(a, b, c, 0, 0, 0); }
; DI void row2_phase(const Params& P, int l, int r_begin, char* smem) {
;     ...
; #pragma unroll 4
;     for (int kk = 0; kk < 32; kk++) {
;       const int k0 = kk * 32;
;       float x[8], g[8], s1[8], s0[8];
;       *(float4*)&x[0] = *(const float4*)(xm + k0); *(float4*)&x[4] = *(const float4*)(xm + k0 + 4);
;       *(float4*)&g[0] = *(const float4*)(gam + fq * 8 + k0); *(float4*)&g[4] = *(const float4*)(gam + fq * 8 + k0 + 4);
;       *(float4*)&s1[0] = *(const float4*)(sc + k0); *(float4*)&s1[4] = *(const float4*)(sc + k0 + 4);
;       *(float4*)&s0[0] = *(const float4*)(sh + k0); *(float4*)&s0[4] = *(const float4*)(sh + k0 + 4);
;       h8 hi, lo;
; #pragma unroll
;       for (int i = 0; i < 8; i++) {
;         float v = x[i] * rstd * g[i] * (1.f + s1[i]) + s0[i];
;         hi[i] = (half_t)v; lo[i] = (half_t)(v - (float)hi[i]);
;       }
;       *(h8*)(hxo + k0) = hi;
; #pragma unroll
;       for (int n3 = 0; n3 < 3; n3++) {
;         h8 bh = *(const h8*)(Whi + (size_t)(n3 * 16 + fr) * 1024 + k0 + fq * 8);
;         h8 bl = *(const h8*)(Wlo + (size_t)(n3 * 16 + fr) * 1024 + k0 + fq * 8);
;         acc[n3] = mfma16(hi, bh, acc[n3]); acc[n3] = mfma16(lo, bh, acc[n3]); acc[n3] = mfma16(hi, bl, acc[n3]);
;       }
;     }
	v_mfma_f32_16x16x32_f16 a[8:11], v[74:77], a[80:83], a[8:11]
	v_mfma_f32_16x16x32_f16 a[8:11], v[78:81], a[80:83], a[8:11]
	v_mfma_f32_16x16x32_f16 a[8:11], v[74:77], a[84:87], a[8:11]
	v_mfma_f32_16x16x32_f16 a[4:7], v[74:77], a[88:91], a[4:7]
	v_mfma_f32_16x16x32_f16 a[4:7], v[78:81], a[88:91], a[4:7]
	v_mfma_f32_16x16x32_f16 a[4:7], v[74:77], a[92:95], a[4:7]
	v_mfma_f32_16x16x32_f16 a[0:3], v[74:77], a[96:99], a[0:3]
	v_mfma_f32_16x16x32_f16 a[0:3], v[78:81], a[96:99], a[0:3]
	v_mfma_f32_16x16x32_f16 a[0:3], v[74:77], a[100:103], a[0:3]
	global_load_dwordx4 a[80:83], v[90:91], off offset:1152
	global_load_dwordx4 a[84:87], v[92:93], off offset:1152
	global_load_dwordx4 a[88:91], v[94:95], off offset:1152
	global_load_dwordx4 a[92:95], v[96:97], off offset:1152
	global_load_dwordx4 a[96:99], v[98:99], off offset:1152
	global_load_dwordx4 a[100:103], v[100:101], off offset:1152
	s_waitcnt vmcnt(54)
	v_accvgpr_read_b32 v0, a40
	v_accvgpr_read_b32 v1, a41
	v_accvgpr_read_b32 v2, a42
	v_accvgpr_read_b32 v3, a43
	v_accvgpr_read_b32 v4, a44
	v_accvgpr_read_b32 v5, a45
	v_accvgpr_read_b32 v6, a46
	v_accvgpr_read_b32 v7, a47
	global_load_dwordx4 a[40:43], v[22:23], off offset:2944
	global_load_dwordx4 a[44:47], v[22:23], off offset:2960
	v_pk_mul_f32 v[0:1], v[28:29], v[0:1]
	v_pk_mul_f32 v[2:3], v[28:29], v[2:3]
	v_pk_mul_f32 v[4:5], v[28:29], v[4:5]
	v_pk_mul_f32 v[6:7], v[28:29], v[6:7]
	s_waitcnt lgkmcnt(0)
	v_pk_mul_f32 v[0:1], v[0:1], v[32:33]
	v_pk_mul_f32 v[2:3], v[2:3], v[34:35]
	v_pk_mul_f32 v[4:5], v[4:5], v[36:37]
	v_pk_mul_f32 v[6:7], v[6:7], v[38:39]
	v_pk_add_f32 v[40:41], v[40:41], 1.0 op_sel_hi:[1,0]
	v_pk_add_f32 v[42:43], v[42:43], 1.0 op_sel_hi:[1,0]
	v_pk_add_f32 v[44:45], v[44:45], 1.0 op_sel_hi:[1,0]
	v_pk_add_f32 v[46:47], v[46:47], 1.0 op_sel_hi:[1,0]
	v_pk_fma_f32 v[0:1], v[0:1], v[40:41], v[58:59]
	v_pk_fma_f32 v[2:3], v[2:3], v[42:43], v[60:61]
	v_pk_fma_f32 v[4:5], v[4:5], v[44:45], v[62:63]
	v_pk_fma_f32 v[6:7], v[6:7], v[46:47], v[64:65]
	ds_read_b128 v[32:35], v102 offset:1792
	ds_read_b128 v[36:39], v102 offset:1808
	ds_read_b128 v[40:43], v102 offset:5888
	ds_read_b128 v[44:47], v102 offset:5904
	ds_read_b128 v[58:61], v102 offset:9984
	ds_read_b128 v[62:65], v102 offset:10000
	v_cvt_pk_f16_f32 v74, v0, v1
	v_cvt_pk_f16_f32 v75, v2, v3
	v_cvt_pk_f16_f32 v76, v4, v5
	v_cvt_pk_f16_f32 v77, v6, v7
	v_cvt_f32_f16_e32 v66, v74
	v_cvt_f32_f16_sdwa v67, v74 dst_sel:DWORD dst_unused:UNUSED_PAD src0_sel:WORD_1
	v_cvt_f32_f16_e32 v68, v75
	v_cvt_f32_f16_sdwa v69, v75 dst_sel:DWORD dst_unused:UNUSED_PAD src0_sel:WORD_1
	v_cvt_f32_f16_e32 v70, v76
	v_cvt_f32_f16_sdwa v71, v76 dst_sel:DWORD dst_unused:UNUSED_PAD src0_sel:WORD_1
	v_cvt_f32_f16_e32 v72, v77
	v_cvt_f32_f16_sdwa v73, v77 dst_sel:DWORD dst_unused:UNUSED_PAD src0_sel:WORD_1
	v_pk_add_f32 v[0:1], v[0:1], v[66:67] neg_lo:[0,1] neg_hi:[0,1]
	v_pk_add_f32 v[2:3], v[2:3], v[68:69] neg_lo:[0,1] neg_hi:[0,1]
	v_pk_add_f32 v[4:5], v[4:5], v[70:71] neg_lo:[0,1] neg_hi:[0,1]
	v_pk_add_f32 v[6:7], v[6:7], v[72:73] neg_lo:[0,1] neg_hi:[0,1]
	s_nop 0
	v_cvt_pk_f16_f32 v78, v0, v1
	v_cvt_pk_f16_f32 v79, v2, v3
	v_cvt_pk_f16_f32 v80, v4, v5
	v_cvt_pk_f16_f32 v81, v6, v7
	global_store_dwordx4 v[88:89], v[74:77], off offset:832
	s_waitcnt vmcnt(48)
	v_mfma_f32_16x16x32_f16 a[8:11], v[74:77], a[104:107], a[8:11]
	v_mfma_f32_16x16x32_f16 a[8:11], v[78:81], a[104:107], a[8:11]
	v_mfma_f32_16x16x32_f16 a[8:11], v[74:77], a[108:111], a[8:11]
	v_mfma_f32_16x16x32_f16 a[4:7], v[74:77], a[112:115], a[4:7]
	v_mfma_f32_16x16x32_f16 a[4:7], v[78:81], a[112:115], a[4:7]
	v_mfma_f32_16x16x32_f16 a[4:7], v[74:77], a[116:119], a[4:7]
	v_mfma_f32_16x16x32_f16 a[0:3], v[74:77], a[120:123], a[0:3]
	v_mfma_f32_16x16x32_f16 a[0:3], v[78:81], a[120:123], a[0:3]
	v_mfma_f32_16x16x32_f16 a[0:3], v[74:77], a[124:127], a[0:3]
	global_load_dwordx4 a[104:107], v[90:91], off offset:1216
	global_load_dwordx4 a[108:111], v[92:93], off offset:1216
	global_load_dwordx4 a[112:115], v[94:95], off offset:1216
	global_load_dwordx4 a[116:119], v[96:97], off offset:1216
	global_load_dwordx4 a[120:123], v[98:99], off offset:1216
	global_load_dwordx4 a[124:127], v[100:101], off offset:1216
	s_waitcnt vmcnt(54)
	v_accvgpr_read_b32 v0, a48
	v_accvgpr_read_b32 v1, a49
	v_accvgpr_read_b32 v2, a50
	v_accvgpr_read_b32 v3, a51
	v_accvgpr_read_b32 v4, a52
	v_accvgpr_read_b32 v5, a53
	v_accvgpr_read_b32 v6, a54
	v_accvgpr_read_b32 v7, a55
	global_load_dwordx4 a[48:51], v[22:23], off offset:3072
	global_load_dwordx4 a[52:55], v[22:23], off offset:3088
	v_pk_mul_f32 v[0:1], v[28:29], v[0:1]
	v_pk_mul_f32 v[2:3], v[28:29], v[2:3]
	v_pk_mul_f32 v[4:5], v[28:29], v[4:5]
	v_pk_mul_f32 v[6:7], v[28:29], v[6:7]
	s_waitcnt lgkmcnt(0)
; DI f4 mfma16(h8 a, h8 b, f4 c) { return __builtin_amdgcn_mfma_f32_16x16x32_f16(a, b, c, 0, 0, 0); }
; DI void row2_phase(const Params& P, int l, int r_begin, char* smem) {
;     ...
; #pragma unroll 4
;     for (int kk = 0; kk < 32; kk++) {
;       const int k0 = kk * 32;
;       float x[8], g[8], s1[8], s0[8];
;       *(float4*)&x[0] = *(const float4*)(xm + k0); *(float4*)&x[4] = *(const float4*)(xm + k0 + 4);
;       *(float4*)&g[0] = *(const float4*)(gam + fq * 8 + k0); *(float4*)&g[4] = *(const float4*)(gam + fq * 8 + k0 + 4);
;       *(float4*)&s1[0] = *(const float4*)(sc + k0); *(float4*)&s1[4] = *(const float4*)(sc + k0 + 4);
;       *(float4*)&s0[0] = *(const float4*)(sh + k0); *(float4*)&s0[4] = *(const float4*)(sh + k0 + 4);
;       h8 hi, lo;
; #pragma unroll
;       for (int i = 0; i < 8; i++) {
;         float v = x[i] * rstd * g[i] * (1.f + s1[i]) + s0[i];
;         hi[i] = (half_t)v; lo[i] = (half_t)(v - (float)hi[i]);
;       }
;       *(h8*)(hxo + k0) = hi;
; #pragma unroll
;       for (int n3 = 0; n3 < 3; n3++) {
;         h8 bh = *(const h8*)(Whi + (size_t)(n3 * 16 + fr) * 1024 + k0 + fq * 8);
;         h8 bl = *(const h8*)(Wlo + (size_t)(n3 * 16 + fr) * 1024 + k0 + fq * 8);
;         acc[n3] = mfma16(hi, bh, acc[n3]); acc[n3] = mfma16(lo, bh, acc[n3]); acc[n3] = mfma16(hi, bl, acc[n3]);
;       }
;     }
	v_pk_mul_f32 v[0:1], v[0:1], v[32:33]
	v_pk_mul_f32 v[2:3], v[2:3], v[34:35]
	v_pk_mul_f32 v[4:5], v[4:5], v[36:37]
	v_pk_mul_f32 v[6:7], v[6:7], v[38:39]
	v_pk_add_f32 v[40:41], v[40:41], 1.0 op_sel_hi:[1,0]
	v_pk_add_f32 v[42:43], v[42:43], 1.0 op_sel_hi:[1,0]
	v_pk_add_f32 v[44:45], v[44:45], 1.0 op_sel_hi:[1,0]
	v_pk_add_f32 v[46:47], v[46:47], 1.0 op_sel_hi:[1,0]
	v_pk_fma_f32 v[0:1], v[0:1], v[40:41], v[58:59]
	v_pk_fma_f32 v[2:3], v[2:3], v[42:43], v[60:61]
	v_pk_fma_f32 v[4:5], v[4:5], v[44:45], v[62:63]
	v_pk_fma_f32 v[6:7], v[6:7], v[46:47], v[64:65]
	ds_read_b128 v[32:35], v102 offset:1920
	ds_read_b128 v[36:39], v102 offset:1936
	ds_read_b128 v[40:43], v102 offset:6016
	ds_read_b128 v[44:47], v102 offset:6032
	ds_read_b128 v[58:61], v102 offset:10112
	ds_read_b128 v[62:65], v102 offset:10128
	v_cvt_pk_f16_f32 v74, v0, v1
	v_cvt_pk_f16_f32 v75, v2, v3
	v_cvt_pk_f16_f32 v76, v4, v5
	v_cvt_pk_f16_f32 v77, v6, v7
	v_cvt_f32_f16_e32 v66, v74
	v_cvt_f32_f16_sdwa v67, v74 dst_sel:DWORD dst_unused:UNUSED_PAD src0_sel:WORD_1
	v_cvt_f32_f16_e32 v68, v75
	v_cvt_f32_f16_sdwa v69, v75 dst_sel:DWORD dst_unused:UNUSED_PAD src0_sel:WORD_1
	v_cvt_f32_f16_e32 v70, v76
	v_cvt_f32_f16_sdwa v71, v76 dst_sel:DWORD dst_unused:UNUSED_PAD src0_sel:WORD_1
	v_cvt_f32_f16_e32 v72, v77
	v_cvt_f32_f16_sdwa v73, v77 dst_sel:DWORD dst_unused:UNUSED_PAD src0_sel:WORD_1
	v_pk_add_f32 v[0:1], v[0:1], v[66:67] neg_lo:[0,1] neg_hi:[0,1]
	v_pk_add_f32 v[2:3], v[2:3], v[68:69] neg_lo:[0,1] neg_hi:[0,1]
	v_pk_add_f32 v[4:5], v[4:5], v[70:71] neg_lo:[0,1] neg_hi:[0,1]
	v_pk_add_f32 v[6:7], v[6:7], v[72:73] neg_lo:[0,1] neg_hi:[0,1]
	s_nop 0
	v_cvt_pk_f16_f32 v78, v0, v1
	v_cvt_pk_f16_f32 v79, v2, v3
	v_cvt_pk_f16_f32 v80, v4, v5
	v_cvt_pk_f16_f32 v81, v6, v7
	global_store_dwordx4 v[88:89], v[74:77], off offset:896
	s_waitcnt vmcnt(48)
	v_mfma_f32_16x16x32_f16 a[8:11], v[74:77], a[128:131], a[8:11]
	v_mfma_f32_16x16x32_f16 a[8:11], v[78:81], a[128:131], a[8:11]
	v_mfma_f32_16x16x32_f16 a[8:11], v[74:77], a[132:135], a[8:11]
	v_mfma_f32_16x16x32_f16 a[4:7], v[74:77], a[136:139], a[4:7]
	v_mfma_f32_16x16x32_f16 a[4:7], v[78:81], a[136:139], a[4:7]
	v_mfma_f32_16x16x32_f16 a[4:7], v[74:77], a[140:143], a[4:7]
	v_mfma_f32_16x16x32_f16 a[0:3], v[74:77], a[144:147], a[0:3]
	v_mfma_f32_16x16x32_f16 a[0:3], v[78:81], a[144:147], a[0:3]
	v_mfma_f32_16x16x32_f16 a[0:3], v[74:77], a[148:151], a[0:3]
	global_load_dwordx4 a[128:131], v[90:91], off offset:1280
	global_load_dwordx4 a[132:135], v[92:93], off offset:1280
	global_load_dwordx4 a[136:139], v[94:95], off offset:1280
	global_load_dwordx4 a[140:143], v[96:97], off offset:1280
	global_load_dwordx4 a[144:147], v[98:99], off offset:1280
	global_load_dwordx4 a[148:151], v[100:101], off offset:1280
	s_waitcnt vmcnt(54)
	v_accvgpr_read_b32 v0, a56
	v_accvgpr_read_b32 v1, a57
	v_accvgpr_read_b32 v2, a58
	v_accvgpr_read_b32 v3, a59
	v_accvgpr_read_b32 v4, a60
	v_accvgpr_read_b32 v5, a61
	v_accvgpr_read_b32 v6, a62
	v_accvgpr_read_b32 v7, a63
	global_load_dwordx4 a[56:59], v[22:23], off offset:3200
	global_load_dwordx4 a[60:63], v[22:23], off offset:3216
	v_pk_mul_f32 v[0:1], v[28:29], v[0:1]
	v_pk_mul_f32 v[2:3], v[28:29], v[2:3]
	v_pk_mul_f32 v[4:5], v[28:29], v[4:5]
	v_pk_mul_f32 v[6:7], v[28:29], v[6:7]
	s_waitcnt lgkmcnt(0)
	v_pk_mul_f32 v[0:1], v[0:1], v[32:33]
	v_pk_mul_f32 v[2:3], v[2:3], v[34:35]
	v_pk_mul_f32 v[4:5], v[4:5], v[36:37]
	v_pk_mul_f32 v[6:7], v[6:7], v[38:39]
	v_pk_add_f32 v[40:41], v[40:41], 1.0 op_sel_hi:[1,0]
	v_pk_add_f32 v[42:43], v[42:43], 1.0 op_sel_hi:[1,0]
	v_pk_add_f32 v[44:45], v[44:45], 1.0 op_sel_hi:[1,0]
	v_pk_add_f32 v[46:47], v[46:47], 1.0 op_sel_hi:[1,0]
	v_pk_fma_f32 v[0:1], v[0:1], v[40:41], v[58:59]
	v_pk_fma_f32 v[2:3], v[2:3], v[42:43], v[60:61]
	v_pk_fma_f32 v[4:5], v[4:5], v[44:45], v[62:63]
	v_pk_fma_f32 v[6:7], v[6:7], v[46:47], v[64:65]
	ds_read_b128 v[32:35], v102 offset:2048
	ds_read_b128 v[36:39], v102 offset:2064
	ds_read_b128 v[40:43], v102 offset:6144
	ds_read_b128 v[44:47], v102 offset:6160
	ds_read_b128 v[58:61], v102 offset:10240
	ds_read_b128 v[62:65], v102 offset:10256
	v_cvt_pk_f16_f32 v74, v0, v1
	v_cvt_pk_f16_f32 v75, v2, v3
	v_cvt_pk_f16_f32 v76, v4, v5
	v_cvt_pk_f16_f32 v77, v6, v7
	v_cvt_f32_f16_e32 v66, v74
	v_cvt_f32_f16_sdwa v67, v74 dst_sel:DWORD dst_unused:UNUSED_PAD src0_sel:WORD_1
	v_cvt_f32_f16_e32 v68, v75
	v_cvt_f32_f16_sdwa v69, v75 dst_sel:DWORD dst_unused:UNUSED_PAD src0_sel:WORD_1
	v_cvt_f32_f16_e32 v70, v76
	v_cvt_f32_f16_sdwa v71, v76 dst_sel:DWORD dst_unused:UNUSED_PAD src0_sel:WORD_1
	v_cvt_f32_f16_e32 v72, v77
	v_cvt_f32_f16_sdwa v73, v77 dst_sel:DWORD dst_unused:UNUSED_PAD src0_sel:WORD_1
	v_pk_add_f32 v[0:1], v[0:1], v[66:67] neg_lo:[0,1] neg_hi:[0,1]
	v_pk_add_f32 v[2:3], v[2:3], v[68:69] neg_lo:[0,1] neg_hi:[0,1]
	v_pk_add_f32 v[4:5], v[4:5], v[70:71] neg_lo:[0,1] neg_hi:[0,1]
	v_pk_add_f32 v[6:7], v[6:7], v[72:73] neg_lo:[0,1] neg_hi:[0,1]
	s_nop 0
	v_cvt_pk_f16_f32 v78, v0, v1
	v_cvt_pk_f16_f32 v79, v2, v3
	v_cvt_pk_f16_f32 v80, v4, v5
	v_cvt_pk_f16_f32 v81, v6, v7
	global_store_dwordx4 v[88:89], v[74:77], off offset:960
	s_waitcnt vmcnt(48)
	v_mfma_f32_16x16x32_f16 a[8:11], v[74:77], a[152:155], a[8:11]
	v_mfma_f32_16x16x32_f16 a[8:11], v[78:81], a[152:155], a[8:11]
	v_mfma_f32_16x16x32_f16 a[8:11], v[74:77], a[156:159], a[8:11]
	v_mfma_f32_16x16x32_f16 a[4:7], v[74:77], a[160:163], a[4:7]
	v_mfma_f32_16x16x32_f16 a[4:7], v[78:81], a[160:163], a[4:7]
	v_mfma_f32_16x16x32_f16 a[4:7], v[74:77], a[164:167], a[4:7]
	v_mfma_f32_16x16x32_f16 a[0:3], v[74:77], a[168:171], a[0:3]
	v_mfma_f32_16x16x32_f16 a[0:3], v[78:81], a[168:171], a[0:3]
	v_mfma_f32_16x16x32_f16 a[0:3], v[74:77], a[172:175], a[0:3]
	global_load_dwordx4 a[152:155], v[90:91], off offset:1344
	global_load_dwordx4 a[156:159], v[92:93], off offset:1344
	global_load_dwordx4 a[160:163], v[94:95], off offset:1344
	global_load_dwordx4 a[164:167], v[96:97], off offset:1344
	global_load_dwordx4 a[168:171], v[98:99], off offset:1344
	global_load_dwordx4 a[172:175], v[100:101], off offset:1344
	s_waitcnt vmcnt(54)
; DI f4 mfma16(h8 a, h8 b, f4 c) { return __builtin_amdgcn_mfma_f32_16x16x32_f16(a, b, c, 0, 0, 0); }
; DI void row2_phase(const Params& P, int l, int r_begin, char* smem) {
;     ...
; #pragma unroll 4
;     for (int kk = 0; kk < 32; kk++) {
;       const int k0 = kk * 32;
;       float x[8], g[8], s1[8], s0[8];
;       *(float4*)&x[0] = *(const float4*)(xm + k0); *(float4*)&x[4] = *(const float4*)(xm + k0 + 4);
;       *(float4*)&g[0] = *(const float4*)(gam + fq * 8 + k0); *(float4*)&g[4] = *(const float4*)(gam + fq * 8 + k0 + 4);
;       *(float4*)&s1[0] = *(const float4*)(sc + k0); *(float4*)&s1[4] = *(const float4*)(sc + k0 + 4);
;       *(float4*)&s0[0] = *(const float4*)(sh + k0); *(float4*)&s0[4] = *(const float4*)(sh + k0 + 4);
;       h8 hi, lo;
; #pragma unroll
;       for (int i = 0; i < 8; i++) {
;         float v = x[i] * rstd * g[i] * (1.f + s1[i]) + s0[i];
;         hi[i] = (half_t)v; lo[i] = (half_t)(v - (float)hi[i]);
;       }
;       *(h8*)(hxo + k0) = hi;
; #pragma unroll
;       for (int n3 = 0; n3 < 3; n3++) {
;         h8 bh = *(const h8*)(Whi + (size_t)(n3 * 16 + fr) * 1024 + k0 + fq * 8);
;         h8 bl = *(const h8*)(Wlo + (size_t)(n3 * 16 + fr) * 1024 + k0 + fq * 8);
;         acc[n3] = mfma16(hi, bh, acc[n3]); acc[n3] = mfma16(lo, bh, acc[n3]); acc[n3] = mfma16(hi, bl, acc[n3]);
;       }
;     }
	v_accvgpr_read_b32 v0, a64
	v_accvgpr_read_b32 v1, a65
	v_accvgpr_read_b32 v2, a66
	v_accvgpr_read_b32 v3, a67
	v_accvgpr_read_b32 v4, a68
	v_accvgpr_read_b32 v5, a69
	v_accvgpr_read_b32 v6, a70
	v_accvgpr_read_b32 v7, a71
	global_load_dwordx4 a[64:67], v[22:23], off offset:3328
	global_load_dwordx4 a[68:71], v[22:23], off offset:3344
	v_pk_mul_f32 v[0:1], v[28:29], v[0:1]
	v_pk_mul_f32 v[2:3], v[28:29], v[2:3]
	v_pk_mul_f32 v[4:5], v[28:29], v[4:5]
	v_pk_mul_f32 v[6:7], v[28:29], v[6:7]
	s_waitcnt lgkmcnt(0)
	v_pk_mul_f32 v[0:1], v[0:1], v[32:33]
	v_pk_mul_f32 v[2:3], v[2:3], v[34:35]
	v_pk_mul_f32 v[4:5], v[4:5], v[36:37]
	v_pk_mul_f32 v[6:7], v[6:7], v[38:39]
	v_pk_add_f32 v[40:41], v[40:41], 1.0 op_sel_hi:[1,0]
	v_pk_add_f32 v[42:43], v[42:43], 1.0 op_sel_hi:[1,0]
	v_pk_add_f32 v[44:45], v[44:45], 1.0 op_sel_hi:[1,0]
	v_pk_add_f32 v[46:47], v[46:47], 1.0 op_sel_hi:[1,0]
	v_pk_fma_f32 v[0:1], v[0:1], v[40:41], v[58:59]
	v_pk_fma_f32 v[2:3], v[2:3], v[42:43], v[60:61]
	v_pk_fma_f32 v[4:5], v[4:5], v[44:45], v[62:63]
	v_pk_fma_f32 v[6:7], v[6:7], v[46:47], v[64:65]
	ds_read_b128 v[32:35], v102 offset:2176
	ds_read_b128 v[36:39], v102 offset:2192
	ds_read_b128 v[40:43], v102 offset:6272
	ds_read_b128 v[44:47], v102 offset:6288
	ds_read_b128 v[58:61], v102 offset:10368
	ds_read_b128 v[62:65], v102 offset:10384
	v_cvt_pk_f16_f32 v74, v0, v1
	v_cvt_pk_f16_f32 v75, v2, v3
	v_cvt_pk_f16_f32 v76, v4, v5
	v_cvt_pk_f16_f32 v77, v6, v7
	v_cvt_f32_f16_e32 v66, v74
	v_cvt_f32_f16_sdwa v67, v74 dst_sel:DWORD dst_unused:UNUSED_PAD src0_sel:WORD_1
	v_cvt_f32_f16_e32 v68, v75
	v_cvt_f32_f16_sdwa v69, v75 dst_sel:DWORD dst_unused:UNUSED_PAD src0_sel:WORD_1
	v_cvt_f32_f16_e32 v70, v76
	v_cvt_f32_f16_sdwa v71, v76 dst_sel:DWORD dst_unused:UNUSED_PAD src0_sel:WORD_1
	v_cvt_f32_f16_e32 v72, v77
	v_cvt_f32_f16_sdwa v73, v77 dst_sel:DWORD dst_unused:UNUSED_PAD src0_sel:WORD_1
	v_pk_add_f32 v[0:1], v[0:1], v[66:67] neg_lo:[0,1] neg_hi:[0,1]
	v_pk_add_f32 v[2:3], v[2:3], v[68:69] neg_lo:[0,1] neg_hi:[0,1]
	v_pk_add_f32 v[4:5], v[4:5], v[70:71] neg_lo:[0,1] neg_hi:[0,1]
	v_pk_add_f32 v[6:7], v[6:7], v[72:73] neg_lo:[0,1] neg_hi:[0,1]
	s_nop 0
	v_cvt_pk_f16_f32 v78, v0, v1
	v_cvt_pk_f16_f32 v79, v2, v3
	v_cvt_pk_f16_f32 v80, v4, v5
	v_cvt_pk_f16_f32 v81, v6, v7
	global_store_dwordx4 v[88:89], v[74:77], off offset:1024
	s_waitcnt vmcnt(48)
	v_mfma_f32_16x16x32_f16 a[8:11], v[74:77], a[204:207], a[8:11]
	v_mfma_f32_16x16x32_f16 a[8:11], v[78:81], a[204:207], a[8:11]
	v_mfma_f32_16x16x32_f16 a[8:11], v[74:77], a[208:211], a[8:11]
	v_mfma_f32_16x16x32_f16 a[4:7], v[74:77], a[212:215], a[4:7]
	v_mfma_f32_16x16x32_f16 a[4:7], v[78:81], a[212:215], a[4:7]
	v_mfma_f32_16x16x32_f16 a[4:7], v[74:77], a[216:219], a[4:7]
	v_mfma_f32_16x16x32_f16 a[0:3], v[74:77], a[220:223], a[0:3]
	v_mfma_f32_16x16x32_f16 a[0:3], v[78:81], a[220:223], a[0:3]
	v_mfma_f32_16x16x32_f16 a[0:3], v[74:77], a[224:227], a[0:3]
	global_load_dwordx4 a[204:207], v[90:91], off offset:1408
	global_load_dwordx4 a[208:211], v[92:93], off offset:1408
	global_load_dwordx4 a[212:215], v[94:95], off offset:1408
	global_load_dwordx4 a[216:219], v[96:97], off offset:1408
	global_load_dwordx4 a[220:223], v[98:99], off offset:1408
	global_load_dwordx4 a[224:227], v[100:101], off offset:1408
	s_waitcnt vmcnt(54)
	v_accvgpr_read_b32 v0, a72
	v_accvgpr_read_b32 v1, a73
	v_accvgpr_read_b32 v2, a74
	v_accvgpr_read_b32 v3, a75
	v_accvgpr_read_b32 v4, a76
	v_accvgpr_read_b32 v5, a77
	v_accvgpr_read_b32 v6, a78
	v_accvgpr_read_b32 v7, a79
	global_load_dwordx4 a[72:75], v[22:23], off offset:3456
	global_load_dwordx4 a[76:79], v[22:23], off offset:3472
	v_pk_mul_f32 v[0:1], v[28:29], v[0:1]
	v_pk_mul_f32 v[2:3], v[28:29], v[2:3]
	v_pk_mul_f32 v[4:5], v[28:29], v[4:5]
	v_pk_mul_f32 v[6:7], v[28:29], v[6:7]
	s_waitcnt lgkmcnt(0)
	v_pk_mul_f32 v[0:1], v[0:1], v[32:33]
	v_pk_mul_f32 v[2:3], v[2:3], v[34:35]
	v_pk_mul_f32 v[4:5], v[4:5], v[36:37]
	v_pk_mul_f32 v[6:7], v[6:7], v[38:39]
	v_pk_add_f32 v[40:41], v[40:41], 1.0 op_sel_hi:[1,0]
	v_pk_add_f32 v[42:43], v[42:43], 1.0 op_sel_hi:[1,0]
	v_pk_add_f32 v[44:45], v[44:45], 1.0 op_sel_hi:[1,0]
	v_pk_add_f32 v[46:47], v[46:47], 1.0 op_sel_hi:[1,0]
	v_pk_fma_f32 v[0:1], v[0:1], v[40:41], v[58:59]
	v_pk_fma_f32 v[2:3], v[2:3], v[42:43], v[60:61]
	v_pk_fma_f32 v[4:5], v[4:5], v[44:45], v[62:63]
	v_pk_fma_f32 v[6:7], v[6:7], v[46:47], v[64:65]
	ds_read_b128 v[32:35], v102 offset:2304
	ds_read_b128 v[36:39], v102 offset:2320
	ds_read_b128 v[40:43], v102 offset:6400
	ds_read_b128 v[44:47], v102 offset:6416
	ds_read_b128 v[58:61], v102 offset:10496
	ds_read_b128 v[62:65], v102 offset:10512
	v_cvt_pk_f16_f32 v74, v0, v1
	v_cvt_pk_f16_f32 v75, v2, v3
	v_cvt_pk_f16_f32 v76, v4, v5
	v_cvt_pk_f16_f32 v77, v6, v7
	v_cvt_f32_f16_e32 v66, v74
	v_cvt_f32_f16_sdwa v67, v74 dst_sel:DWORD dst_unused:UNUSED_PAD src0_sel:WORD_1
	v_cvt_f32_f16_e32 v68, v75
	v_cvt_f32_f16_sdwa v69, v75 dst_sel:DWORD dst_unused:UNUSED_PAD src0_sel:WORD_1
	v_cvt_f32_f16_e32 v70, v76
	v_cvt_f32_f16_sdwa v71, v76 dst_sel:DWORD dst_unused:UNUSED_PAD src0_sel:WORD_1
	v_cvt_f32_f16_e32 v72, v77
	v_cvt_f32_f16_sdwa v73, v77 dst_sel:DWORD dst_unused:UNUSED_PAD src0_sel:WORD_1
	v_pk_add_f32 v[0:1], v[0:1], v[66:67] neg_lo:[0,1] neg_hi:[0,1]
	v_pk_add_f32 v[2:3], v[2:3], v[68:69] neg_lo:[0,1] neg_hi:[0,1]
	v_pk_add_f32 v[4:5], v[4:5], v[70:71] neg_lo:[0,1] neg_hi:[0,1]
	v_pk_add_f32 v[6:7], v[6:7], v[72:73] neg_lo:[0,1] neg_hi:[0,1]
	s_nop 0
	v_cvt_pk_f16_f32 v78, v0, v1
	v_cvt_pk_f16_f32 v79, v2, v3
	v_cvt_pk_f16_f32 v80, v4, v5
	v_cvt_pk_f16_f32 v81, v6, v7
	global_store_dwordx4 v[88:89], v[74:77], off offset:1088
	s_waitcnt vmcnt(48)
; DI f4 mfma16(h8 a, h8 b, f4 c) { return __builtin_amdgcn_mfma_f32_16x16x32_f16(a, b, c, 0, 0, 0); }
; DI void row2_phase(const Params& P, int l, int r_begin, char* smem) {
;     ...
; #pragma unroll 4
;     for (int kk = 0; kk < 32; kk++) {
;       const int k0 = kk * 32;
;       float x[8], g[8], s1[8], s0[8];
;       *(float4*)&x[0] = *(const float4*)(xm + k0); *(float4*)&x[4] = *(const float4*)(xm + k0 + 4);
;       *(float4*)&g[0] = *(const float4*)(gam + fq * 8 + k0); *(float4*)&g[4] = *(const float4*)(gam + fq * 8 + k0 + 4);
;       *(float4*)&s1[0] = *(const float4*)(sc + k0); *(float4*)&s1[4] = *(const float4*)(sc + k0 + 4);
;       *(float4*)&s0[0] = *(const float4*)(sh + k0); *(float4*)&s0[4] = *(const float4*)(sh + k0 + 4);
;       h8 hi, lo;
; #pragma unroll
;       for (int i = 0; i < 8; i++) {
;         float v = x[i] * rstd * g[i] * (1.f + s1[i]) + s0[i];
;         hi[i] = (half_t)v; lo[i] = (half_t)(v - (float)hi[i]);
;       }
;       *(h8*)(hxo + k0) = hi;
; #pragma unroll
;       for (int n3 = 0; n3 < 3; n3++) {
;         h8 bh = *(const h8*)(Whi + (size_t)(n3 * 16 + fr) * 1024 + k0 + fq * 8);
;         h8 bl = *(const h8*)(Wlo + (size_t)(n3 * 16 + fr) * 1024 + k0 + fq * 8);
;         acc[n3] = mfma16(hi, bh, acc[n3]); acc[n3] = mfma16(lo, bh, acc[n3]); acc[n3] = mfma16(hi, bl, acc[n3]);
;       }
;     }
	v_mfma_f32_16x16x32_f16 a[8:11], v[74:77], a[228:231], a[8:11]
	v_mfma_f32_16x16x32_f16 a[8:11], v[78:81], a[228:231], a[8:11]
	v_mfma_f32_16x16x32_f16 a[8:11], v[74:77], a[232:235], a[8:11]
	v_mfma_f32_16x16x32_f16 a[4:7], v[74:77], a[236:239], a[4:7]
	v_mfma_f32_16x16x32_f16 a[4:7], v[78:81], a[236:239], a[4:7]
	v_mfma_f32_16x16x32_f16 a[4:7], v[74:77], a[240:243], a[4:7]
	v_mfma_f32_16x16x32_f16 a[0:3], v[74:77], a[244:247], a[0:3]
	v_mfma_f32_16x16x32_f16 a[0:3], v[78:81], a[244:247], a[0:3]
	v_mfma_f32_16x16x32_f16 a[0:3], v[74:77], a[248:251], a[0:3]
	global_load_dwordx4 a[228:231], v[90:91], off offset:1472
	global_load_dwordx4 a[232:235], v[92:93], off offset:1472
	global_load_dwordx4 a[236:239], v[94:95], off offset:1472
	global_load_dwordx4 a[240:243], v[96:97], off offset:1472
	global_load_dwordx4 a[244:247], v[98:99], off offset:1472
	global_load_dwordx4 a[248:251], v[100:101], off offset:1472
	s_waitcnt vmcnt(54)
	v_accvgpr_read_b32 v0, a180
	v_accvgpr_read_b32 v1, a181
	v_accvgpr_read_b32 v2, a182
	v_accvgpr_read_b32 v3, a183
	v_accvgpr_read_b32 v4, a184
	v_accvgpr_read_b32 v5, a185
	v_accvgpr_read_b32 v6, a186
	v_accvgpr_read_b32 v7, a187
	global_load_dwordx4 a[180:183], v[22:23], off offset:3584
	global_load_dwordx4 a[184:187], v[22:23], off offset:3600
	v_pk_mul_f32 v[0:1], v[28:29], v[0:1]
	v_pk_mul_f32 v[2:3], v[28:29], v[2:3]
	v_pk_mul_f32 v[4:5], v[28:29], v[4:5]
	v_pk_mul_f32 v[6:7], v[28:29], v[6:7]
	s_waitcnt lgkmcnt(0)
	v_pk_mul_f32 v[0:1], v[0:1], v[32:33]
	v_pk_mul_f32 v[2:3], v[2:3], v[34:35]
	v_pk_mul_f32 v[4:5], v[4:5], v[36:37]
	v_pk_mul_f32 v[6:7], v[6:7], v[38:39]
	v_pk_add_f32 v[40:41], v[40:41], 1.0 op_sel_hi:[1,0]
	v_pk_add_f32 v[42:43], v[42:43], 1.0 op_sel_hi:[1,0]
	v_pk_add_f32 v[44:45], v[44:45], 1.0 op_sel_hi:[1,0]
	v_pk_add_f32 v[46:47], v[46:47], 1.0 op_sel_hi:[1,0]
	v_pk_fma_f32 v[0:1], v[0:1], v[40:41], v[58:59]
	v_pk_fma_f32 v[2:3], v[2:3], v[42:43], v[60:61]
	v_pk_fma_f32 v[4:5], v[4:5], v[44:45], v[62:63]
	v_pk_fma_f32 v[6:7], v[6:7], v[46:47], v[64:65]
	ds_read_b128 v[32:35], v102 offset:2432
	ds_read_b128 v[36:39], v102 offset:2448
	ds_read_b128 v[40:43], v102 offset:6528
	ds_read_b128 v[44:47], v102 offset:6544
	ds_read_b128 v[58:61], v102 offset:10624
	ds_read_b128 v[62:65], v102 offset:10640
	v_cvt_pk_f16_f32 v74, v0, v1
	v_cvt_pk_f16_f32 v75, v2, v3
	v_cvt_pk_f16_f32 v76, v4, v5
	v_cvt_pk_f16_f32 v77, v6, v7
	v_cvt_f32_f16_e32 v66, v74
	v_cvt_f32_f16_sdwa v67, v74 dst_sel:DWORD dst_unused:UNUSED_PAD src0_sel:WORD_1
	v_cvt_f32_f16_e32 v68, v75
	v_cvt_f32_f16_sdwa v69, v75 dst_sel:DWORD dst_unused:UNUSED_PAD src0_sel:WORD_1
	v_cvt_f32_f16_e32 v70, v76
	v_cvt_f32_f16_sdwa v71, v76 dst_sel:DWORD dst_unused:UNUSED_PAD src0_sel:WORD_1
	v_cvt_f32_f16_e32 v72, v77
	v_cvt_f32_f16_sdwa v73, v77 dst_sel:DWORD dst_unused:UNUSED_PAD src0_sel:WORD_1
	v_pk_add_f32 v[0:1], v[0:1], v[66:67] neg_lo:[0,1] neg_hi:[0,1]
	v_pk_add_f32 v[2:3], v[2:3], v[68:69] neg_lo:[0,1] neg_hi:[0,1]
	v_pk_add_f32 v[4:5], v[4:5], v[70:71] neg_lo:[0,1] neg_hi:[0,1]
	v_pk_add_f32 v[6:7], v[6:7], v[72:73] neg_lo:[0,1] neg_hi:[0,1]
	s_nop 0
	v_cvt_pk_f16_f32 v78, v0, v1
	v_cvt_pk_f16_f32 v79, v2, v3
	v_cvt_pk_f16_f32 v80, v4, v5
	v_cvt_pk_f16_f32 v81, v6, v7
	global_store_dwordx4 v[88:89], v[74:77], off offset:1152
	s_waitcnt vmcnt(48)
	v_mfma_f32_16x16x32_f16 a[8:11], v[74:77], a[80:83], a[8:11]
	v_mfma_f32_16x16x32_f16 a[8:11], v[78:81], a[80:83], a[8:11]
	v_mfma_f32_16x16x32_f16 a[8:11], v[74:77], a[84:87], a[8:11]
	v_mfma_f32_16x16x32_f16 a[4:7], v[74:77], a[88:91], a[4:7]
	v_mfma_f32_16x16x32_f16 a[4:7], v[78:81], a[88:91], a[4:7]
	v_mfma_f32_16x16x32_f16 a[4:7], v[74:77], a[92:95], a[4:7]
	v_mfma_f32_16x16x32_f16 a[0:3], v[74:77], a[96:99], a[0:3]
	v_mfma_f32_16x16x32_f16 a[0:3], v[78:81], a[96:99], a[0:3]
	v_mfma_f32_16x16x32_f16 a[0:3], v[74:77], a[100:103], a[0:3]
	global_load_dwordx4 a[80:83], v[90:91], off offset:1536
	global_load_dwordx4 a[84:87], v[92:93], off offset:1536
	global_load_dwordx4 a[88:91], v[94:95], off offset:1536
	global_load_dwordx4 a[92:95], v[96:97], off offset:1536
	global_load_dwordx4 a[96:99], v[98:99], off offset:1536
	global_load_dwordx4 a[100:103], v[100:101], off offset:1536
	s_waitcnt vmcnt(54)
	v_accvgpr_read_b32 v0, a196
	v_accvgpr_read_b32 v1, a197
	v_accvgpr_read_b32 v2, a198
	v_accvgpr_read_b32 v3, a199
	v_accvgpr_read_b32 v4, a200
	v_accvgpr_read_b32 v5, a201
	v_accvgpr_read_b32 v6, a202
	v_accvgpr_read_b32 v7, a203
	global_load_dwordx4 a[196:199], v[22:23], off offset:3712
	global_load_dwordx4 a[200:203], v[22:23], off offset:3728
	v_pk_mul_f32 v[0:1], v[28:29], v[0:1]
	v_pk_mul_f32 v[2:3], v[28:29], v[2:3]
	v_pk_mul_f32 v[4:5], v[28:29], v[4:5]
	v_pk_mul_f32 v[6:7], v[28:29], v[6:7]
	s_waitcnt lgkmcnt(0)
; DI f4 mfma16(h8 a, h8 b, f4 c) { return __builtin_amdgcn_mfma_f32_16x16x32_f16(a, b, c, 0, 0, 0); }
; DI void row2_phase(const Params& P, int l, int r_begin, char* smem) {
;     ...
; #pragma unroll 4
;     for (int kk = 0; kk < 32; kk++) {
;       const int k0 = kk * 32;
;       float x[8], g[8], s1[8], s0[8];
;       *(float4*)&x[0] = *(const float4*)(xm + k0); *(float4*)&x[4] = *(const float4*)(xm + k0 + 4);
;       *(float4*)&g[0] = *(const float4*)(gam + fq * 8 + k0); *(float4*)&g[4] = *(const float4*)(gam + fq * 8 + k0 + 4);
;       *(float4*)&s1[0] = *(const float4*)(sc + k0); *(float4*)&s1[4] = *(const float4*)(sc + k0 + 4);
;       *(float4*)&s0[0] = *(const float4*)(sh + k0); *(float4*)&s0[4] = *(const float4*)(sh + k0 + 4);
;       h8 hi, lo;
; #pragma unroll
;       for (int i = 0; i < 8; i++) {
;         float v = x[i] * rstd * g[i] * (1.f + s1[i]) + s0[i];
;         hi[i] = (half_t)v; lo[i] = (half_t)(v - (float)hi[i]);
;       }
;       *(h8*)(hxo + k0) = hi;
; #pragma unroll
;       for (int n3 = 0; n3 < 3; n3++) {
;         h8 bh = *(const h8*)(Whi + (size_t)(n3 * 16 + fr) * 1024 + k0 + fq * 8);
;         h8 bl = *(const h8*)(Wlo + (size_t)(n3 * 16 + fr) * 1024 + k0 + fq * 8);
;         acc[n3] = mfma16(hi, bh, acc[n3]); acc[n3] = mfma16(lo, bh, acc[n3]); acc[n3] = mfma16(hi, bl, acc[n3]);
;       }
;     }
	v_pk_mul_f32 v[0:1], v[0:1], v[32:33]
	v_pk_mul_f32 v[2:3], v[2:3], v[34:35]
	v_pk_mul_f32 v[4:5], v[4:5], v[36:37]
	v_pk_mul_f32 v[6:7], v[6:7], v[38:39]
	v_pk_add_f32 v[40:41], v[40:41], 1.0 op_sel_hi:[1,0]
	v_pk_add_f32 v[42:43], v[42:43], 1.0 op_sel_hi:[1,0]
	v_pk_add_f32 v[44:45], v[44:45], 1.0 op_sel_hi:[1,0]
	v_pk_add_f32 v[46:47], v[46:47], 1.0 op_sel_hi:[1,0]
	v_pk_fma_f32 v[0:1], v[0:1], v[40:41], v[58:59]
	v_pk_fma_f32 v[2:3], v[2:3], v[42:43], v[60:61]
	v_pk_fma_f32 v[4:5], v[4:5], v[44:45], v[62:63]
	v_pk_fma_f32 v[6:7], v[6:7], v[46:47], v[64:65]
	ds_read_b128 v[32:35], v102 offset:2560
	ds_read_b128 v[36:39], v102 offset:2576
	ds_read_b128 v[40:43], v102 offset:6656
	ds_read_b128 v[44:47], v102 offset:6672
	ds_read_b128 v[58:61], v102 offset:10752
	ds_read_b128 v[62:65], v102 offset:10768
	v_cvt_pk_f16_f32 v74, v0, v1
	v_cvt_pk_f16_f32 v75, v2, v3
	v_cvt_pk_f16_f32 v76, v4, v5
	v_cvt_pk_f16_f32 v77, v6, v7
	v_cvt_f32_f16_e32 v66, v74
	v_cvt_f32_f16_sdwa v67, v74 dst_sel:DWORD dst_unused:UNUSED_PAD src0_sel:WORD_1
	v_cvt_f32_f16_e32 v68, v75
	v_cvt_f32_f16_sdwa v69, v75 dst_sel:DWORD dst_unused:UNUSED_PAD src0_sel:WORD_1
	v_cvt_f32_f16_e32 v70, v76
	v_cvt_f32_f16_sdwa v71, v76 dst_sel:DWORD dst_unused:UNUSED_PAD src0_sel:WORD_1
	v_cvt_f32_f16_e32 v72, v77
	v_cvt_f32_f16_sdwa v73, v77 dst_sel:DWORD dst_unused:UNUSED_PAD src0_sel:WORD_1
	v_pk_add_f32 v[0:1], v[0:1], v[66:67] neg_lo:[0,1] neg_hi:[0,1]
	v_pk_add_f32 v[2:3], v[2:3], v[68:69] neg_lo:[0,1] neg_hi:[0,1]
	v_pk_add_f32 v[4:5], v[4:5], v[70:71] neg_lo:[0,1] neg_hi:[0,1]
	v_pk_add_f32 v[6:7], v[6:7], v[72:73] neg_lo:[0,1] neg_hi:[0,1]
	s_nop 0
	v_cvt_pk_f16_f32 v78, v0, v1
	v_cvt_pk_f16_f32 v79, v2, v3
	v_cvt_pk_f16_f32 v80, v4, v5
	v_cvt_pk_f16_f32 v81, v6, v7
	global_store_dwordx4 v[88:89], v[74:77], off offset:1216
	s_waitcnt vmcnt(48)
	v_mfma_f32_16x16x32_f16 a[8:11], v[74:77], a[104:107], a[8:11]
	v_mfma_f32_16x16x32_f16 a[8:11], v[78:81], a[104:107], a[8:11]
	v_mfma_f32_16x16x32_f16 a[8:11], v[74:77], a[108:111], a[8:11]
	v_mfma_f32_16x16x32_f16 a[4:7], v[74:77], a[112:115], a[4:7]
	v_mfma_f32_16x16x32_f16 a[4:7], v[78:81], a[112:115], a[4:7]
	v_mfma_f32_16x16x32_f16 a[4:7], v[74:77], a[116:119], a[4:7]
	v_mfma_f32_16x16x32_f16 a[0:3], v[74:77], a[120:123], a[0:3]
	v_mfma_f32_16x16x32_f16 a[0:3], v[78:81], a[120:123], a[0:3]
	v_mfma_f32_16x16x32_f16 a[0:3], v[74:77], a[124:127], a[0:3]
	global_load_dwordx4 a[104:107], v[90:91], off offset:1600
	global_load_dwordx4 a[108:111], v[92:93], off offset:1600
	global_load_dwordx4 a[112:115], v[94:95], off offset:1600
	global_load_dwordx4 a[116:119], v[96:97], off offset:1600
	global_load_dwordx4 a[120:123], v[98:99], off offset:1600
	global_load_dwordx4 a[124:127], v[100:101], off offset:1600
	s_waitcnt vmcnt(54)
	v_accvgpr_read_b32 v0, a16
	v_accvgpr_read_b32 v1, a17
	v_accvgpr_read_b32 v2, a18
	v_accvgpr_read_b32 v3, a19
	v_accvgpr_read_b32 v4, a20
	v_accvgpr_read_b32 v5, a21
	v_accvgpr_read_b32 v6, a22
	v_accvgpr_read_b32 v7, a23
	global_load_dwordx4 a[16:19], v[22:23], off offset:3840
	global_load_dwordx4 a[20:23], v[22:23], off offset:3856
	v_pk_mul_f32 v[0:1], v[28:29], v[0:1]
	v_pk_mul_f32 v[2:3], v[28:29], v[2:3]
	v_pk_mul_f32 v[4:5], v[28:29], v[4:5]
	v_pk_mul_f32 v[6:7], v[28:29], v[6:7]
	s_waitcnt lgkmcnt(0)
	v_pk_mul_f32 v[0:1], v[0:1], v[32:33]
	v_pk_mul_f32 v[2:3], v[2:3], v[34:35]
	v_pk_mul_f32 v[4:5], v[4:5], v[36:37]
	v_pk_mul_f32 v[6:7], v[6:7], v[38:39]
	v_pk_add_f32 v[40:41], v[40:41], 1.0 op_sel_hi:[1,0]
	v_pk_add_f32 v[42:43], v[42:43], 1.0 op_sel_hi:[1,0]
	v_pk_add_f32 v[44:45], v[44:45], 1.0 op_sel_hi:[1,0]
	v_pk_add_f32 v[46:47], v[46:47], 1.0 op_sel_hi:[1,0]
	v_pk_fma_f32 v[0:1], v[0:1], v[40:41], v[58:59]
	v_pk_fma_f32 v[2:3], v[2:3], v[42:43], v[60:61]
	v_pk_fma_f32 v[4:5], v[4:5], v[44:45], v[62:63]
	v_pk_fma_f32 v[6:7], v[6:7], v[46:47], v[64:65]
	ds_read_b128 v[32:35], v102 offset:2688
	ds_read_b128 v[36:39], v102 offset:2704
	ds_read_b128 v[40:43], v102 offset:6784
	ds_read_b128 v[44:47], v102 offset:6800
	ds_read_b128 v[58:61], v102 offset:10880
	ds_read_b128 v[62:65], v102 offset:10896
	v_cvt_pk_f16_f32 v74, v0, v1
	v_cvt_pk_f16_f32 v75, v2, v3
	v_cvt_pk_f16_f32 v76, v4, v5
	v_cvt_pk_f16_f32 v77, v6, v7
	v_cvt_f32_f16_e32 v66, v74
	v_cvt_f32_f16_sdwa v67, v74 dst_sel:DWORD dst_unused:UNUSED_PAD src0_sel:WORD_1
	v_cvt_f32_f16_e32 v68, v75
	v_cvt_f32_f16_sdwa v69, v75 dst_sel:DWORD dst_unused:UNUSED_PAD src0_sel:WORD_1
	v_cvt_f32_f16_e32 v70, v76
	v_cvt_f32_f16_sdwa v71, v76 dst_sel:DWORD dst_unused:UNUSED_PAD src0_sel:WORD_1
	v_cvt_f32_f16_e32 v72, v77
	v_cvt_f32_f16_sdwa v73, v77 dst_sel:DWORD dst_unused:UNUSED_PAD src0_sel:WORD_1
	v_pk_add_f32 v[0:1], v[0:1], v[66:67] neg_lo:[0,1] neg_hi:[0,1]
	v_pk_add_f32 v[2:3], v[2:3], v[68:69] neg_lo:[0,1] neg_hi:[0,1]
	v_pk_add_f32 v[4:5], v[4:5], v[70:71] neg_lo:[0,1] neg_hi:[0,1]
	v_pk_add_f32 v[6:7], v[6:7], v[72:73] neg_lo:[0,1] neg_hi:[0,1]
	s_nop 0
	v_cvt_pk_f16_f32 v78, v0, v1
	v_cvt_pk_f16_f32 v79, v2, v3
	v_cvt_pk_f16_f32 v80, v4, v5
	v_cvt_pk_f16_f32 v81, v6, v7
	global_store_dwordx4 v[88:89], v[74:77], off offset:1280
	s_waitcnt vmcnt(48)
	v_mfma_f32_16x16x32_f16 a[8:11], v[74:77], a[128:131], a[8:11]
	v_mfma_f32_16x16x32_f16 a[8:11], v[78:81], a[128:131], a[8:11]
	v_mfma_f32_16x16x32_f16 a[8:11], v[74:77], a[132:135], a[8:11]
	v_mfma_f32_16x16x32_f16 a[4:7], v[74:77], a[136:139], a[4:7]
	v_mfma_f32_16x16x32_f16 a[4:7], v[78:81], a[136:139], a[4:7]
	v_mfma_f32_16x16x32_f16 a[4:7], v[74:77], a[140:143], a[4:7]
	v_mfma_f32_16x16x32_f16 a[0:3], v[74:77], a[144:147], a[0:3]
	v_mfma_f32_16x16x32_f16 a[0:3], v[78:81], a[144:147], a[0:3]
	v_mfma_f32_16x16x32_f16 a[0:3], v[74:77], a[148:151], a[0:3]
	global_load_dwordx4 a[128:131], v[90:91], off offset:1664
	global_load_dwordx4 a[132:135], v[92:93], off offset:1664
	global_load_dwordx4 a[136:139], v[94:95], off offset:1664
	global_load_dwordx4 a[140:143], v[96:97], off offset:1664
	global_load_dwordx4 a[144:147], v[98:99], off offset:1664
	global_load_dwordx4 a[148:151], v[100:101], off offset:1664
	s_waitcnt vmcnt(54)
; DI f4 mfma16(h8 a, h8 b, f4 c) { return __builtin_amdgcn_mfma_f32_16x16x32_f16(a, b, c, 0, 0, 0); }
; DI void row2_phase(const Params& P, int l, int r_begin, char* smem) {
;     ...
; #pragma unroll 4
;     for (int kk = 0; kk < 32; kk++) {
;       const int k0 = kk * 32;
;       float x[8], g[8], s1[8], s0[8];
;       *(float4*)&x[0] = *(const float4*)(xm + k0); *(float4*)&x[4] = *(const float4*)(xm + k0 + 4);
;       *(float4*)&g[0] = *(const float4*)(gam + fq * 8 + k0); *(float4*)&g[4] = *(const float4*)(gam + fq * 8 + k0 + 4);
;       *(float4*)&s1[0] = *(const float4*)(sc + k0); *(float4*)&s1[4] = *(const float4*)(sc + k0 + 4);
;       *(float4*)&s0[0] = *(const float4*)(sh + k0); *(float4*)&s0[4] = *(const float4*)(sh + k0 + 4);
;       h8 hi, lo;
; #pragma unroll
;       for (int i = 0; i < 8; i++) {
;         float v = x[i] * rstd * g[i] * (1.f + s1[i]) + s0[i];
;         hi[i] = (half_t)v; lo[i] = (half_t)(v - (float)hi[i]);
;       }
;       *(h8*)(hxo + k0) = hi;
; #pragma unroll
;       for (int n3 = 0; n3 < 3; n3++) {
;         h8 bh = *(const h8*)(Whi + (size_t)(n3 * 16 + fr) * 1024 + k0 + fq * 8);
;         h8 bl = *(const h8*)(Wlo + (size_t)(n3 * 16 + fr) * 1024 + k0 + fq * 8);
;         acc[n3] = mfma16(hi, bh, acc[n3]); acc[n3] = mfma16(lo, bh, acc[n3]); acc[n3] = mfma16(hi, bl, acc[n3]);
;       }
;     }
	v_accvgpr_read_b32 v0, a24
	v_accvgpr_read_b32 v1, a25
	v_accvgpr_read_b32 v2, a26
	v_accvgpr_read_b32 v3, a27
	v_accvgpr_read_b32 v4, a28
	v_accvgpr_read_b32 v5, a29
	v_accvgpr_read_b32 v6, a30
	v_accvgpr_read_b32 v7, a31
	global_load_dwordx4 a[24:27], v[22:23], off offset:3968
	global_load_dwordx4 a[28:31], v[22:23], off offset:3984
	v_pk_mul_f32 v[0:1], v[28:29], v[0:1]
	v_pk_mul_f32 v[2:3], v[28:29], v[2:3]
	v_pk_mul_f32 v[4:5], v[28:29], v[4:5]
	v_pk_mul_f32 v[6:7], v[28:29], v[6:7]
	s_waitcnt lgkmcnt(0)
	v_pk_mul_f32 v[0:1], v[0:1], v[32:33]
	v_pk_mul_f32 v[2:3], v[2:3], v[34:35]
	v_pk_mul_f32 v[4:5], v[4:5], v[36:37]
	v_pk_mul_f32 v[6:7], v[6:7], v[38:39]
	v_pk_add_f32 v[40:41], v[40:41], 1.0 op_sel_hi:[1,0]
	v_pk_add_f32 v[42:43], v[42:43], 1.0 op_sel_hi:[1,0]
	v_pk_add_f32 v[44:45], v[44:45], 1.0 op_sel_hi:[1,0]
	v_pk_add_f32 v[46:47], v[46:47], 1.0 op_sel_hi:[1,0]
	v_pk_fma_f32 v[0:1], v[0:1], v[40:41], v[58:59]
	v_pk_fma_f32 v[2:3], v[2:3], v[42:43], v[60:61]
	v_pk_fma_f32 v[4:5], v[4:5], v[44:45], v[62:63]
	v_pk_fma_f32 v[6:7], v[6:7], v[46:47], v[64:65]
	ds_read_b128 v[32:35], v102 offset:2816
	ds_read_b128 v[36:39], v102 offset:2832
	ds_read_b128 v[40:43], v102 offset:6912
	ds_read_b128 v[44:47], v102 offset:6928
	ds_read_b128 v[58:61], v102 offset:11008
	ds_read_b128 v[62:65], v102 offset:11024
	v_cvt_pk_f16_f32 v74, v0, v1
	v_cvt_pk_f16_f32 v75, v2, v3
	v_cvt_pk_f16_f32 v76, v4, v5
	v_cvt_pk_f16_f32 v77, v6, v7
	v_cvt_f32_f16_e32 v66, v74
	v_cvt_f32_f16_sdwa v67, v74 dst_sel:DWORD dst_unused:UNUSED_PAD src0_sel:WORD_1
	v_cvt_f32_f16_e32 v68, v75
	v_cvt_f32_f16_sdwa v69, v75 dst_sel:DWORD dst_unused:UNUSED_PAD src0_sel:WORD_1
	v_cvt_f32_f16_e32 v70, v76
	v_cvt_f32_f16_sdwa v71, v76 dst_sel:DWORD dst_unused:UNUSED_PAD src0_sel:WORD_1
	v_cvt_f32_f16_e32 v72, v77
	v_cvt_f32_f16_sdwa v73, v77 dst_sel:DWORD dst_unused:UNUSED_PAD src0_sel:WORD_1
	v_pk_add_f32 v[0:1], v[0:1], v[66:67] neg_lo:[0,1] neg_hi:[0,1]
	v_pk_add_f32 v[2:3], v[2:3], v[68:69] neg_lo:[0,1] neg_hi:[0,1]
	v_pk_add_f32 v[4:5], v[4:5], v[70:71] neg_lo:[0,1] neg_hi:[0,1]
	v_pk_add_f32 v[6:7], v[6:7], v[72:73] neg_lo:[0,1] neg_hi:[0,1]
	s_nop 0
	v_cvt_pk_f16_f32 v78, v0, v1
	v_cvt_pk_f16_f32 v79, v2, v3
	v_cvt_pk_f16_f32 v80, v4, v5
	v_cvt_pk_f16_f32 v81, v6, v7
	global_store_dwordx4 v[88:89], v[74:77], off offset:1344
	s_waitcnt vmcnt(48)
	v_mfma_f32_16x16x32_f16 a[8:11], v[74:77], a[152:155], a[8:11]
	v_mfma_f32_16x16x32_f16 a[8:11], v[78:81], a[152:155], a[8:11]
	v_mfma_f32_16x16x32_f16 a[8:11], v[74:77], a[156:159], a[8:11]
	v_mfma_f32_16x16x32_f16 a[4:7], v[74:77], a[160:163], a[4:7]
	v_mfma_f32_16x16x32_f16 a[4:7], v[78:81], a[160:163], a[4:7]
	v_mfma_f32_16x16x32_f16 a[4:7], v[74:77], a[164:167], a[4:7]
	v_mfma_f32_16x16x32_f16 a[0:3], v[74:77], a[168:171], a[0:3]
	v_mfma_f32_16x16x32_f16 a[0:3], v[78:81], a[168:171], a[0:3]
	v_mfma_f32_16x16x32_f16 a[0:3], v[74:77], a[172:175], a[0:3]
	global_load_dwordx4 a[152:155], v[90:91], off offset:1728
	global_load_dwordx4 a[156:159], v[92:93], off offset:1728
	global_load_dwordx4 a[160:163], v[94:95], off offset:1728
	global_load_dwordx4 a[164:167], v[96:97], off offset:1728
	global_load_dwordx4 a[168:171], v[98:99], off offset:1728
	global_load_dwordx4 a[172:175], v[100:101], off offset:1728
	s_waitcnt vmcnt(54)
	v_accvgpr_read_b32 v0, a32
	v_accvgpr_read_b32 v1, a33
	v_accvgpr_read_b32 v2, a34
	v_accvgpr_read_b32 v3, a35
	v_accvgpr_read_b32 v4, a36
	v_accvgpr_read_b32 v5, a37
	v_accvgpr_read_b32 v6, a38
	v_accvgpr_read_b32 v7, a39
	v_pk_mul_f32 v[0:1], v[28:29], v[0:1]
	v_pk_mul_f32 v[2:3], v[28:29], v[2:3]
	v_pk_mul_f32 v[4:5], v[28:29], v[4:5]
	v_pk_mul_f32 v[6:7], v[28:29], v[6:7]
	s_waitcnt lgkmcnt(0)
	v_pk_mul_f32 v[0:1], v[0:1], v[32:33]
	v_pk_mul_f32 v[2:3], v[2:3], v[34:35]
	v_pk_mul_f32 v[4:5], v[4:5], v[36:37]
	v_pk_mul_f32 v[6:7], v[6:7], v[38:39]
	v_pk_add_f32 v[40:41], v[40:41], 1.0 op_sel_hi:[1,0]
	v_pk_add_f32 v[42:43], v[42:43], 1.0 op_sel_hi:[1,0]
	v_pk_add_f32 v[44:45], v[44:45], 1.0 op_sel_hi:[1,0]
	v_pk_add_f32 v[46:47], v[46:47], 1.0 op_sel_hi:[1,0]
	v_pk_fma_f32 v[0:1], v[0:1], v[40:41], v[58:59]
	v_pk_fma_f32 v[2:3], v[2:3], v[42:43], v[60:61]
	v_pk_fma_f32 v[4:5], v[4:5], v[44:45], v[62:63]
	v_pk_fma_f32 v[6:7], v[6:7], v[46:47], v[64:65]
	ds_read_b128 v[32:35], v102 offset:2944
	ds_read_b128 v[36:39], v102 offset:2960
	ds_read_b128 v[40:43], v102 offset:7040
	ds_read_b128 v[44:47], v102 offset:7056
	ds_read_b128 v[58:61], v102 offset:11136
	ds_read_b128 v[62:65], v102 offset:11152
	v_cvt_pk_f16_f32 v74, v0, v1
	v_cvt_pk_f16_f32 v75, v2, v3
	v_cvt_pk_f16_f32 v76, v4, v5
	v_cvt_pk_f16_f32 v77, v6, v7
	v_cvt_f32_f16_e32 v66, v74
	v_cvt_f32_f16_sdwa v67, v74 dst_sel:DWORD dst_unused:UNUSED_PAD src0_sel:WORD_1
	v_cvt_f32_f16_e32 v68, v75
	v_cvt_f32_f16_sdwa v69, v75 dst_sel:DWORD dst_unused:UNUSED_PAD src0_sel:WORD_1
	v_cvt_f32_f16_e32 v70, v76
	v_cvt_f32_f16_sdwa v71, v76 dst_sel:DWORD dst_unused:UNUSED_PAD src0_sel:WORD_1
	v_cvt_f32_f16_e32 v72, v77
	v_cvt_f32_f16_sdwa v73, v77 dst_sel:DWORD dst_unused:UNUSED_PAD src0_sel:WORD_1
	v_pk_add_f32 v[0:1], v[0:1], v[66:67] neg_lo:[0,1] neg_hi:[0,1]
	v_pk_add_f32 v[2:3], v[2:3], v[68:69] neg_lo:[0,1] neg_hi:[0,1]
	v_pk_add_f32 v[4:5], v[4:5], v[70:71] neg_lo:[0,1] neg_hi:[0,1]
	v_pk_add_f32 v[6:7], v[6:7], v[72:73] neg_lo:[0,1] neg_hi:[0,1]
	s_nop 0
	v_cvt_pk_f16_f32 v78, v0, v1
	v_cvt_pk_f16_f32 v79, v2, v3
	v_cvt_pk_f16_f32 v80, v4, v5
	v_cvt_pk_f16_f32 v81, v6, v7
	global_store_dwordx4 v[88:89], v[74:77], off offset:1408
	s_waitcnt vmcnt(46)
; DI f4 mfma16(h8 a, h8 b, f4 c) { return __builtin_amdgcn_mfma_f32_16x16x32_f16(a, b, c, 0, 0, 0); }
; DI void row2_phase(const Params& P, int l, int r_begin, char* smem) {
;     ...
; #pragma unroll 4
;     for (int kk = 0; kk < 32; kk++) {
;       const int k0 = kk * 32;
;       float x[8], g[8], s1[8], s0[8];
;       *(float4*)&x[0] = *(const float4*)(xm + k0); *(float4*)&x[4] = *(const float4*)(xm + k0 + 4);
;       *(float4*)&g[0] = *(const float4*)(gam + fq * 8 + k0); *(float4*)&g[4] = *(const float4*)(gam + fq * 8 + k0 + 4);
;       *(float4*)&s1[0] = *(const float4*)(sc + k0); *(float4*)&s1[4] = *(const float4*)(sc + k0 + 4);
;       *(float4*)&s0[0] = *(const float4*)(sh + k0); *(float4*)&s0[4] = *(const float4*)(sh + k0 + 4);
;       h8 hi, lo;
; #pragma unroll
;       for (int i = 0; i < 8; i++) {
;         float v = x[i] * rstd * g[i] * (1.f + s1[i]) + s0[i];
;         hi[i] = (half_t)v; lo[i] = (half_t)(v - (float)hi[i]);
;       }
;       *(h8*)(hxo + k0) = hi;
; #pragma unroll
;       for (int n3 = 0; n3 < 3; n3++) {
;         h8 bh = *(const h8*)(Whi + (size_t)(n3 * 16 + fr) * 1024 + k0 + fq * 8);
;         h8 bl = *(const h8*)(Wlo + (size_t)(n3 * 16 + fr) * 1024 + k0 + fq * 8);
;         acc[n3] = mfma16(hi, bh, acc[n3]); acc[n3] = mfma16(lo, bh, acc[n3]); acc[n3] = mfma16(hi, bl, acc[n3]);
;       }
;     }
	v_mfma_f32_16x16x32_f16 a[8:11], v[74:77], a[204:207], a[8:11]
	v_mfma_f32_16x16x32_f16 a[8:11], v[78:81], a[204:207], a[8:11]
	v_mfma_f32_16x16x32_f16 a[8:11], v[74:77], a[208:211], a[8:11]
	v_mfma_f32_16x16x32_f16 a[4:7], v[74:77], a[212:215], a[4:7]
	v_mfma_f32_16x16x32_f16 a[4:7], v[78:81], a[212:215], a[4:7]
	v_mfma_f32_16x16x32_f16 a[4:7], v[74:77], a[216:219], a[4:7]
	v_mfma_f32_16x16x32_f16 a[0:3], v[74:77], a[220:223], a[0:3]
	v_mfma_f32_16x16x32_f16 a[0:3], v[78:81], a[220:223], a[0:3]
	v_mfma_f32_16x16x32_f16 a[0:3], v[74:77], a[224:227], a[0:3]
	global_load_dwordx4 a[204:207], v[90:91], off offset:1792
	global_load_dwordx4 a[208:211], v[92:93], off offset:1792
	global_load_dwordx4 a[212:215], v[94:95], off offset:1792
	global_load_dwordx4 a[216:219], v[96:97], off offset:1792
	global_load_dwordx4 a[220:223], v[98:99], off offset:1792
	global_load_dwordx4 a[224:227], v[100:101], off offset:1792
	s_waitcnt vmcnt(52)
	v_accvgpr_read_b32 v0, a40
	v_accvgpr_read_b32 v1, a41
	v_accvgpr_read_b32 v2, a42
	v_accvgpr_read_b32 v3, a43
	v_accvgpr_read_b32 v4, a44
	v_accvgpr_read_b32 v5, a45
	v_accvgpr_read_b32 v6, a46
	v_accvgpr_read_b32 v7, a47
	v_pk_mul_f32 v[0:1], v[28:29], v[0:1]
	v_pk_mul_f32 v[2:3], v[28:29], v[2:3]
	v_pk_mul_f32 v[4:5], v[28:29], v[4:5]
	v_pk_mul_f32 v[6:7], v[28:29], v[6:7]
	s_waitcnt lgkmcnt(0)
	v_pk_mul_f32 v[0:1], v[0:1], v[32:33]
	v_pk_mul_f32 v[2:3], v[2:3], v[34:35]
	v_pk_mul_f32 v[4:5], v[4:5], v[36:37]
	v_pk_mul_f32 v[6:7], v[6:7], v[38:39]
	v_pk_add_f32 v[40:41], v[40:41], 1.0 op_sel_hi:[1,0]
	v_pk_add_f32 v[42:43], v[42:43], 1.0 op_sel_hi:[1,0]
	v_pk_add_f32 v[44:45], v[44:45], 1.0 op_sel_hi:[1,0]
	v_pk_add_f32 v[46:47], v[46:47], 1.0 op_sel_hi:[1,0]
	v_pk_fma_f32 v[0:1], v[0:1], v[40:41], v[58:59]
	v_pk_fma_f32 v[2:3], v[2:3], v[42:43], v[60:61]
	v_pk_fma_f32 v[4:5], v[4:5], v[44:45], v[62:63]
	v_pk_fma_f32 v[6:7], v[6:7], v[46:47], v[64:65]
	ds_read_b128 v[32:35], v102 offset:3072
	ds_read_b128 v[36:39], v102 offset:3088
	ds_read_b128 v[40:43], v102 offset:7168
	ds_read_b128 v[44:47], v102 offset:7184
	ds_read_b128 v[58:61], v102 offset:11264
	ds_read_b128 v[62:65], v102 offset:11280
	v_cvt_pk_f16_f32 v74, v0, v1
	v_cvt_pk_f16_f32 v75, v2, v3
	v_cvt_pk_f16_f32 v76, v4, v5
	v_cvt_pk_f16_f32 v77, v6, v7
	v_cvt_f32_f16_e32 v66, v74
	v_cvt_f32_f16_sdwa v67, v74 dst_sel:DWORD dst_unused:UNUSED_PAD src0_sel:WORD_1
	v_cvt_f32_f16_e32 v68, v75
	v_cvt_f32_f16_sdwa v69, v75 dst_sel:DWORD dst_unused:UNUSED_PAD src0_sel:WORD_1
	v_cvt_f32_f16_e32 v70, v76
	v_cvt_f32_f16_sdwa v71, v76 dst_sel:DWORD dst_unused:UNUSED_PAD src0_sel:WORD_1
	v_cvt_f32_f16_e32 v72, v77
	v_cvt_f32_f16_sdwa v73, v77 dst_sel:DWORD dst_unused:UNUSED_PAD src0_sel:WORD_1
	v_pk_add_f32 v[0:1], v[0:1], v[66:67] neg_lo:[0,1] neg_hi:[0,1]
	v_pk_add_f32 v[2:3], v[2:3], v[68:69] neg_lo:[0,1] neg_hi:[0,1]
	v_pk_add_f32 v[4:5], v[4:5], v[70:71] neg_lo:[0,1] neg_hi:[0,1]
	v_pk_add_f32 v[6:7], v[6:7], v[72:73] neg_lo:[0,1] neg_hi:[0,1]
	s_nop 0
	v_cvt_pk_f16_f32 v78, v0, v1
	v_cvt_pk_f16_f32 v79, v2, v3
	v_cvt_pk_f16_f32 v80, v4, v5
	v_cvt_pk_f16_f32 v81, v6, v7
	global_store_dwordx4 v[88:89], v[74:77], off offset:1472
	s_waitcnt vmcnt(44)
	v_mfma_f32_16x16x32_f16 a[8:11], v[74:77], a[228:231], a[8:11]
	v_mfma_f32_16x16x32_f16 a[8:11], v[78:81], a[228:231], a[8:11]
	v_mfma_f32_16x16x32_f16 a[8:11], v[74:77], a[232:235], a[8:11]
	v_mfma_f32_16x16x32_f16 a[4:7], v[74:77], a[236:239], a[4:7]
	v_mfma_f32_16x16x32_f16 a[4:7], v[78:81], a[236:239], a[4:7]
	v_mfma_f32_16x16x32_f16 a[4:7], v[74:77], a[240:243], a[4:7]
	v_mfma_f32_16x16x32_f16 a[0:3], v[74:77], a[244:247], a[0:3]
	v_mfma_f32_16x16x32_f16 a[0:3], v[78:81], a[244:247], a[0:3]
	v_mfma_f32_16x16x32_f16 a[0:3], v[74:77], a[248:251], a[0:3]
	global_load_dwordx4 a[228:231], v[90:91], off offset:1856
	global_load_dwordx4 a[232:235], v[92:93], off offset:1856
	global_load_dwordx4 a[236:239], v[94:95], off offset:1856
	global_load_dwordx4 a[240:243], v[96:97], off offset:1856
	global_load_dwordx4 a[244:247], v[98:99], off offset:1856
	global_load_dwordx4 a[248:251], v[100:101], off offset:1856
	s_waitcnt vmcnt(50)
	v_accvgpr_read_b32 v0, a48
	v_accvgpr_read_b32 v1, a49
	v_accvgpr_read_b32 v2, a50
	v_accvgpr_read_b32 v3, a51
	v_accvgpr_read_b32 v4, a52
	v_accvgpr_read_b32 v5, a53
	v_accvgpr_read_b32 v6, a54
	v_accvgpr_read_b32 v7, a55
	v_pk_mul_f32 v[0:1], v[28:29], v[0:1]
	v_pk_mul_f32 v[2:3], v[28:29], v[2:3]
	v_pk_mul_f32 v[4:5], v[28:29], v[4:5]
	v_pk_mul_f32 v[6:7], v[28:29], v[6:7]
	s_waitcnt lgkmcnt(0)
	v_pk_mul_f32 v[0:1], v[0:1], v[32:33]
	v_pk_mul_f32 v[2:3], v[2:3], v[34:35]
	v_pk_mul_f32 v[4:5], v[4:5], v[36:37]
	v_pk_mul_f32 v[6:7], v[6:7], v[38:39]
	v_pk_add_f32 v[40:41], v[40:41], 1.0 op_sel_hi:[1,0]
	v_pk_add_f32 v[42:43], v[42:43], 1.0 op_sel_hi:[1,0]
	v_pk_add_f32 v[44:45], v[44:45], 1.0 op_sel_hi:[1,0]
	v_pk_add_f32 v[46:47], v[46:47], 1.0 op_sel_hi:[1,0]
	v_pk_fma_f32 v[0:1], v[0:1], v[40:41], v[58:59]
	v_pk_fma_f32 v[2:3], v[2:3], v[42:43], v[60:61]
	v_pk_fma_f32 v[4:5], v[4:5], v[44:45], v[62:63]
	v_pk_fma_f32 v[6:7], v[6:7], v[46:47], v[64:65]
	ds_read_b128 v[32:35], v102 offset:3200
	ds_read_b128 v[36:39], v102 offset:3216
	ds_read_b128 v[40:43], v102 offset:7296
	ds_read_b128 v[44:47], v102 offset:7312
	ds_read_b128 v[58:61], v102 offset:11392
	ds_read_b128 v[62:65], v102 offset:11408
	v_cvt_pk_f16_f32 v74, v0, v1
	v_cvt_pk_f16_f32 v75, v2, v3
	v_cvt_pk_f16_f32 v76, v4, v5
	v_cvt_pk_f16_f32 v77, v6, v7
	v_cvt_f32_f16_e32 v66, v74
	v_cvt_f32_f16_sdwa v67, v74 dst_sel:DWORD dst_unused:UNUSED_PAD src0_sel:WORD_1
	v_cvt_f32_f16_e32 v68, v75
	v_cvt_f32_f16_sdwa v69, v75 dst_sel:DWORD dst_unused:UNUSED_PAD src0_sel:WORD_1
	v_cvt_f32_f16_e32 v70, v76
	v_cvt_f32_f16_sdwa v71, v76 dst_sel:DWORD dst_unused:UNUSED_PAD src0_sel:WORD_1
	v_cvt_f32_f16_e32 v72, v77
	v_cvt_f32_f16_sdwa v73, v77 dst_sel:DWORD dst_unused:UNUSED_PAD src0_sel:WORD_1
	v_pk_add_f32 v[0:1], v[0:1], v[66:67] neg_lo:[0,1] neg_hi:[0,1]
	v_pk_add_f32 v[2:3], v[2:3], v[68:69] neg_lo:[0,1] neg_hi:[0,1]
	v_pk_add_f32 v[4:5], v[4:5], v[70:71] neg_lo:[0,1] neg_hi:[0,1]
	v_pk_add_f32 v[6:7], v[6:7], v[72:73] neg_lo:[0,1] neg_hi:[0,1]
	s_nop 0
	v_cvt_pk_f16_f32 v78, v0, v1
	v_cvt_pk_f16_f32 v79, v2, v3
	v_cvt_pk_f16_f32 v80, v4, v5
	v_cvt_pk_f16_f32 v81, v6, v7
	global_store_dwordx4 v[88:89], v[74:77], off offset:1536
	s_waitcnt vmcnt(42)
; DI f4 mfma16(h8 a, h8 b, f4 c) { return __builtin_amdgcn_mfma_f32_16x16x32_f16(a, b, c, 0, 0, 0); }
; DI void row2_phase(const Params& P, int l, int r_begin, char* smem) {
;     ...
; #pragma unroll 4
;     for (int kk = 0; kk < 32; kk++) {
;       const int k0 = kk * 32;
;       float x[8], g[8], s1[8], s0[8];
;       *(float4*)&x[0] = *(const float4*)(xm + k0); *(float4*)&x[4] = *(const float4*)(xm + k0 + 4);
;       *(float4*)&g[0] = *(const float4*)(gam + fq * 8 + k0); *(float4*)&g[4] = *(const float4*)(gam + fq * 8 + k0 + 4);
;       *(float4*)&s1[0] = *(const float4*)(sc + k0); *(float4*)&s1[4] = *(const float4*)(sc + k0 + 4);
;       *(float4*)&s0[0] = *(const float4*)(sh + k0); *(float4*)&s0[4] = *(const float4*)(sh + k0 + 4);
;       h8 hi, lo;
; #pragma unroll
;       for (int i = 0; i < 8; i++) {
;         float v = x[i] * rstd * g[i] * (1.f + s1[i]) + s0[i];
;         hi[i] = (half_t)v; lo[i] = (half_t)(v - (float)hi[i]);
;       }
;       *(h8*)(hxo + k0) = hi;
; #pragma unroll
;       for (int n3 = 0; n3 < 3; n3++) {
;         h8 bh = *(const h8*)(Whi + (size_t)(n3 * 16 + fr) * 1024 + k0 + fq * 8);
;         h8 bl = *(const h8*)(Wlo + (size_t)(n3 * 16 + fr) * 1024 + k0 + fq * 8);
;         acc[n3] = mfma16(hi, bh, acc[n3]); acc[n3] = mfma16(lo, bh, acc[n3]); acc[n3] = mfma16(hi, bl, acc[n3]);
;       }
;     }
	v_mfma_f32_16x16x32_f16 a[8:11], v[74:77], a[80:83], a[8:11]
	v_mfma_f32_16x16x32_f16 a[8:11], v[78:81], a[80:83], a[8:11]
	v_mfma_f32_16x16x32_f16 a[8:11], v[74:77], a[84:87], a[8:11]
	v_mfma_f32_16x16x32_f16 a[4:7], v[74:77], a[88:91], a[4:7]
	v_mfma_f32_16x16x32_f16 a[4:7], v[78:81], a[88:91], a[4:7]
	v_mfma_f32_16x16x32_f16 a[4:7], v[74:77], a[92:95], a[4:7]
	v_mfma_f32_16x16x32_f16 a[0:3], v[74:77], a[96:99], a[0:3]
	v_mfma_f32_16x16x32_f16 a[0:3], v[78:81], a[96:99], a[0:3]
	v_mfma_f32_16x16x32_f16 a[0:3], v[74:77], a[100:103], a[0:3]
	global_load_dwordx4 a[80:83], v[90:91], off offset:1920
	global_load_dwordx4 a[84:87], v[92:93], off offset:1920
	global_load_dwordx4 a[88:91], v[94:95], off offset:1920
	global_load_dwordx4 a[92:95], v[96:97], off offset:1920
	global_load_dwordx4 a[96:99], v[98:99], off offset:1920
	global_load_dwordx4 a[100:103], v[100:101], off offset:1920
	s_waitcnt vmcnt(48)
	v_accvgpr_read_b32 v0, a56
	v_accvgpr_read_b32 v1, a57
	v_accvgpr_read_b32 v2, a58
	v_accvgpr_read_b32 v3, a59
	v_accvgpr_read_b32 v4, a60
	v_accvgpr_read_b32 v5, a61
	v_accvgpr_read_b32 v6, a62
	v_accvgpr_read_b32 v7, a63
	v_pk_mul_f32 v[0:1], v[28:29], v[0:1]
	v_pk_mul_f32 v[2:3], v[28:29], v[2:3]
	v_pk_mul_f32 v[4:5], v[28:29], v[4:5]
	v_pk_mul_f32 v[6:7], v[28:29], v[6:7]
	s_waitcnt lgkmcnt(0)
	v_pk_mul_f32 v[0:1], v[0:1], v[32:33]
	v_pk_mul_f32 v[2:3], v[2:3], v[34:35]
	v_pk_mul_f32 v[4:5], v[4:5], v[36:37]
	v_pk_mul_f32 v[6:7], v[6:7], v[38:39]
	v_pk_add_f32 v[40:41], v[40:41], 1.0 op_sel_hi:[1,0]
	v_pk_add_f32 v[42:43], v[42:43], 1.0 op_sel_hi:[1,0]
	v_pk_add_f32 v[44:45], v[44:45], 1.0 op_sel_hi:[1,0]
	v_pk_add_f32 v[46:47], v[46:47], 1.0 op_sel_hi:[1,0]
	v_pk_fma_f32 v[0:1], v[0:1], v[40:41], v[58:59]
	v_pk_fma_f32 v[2:3], v[2:3], v[42:43], v[60:61]
	v_pk_fma_f32 v[4:5], v[4:5], v[44:45], v[62:63]
	v_pk_fma_f32 v[6:7], v[6:7], v[46:47], v[64:65]
	ds_read_b128 v[32:35], v102 offset:3328
	ds_read_b128 v[36:39], v102 offset:3344
	ds_read_b128 v[40:43], v102 offset:7424
	ds_read_b128 v[44:47], v102 offset:7440
	ds_read_b128 v[58:61], v102 offset:11520
	ds_read_b128 v[62:65], v102 offset:11536
	v_cvt_pk_f16_f32 v74, v0, v1
	v_cvt_pk_f16_f32 v75, v2, v3
	v_cvt_pk_f16_f32 v76, v4, v5
	v_cvt_pk_f16_f32 v77, v6, v7
	v_cvt_f32_f16_e32 v66, v74
	v_cvt_f32_f16_sdwa v67, v74 dst_sel:DWORD dst_unused:UNUSED_PAD src0_sel:WORD_1
	v_cvt_f32_f16_e32 v68, v75
	v_cvt_f32_f16_sdwa v69, v75 dst_sel:DWORD dst_unused:UNUSED_PAD src0_sel:WORD_1
	v_cvt_f32_f16_e32 v70, v76
	v_cvt_f32_f16_sdwa v71, v76 dst_sel:DWORD dst_unused:UNUSED_PAD src0_sel:WORD_1
	v_cvt_f32_f16_e32 v72, v77
	v_cvt_f32_f16_sdwa v73, v77 dst_sel:DWORD dst_unused:UNUSED_PAD src0_sel:WORD_1
	v_pk_add_f32 v[0:1], v[0:1], v[66:67] neg_lo:[0,1] neg_hi:[0,1]
	v_pk_add_f32 v[2:3], v[2:3], v[68:69] neg_lo:[0,1] neg_hi:[0,1]
	v_pk_add_f32 v[4:5], v[4:5], v[70:71] neg_lo:[0,1] neg_hi:[0,1]
	v_pk_add_f32 v[6:7], v[6:7], v[72:73] neg_lo:[0,1] neg_hi:[0,1]
	s_nop 0
	v_cvt_pk_f16_f32 v78, v0, v1
	v_cvt_pk_f16_f32 v79, v2, v3
	v_cvt_pk_f16_f32 v80, v4, v5
	v_cvt_pk_f16_f32 v81, v6, v7
	global_store_dwordx4 v[88:89], v[74:77], off offset:1600
	s_waitcnt vmcnt(40)
	v_mfma_f32_16x16x32_f16 a[8:11], v[74:77], a[104:107], a[8:11]
	v_mfma_f32_16x16x32_f16 a[8:11], v[78:81], a[104:107], a[8:11]
	v_mfma_f32_16x16x32_f16 a[8:11], v[74:77], a[108:111], a[8:11]
	v_mfma_f32_16x16x32_f16 a[4:7], v[74:77], a[112:115], a[4:7]
	v_mfma_f32_16x16x32_f16 a[4:7], v[78:81], a[112:115], a[4:7]
	v_mfma_f32_16x16x32_f16 a[4:7], v[74:77], a[116:119], a[4:7]
	v_mfma_f32_16x16x32_f16 a[0:3], v[74:77], a[120:123], a[0:3]
	v_mfma_f32_16x16x32_f16 a[0:3], v[78:81], a[120:123], a[0:3]
	v_mfma_f32_16x16x32_f16 a[0:3], v[74:77], a[124:127], a[0:3]
	global_load_dwordx4 a[104:107], v[90:91], off offset:1984
	global_load_dwordx4 a[108:111], v[92:93], off offset:1984
	global_load_dwordx4 a[112:115], v[94:95], off offset:1984
	global_load_dwordx4 a[116:119], v[96:97], off offset:1984
	global_load_dwordx4 a[120:123], v[98:99], off offset:1984
	global_load_dwordx4 a[124:127], v[100:101], off offset:1984
	s_waitcnt vmcnt(46)
	v_accvgpr_read_b32 v0, a64
	v_accvgpr_read_b32 v1, a65
	v_accvgpr_read_b32 v2, a66
	v_accvgpr_read_b32 v3, a67
	v_accvgpr_read_b32 v4, a68
	v_accvgpr_read_b32 v5, a69
	v_accvgpr_read_b32 v6, a70
	v_accvgpr_read_b32 v7, a71
	v_pk_mul_f32 v[0:1], v[28:29], v[0:1]
	v_pk_mul_f32 v[2:3], v[28:29], v[2:3]
	v_pk_mul_f32 v[4:5], v[28:29], v[4:5]
	v_pk_mul_f32 v[6:7], v[28:29], v[6:7]
	s_waitcnt lgkmcnt(0)
	v_pk_mul_f32 v[0:1], v[0:1], v[32:33]
	v_pk_mul_f32 v[2:3], v[2:3], v[34:35]
	v_pk_mul_f32 v[4:5], v[4:5], v[36:37]
	v_pk_mul_f32 v[6:7], v[6:7], v[38:39]
	v_pk_add_f32 v[40:41], v[40:41], 1.0 op_sel_hi:[1,0]
	v_pk_add_f32 v[42:43], v[42:43], 1.0 op_sel_hi:[1,0]
	v_pk_add_f32 v[44:45], v[44:45], 1.0 op_sel_hi:[1,0]
	v_pk_add_f32 v[46:47], v[46:47], 1.0 op_sel_hi:[1,0]
	v_pk_fma_f32 v[0:1], v[0:1], v[40:41], v[58:59]
	v_pk_fma_f32 v[2:3], v[2:3], v[42:43], v[60:61]
	v_pk_fma_f32 v[4:5], v[4:5], v[44:45], v[62:63]
	v_pk_fma_f32 v[6:7], v[6:7], v[46:47], v[64:65]
	ds_read_b128 v[32:35], v102 offset:3456
	ds_read_b128 v[36:39], v102 offset:3472
	ds_read_b128 v[40:43], v102 offset:7552
	ds_read_b128 v[44:47], v102 offset:7568
	ds_read_b128 v[58:61], v102 offset:11648
	ds_read_b128 v[62:65], v102 offset:11664
	v_cvt_pk_f16_f32 v74, v0, v1
	v_cvt_pk_f16_f32 v75, v2, v3
	v_cvt_pk_f16_f32 v76, v4, v5
	v_cvt_pk_f16_f32 v77, v6, v7
	v_cvt_f32_f16_e32 v66, v74
	v_cvt_f32_f16_sdwa v67, v74 dst_sel:DWORD dst_unused:UNUSED_PAD src0_sel:WORD_1
	v_cvt_f32_f16_e32 v68, v75
	v_cvt_f32_f16_sdwa v69, v75 dst_sel:DWORD dst_unused:UNUSED_PAD src0_sel:WORD_1
	v_cvt_f32_f16_e32 v70, v76
	v_cvt_f32_f16_sdwa v71, v76 dst_sel:DWORD dst_unused:UNUSED_PAD src0_sel:WORD_1
	v_cvt_f32_f16_e32 v72, v77
	v_cvt_f32_f16_sdwa v73, v77 dst_sel:DWORD dst_unused:UNUSED_PAD src0_sel:WORD_1
	v_pk_add_f32 v[0:1], v[0:1], v[66:67] neg_lo:[0,1] neg_hi:[0,1]
	v_pk_add_f32 v[2:3], v[2:3], v[68:69] neg_lo:[0,1] neg_hi:[0,1]
	v_pk_add_f32 v[4:5], v[4:5], v[70:71] neg_lo:[0,1] neg_hi:[0,1]
	v_pk_add_f32 v[6:7], v[6:7], v[72:73] neg_lo:[0,1] neg_hi:[0,1]
	s_nop 0
	v_cvt_pk_f16_f32 v78, v0, v1
	v_cvt_pk_f16_f32 v79, v2, v3
	v_cvt_pk_f16_f32 v80, v4, v5
	v_cvt_pk_f16_f32 v81, v6, v7
	global_store_dwordx4 v[88:89], v[74:77], off offset:1664
	s_waitcnt vmcnt(38)
; DI f4 mfma16(h8 a, h8 b, f4 c) { return __builtin_amdgcn_mfma_f32_16x16x32_f16(a, b, c, 0, 0, 0); }
; DI void row2_phase(const Params& P, int l, int r_begin, char* smem) {
;     ...
; #pragma unroll 4
;     for (int kk = 0; kk < 32; kk++) {
;       const int k0 = kk * 32;
;       float x[8], g[8], s1[8], s0[8];
;       *(float4*)&x[0] = *(const float4*)(xm + k0); *(float4*)&x[4] = *(const float4*)(xm + k0 + 4);
;       *(float4*)&g[0] = *(const float4*)(gam + fq * 8 + k0); *(float4*)&g[4] = *(const float4*)(gam + fq * 8 + k0 + 4);
;       *(float4*)&s1[0] = *(const float4*)(sc + k0); *(float4*)&s1[4] = *(const float4*)(sc + k0 + 4);
;       *(float4*)&s0[0] = *(const float4*)(sh + k0); *(float4*)&s0[4] = *(const float4*)(sh + k0 + 4);
;       h8 hi, lo;
; #pragma unroll
;       for (int i = 0; i < 8; i++) {
;         float v = x[i] * rstd * g[i] * (1.f + s1[i]) + s0[i];
;         hi[i] = (half_t)v; lo[i] = (half_t)(v - (float)hi[i]);
;       }
;       *(h8*)(hxo + k0) = hi;
; #pragma unroll
;       for (int n3 = 0; n3 < 3; n3++) {
;         h8 bh = *(const h8*)(Whi + (size_t)(n3 * 16 + fr) * 1024 + k0 + fq * 8);
;         h8 bl = *(const h8*)(Wlo + (size_t)(n3 * 16 + fr) * 1024 + k0 + fq * 8);
;         acc[n3] = mfma16(hi, bh, acc[n3]); acc[n3] = mfma16(lo, bh, acc[n3]); acc[n3] = mfma16(hi, bl, acc[n3]);
;       }
;     }
	v_mfma_f32_16x16x32_f16 a[8:11], v[74:77], a[128:131], a[8:11]
	v_mfma_f32_16x16x32_f16 a[8:11], v[78:81], a[128:131], a[8:11]
	v_mfma_f32_16x16x32_f16 a[8:11], v[74:77], a[132:135], a[8:11]
	v_mfma_f32_16x16x32_f16 a[4:7], v[74:77], a[136:139], a[4:7]
	v_mfma_f32_16x16x32_f16 a[4:7], v[78:81], a[136:139], a[4:7]
	v_mfma_f32_16x16x32_f16 a[4:7], v[74:77], a[140:143], a[4:7]
	v_mfma_f32_16x16x32_f16 a[0:3], v[74:77], a[144:147], a[0:3]
	v_mfma_f32_16x16x32_f16 a[0:3], v[78:81], a[144:147], a[0:3]
	v_mfma_f32_16x16x32_f16 a[0:3], v[74:77], a[148:151], a[0:3]
	s_waitcnt vmcnt(38)
	v_accvgpr_read_b32 v0, a72
	v_accvgpr_read_b32 v1, a73
	v_accvgpr_read_b32 v2, a74
	v_accvgpr_read_b32 v3, a75
	v_accvgpr_read_b32 v4, a76
	v_accvgpr_read_b32 v5, a77
	v_accvgpr_read_b32 v6, a78
	v_accvgpr_read_b32 v7, a79
	v_pk_mul_f32 v[0:1], v[28:29], v[0:1]
	v_pk_mul_f32 v[2:3], v[28:29], v[2:3]
	v_pk_mul_f32 v[4:5], v[28:29], v[4:5]
	v_pk_mul_f32 v[6:7], v[28:29], v[6:7]
	s_waitcnt lgkmcnt(0)
	v_pk_mul_f32 v[0:1], v[0:1], v[32:33]
	v_pk_mul_f32 v[2:3], v[2:3], v[34:35]
	v_pk_mul_f32 v[4:5], v[4:5], v[36:37]
	v_pk_mul_f32 v[6:7], v[6:7], v[38:39]
	v_pk_add_f32 v[40:41], v[40:41], 1.0 op_sel_hi:[1,0]
	v_pk_add_f32 v[42:43], v[42:43], 1.0 op_sel_hi:[1,0]
	v_pk_add_f32 v[44:45], v[44:45], 1.0 op_sel_hi:[1,0]
	v_pk_add_f32 v[46:47], v[46:47], 1.0 op_sel_hi:[1,0]
	v_pk_fma_f32 v[0:1], v[0:1], v[40:41], v[58:59]
	v_pk_fma_f32 v[2:3], v[2:3], v[42:43], v[60:61]
	v_pk_fma_f32 v[4:5], v[4:5], v[44:45], v[62:63]
	v_pk_fma_f32 v[6:7], v[6:7], v[46:47], v[64:65]
	ds_read_b128 v[32:35], v102 offset:3584
	ds_read_b128 v[36:39], v102 offset:3600
	ds_read_b128 v[40:43], v102 offset:7680
	ds_read_b128 v[44:47], v102 offset:7696
	ds_read_b128 v[58:61], v102 offset:11776
	ds_read_b128 v[62:65], v102 offset:11792
	v_cvt_pk_f16_f32 v74, v0, v1
	v_cvt_pk_f16_f32 v75, v2, v3
	v_cvt_pk_f16_f32 v76, v4, v5
	v_cvt_pk_f16_f32 v77, v6, v7
	v_cvt_f32_f16_e32 v66, v74
	v_cvt_f32_f16_sdwa v67, v74 dst_sel:DWORD dst_unused:UNUSED_PAD src0_sel:WORD_1
	v_cvt_f32_f16_e32 v68, v75
	v_cvt_f32_f16_sdwa v69, v75 dst_sel:DWORD dst_unused:UNUSED_PAD src0_sel:WORD_1
	v_cvt_f32_f16_e32 v70, v76
	v_cvt_f32_f16_sdwa v71, v76 dst_sel:DWORD dst_unused:UNUSED_PAD src0_sel:WORD_1
	v_cvt_f32_f16_e32 v72, v77
	v_cvt_f32_f16_sdwa v73, v77 dst_sel:DWORD dst_unused:UNUSED_PAD src0_sel:WORD_1
	v_pk_add_f32 v[0:1], v[0:1], v[66:67] neg_lo:[0,1] neg_hi:[0,1]
	v_pk_add_f32 v[2:3], v[2:3], v[68:69] neg_lo:[0,1] neg_hi:[0,1]
	v_pk_add_f32 v[4:5], v[4:5], v[70:71] neg_lo:[0,1] neg_hi:[0,1]
	v_pk_add_f32 v[6:7], v[6:7], v[72:73] neg_lo:[0,1] neg_hi:[0,1]
	s_nop 0
	v_cvt_pk_f16_f32 v78, v0, v1
	v_cvt_pk_f16_f32 v79, v2, v3
	v_cvt_pk_f16_f32 v80, v4, v5
	v_cvt_pk_f16_f32 v81, v6, v7
	global_store_dwordx4 v[88:89], v[74:77], off offset:1728
	s_waitcnt vmcnt(30)
	v_mfma_f32_16x16x32_f16 a[8:11], v[74:77], a[152:155], a[8:11]
	v_mfma_f32_16x16x32_f16 a[8:11], v[78:81], a[152:155], a[8:11]
	v_mfma_f32_16x16x32_f16 a[8:11], v[74:77], a[156:159], a[8:11]
	v_mfma_f32_16x16x32_f16 a[4:7], v[74:77], a[160:163], a[4:7]
	v_mfma_f32_16x16x32_f16 a[4:7], v[78:81], a[160:163], a[4:7]
	v_mfma_f32_16x16x32_f16 a[4:7], v[74:77], a[164:167], a[4:7]
	v_mfma_f32_16x16x32_f16 a[0:3], v[74:77], a[168:171], a[0:3]
	v_mfma_f32_16x16x32_f16 a[0:3], v[78:81], a[168:171], a[0:3]
	v_mfma_f32_16x16x32_f16 a[0:3], v[74:77], a[172:175], a[0:3]
	s_waitcnt vmcnt(30)
	v_accvgpr_read_b32 v0, a180
	v_accvgpr_read_b32 v1, a181
	v_accvgpr_read_b32 v2, a182
	v_accvgpr_read_b32 v3, a183
	v_accvgpr_read_b32 v4, a184
	v_accvgpr_read_b32 v5, a185
	v_accvgpr_read_b32 v6, a186
	v_accvgpr_read_b32 v7, a187
	v_pk_mul_f32 v[0:1], v[28:29], v[0:1]
	v_pk_mul_f32 v[2:3], v[28:29], v[2:3]
	v_pk_mul_f32 v[4:5], v[28:29], v[4:5]
	v_pk_mul_f32 v[6:7], v[28:29], v[6:7]
	s_waitcnt lgkmcnt(0)
	v_pk_mul_f32 v[0:1], v[0:1], v[32:33]
	v_pk_mul_f32 v[2:3], v[2:3], v[34:35]
	v_pk_mul_f32 v[4:5], v[4:5], v[36:37]
	v_pk_mul_f32 v[6:7], v[6:7], v[38:39]
	v_pk_add_f32 v[40:41], v[40:41], 1.0 op_sel_hi:[1,0]
	v_pk_add_f32 v[42:43], v[42:43], 1.0 op_sel_hi:[1,0]
	v_pk_add_f32 v[44:45], v[44:45], 1.0 op_sel_hi:[1,0]
	v_pk_add_f32 v[46:47], v[46:47], 1.0 op_sel_hi:[1,0]
	v_pk_fma_f32 v[0:1], v[0:1], v[40:41], v[58:59]
	v_pk_fma_f32 v[2:3], v[2:3], v[42:43], v[60:61]
	v_pk_fma_f32 v[4:5], v[4:5], v[44:45], v[62:63]
	v_pk_fma_f32 v[6:7], v[6:7], v[46:47], v[64:65]
	ds_read_b128 v[32:35], v102 offset:3712
	ds_read_b128 v[36:39], v102 offset:3728
	ds_read_b128 v[40:43], v102 offset:7808
	ds_read_b128 v[44:47], v102 offset:7824
	ds_read_b128 v[58:61], v102 offset:11904
	ds_read_b128 v[62:65], v102 offset:11920
	v_cvt_pk_f16_f32 v74, v0, v1
	v_cvt_pk_f16_f32 v75, v2, v3
	v_cvt_pk_f16_f32 v76, v4, v5
	v_cvt_pk_f16_f32 v77, v6, v7
	v_cvt_f32_f16_e32 v66, v74
	v_cvt_f32_f16_sdwa v67, v74 dst_sel:DWORD dst_unused:UNUSED_PAD src0_sel:WORD_1
	v_cvt_f32_f16_e32 v68, v75
	v_cvt_f32_f16_sdwa v69, v75 dst_sel:DWORD dst_unused:UNUSED_PAD src0_sel:WORD_1
	v_cvt_f32_f16_e32 v70, v76
	v_cvt_f32_f16_sdwa v71, v76 dst_sel:DWORD dst_unused:UNUSED_PAD src0_sel:WORD_1
	v_cvt_f32_f16_e32 v72, v77
	v_cvt_f32_f16_sdwa v73, v77 dst_sel:DWORD dst_unused:UNUSED_PAD src0_sel:WORD_1
	v_pk_add_f32 v[0:1], v[0:1], v[66:67] neg_lo:[0,1] neg_hi:[0,1]
	v_pk_add_f32 v[2:3], v[2:3], v[68:69] neg_lo:[0,1] neg_hi:[0,1]
	v_pk_add_f32 v[4:5], v[4:5], v[70:71] neg_lo:[0,1] neg_hi:[0,1]
	v_pk_add_f32 v[6:7], v[6:7], v[72:73] neg_lo:[0,1] neg_hi:[0,1]
	s_nop 0
	v_cvt_pk_f16_f32 v78, v0, v1
	v_cvt_pk_f16_f32 v79, v2, v3
	v_cvt_pk_f16_f32 v80, v4, v5
	v_cvt_pk_f16_f32 v81, v6, v7
	global_store_dwordx4 v[88:89], v[74:77], off offset:1792
	s_waitcnt vmcnt(24)
; DI f4 mfma16(h8 a, h8 b, f4 c) { return __builtin_amdgcn_mfma_f32_16x16x32_f16(a, b, c, 0, 0, 0); }
; DI void row2_phase(const Params& P, int l, int r_begin, char* smem) {
;     ...
; #pragma unroll 4
;     for (int kk = 0; kk < 32; kk++) {
;       const int k0 = kk * 32;
;       float x[8], g[8], s1[8], s0[8];
;       *(float4*)&x[0] = *(const float4*)(xm + k0); *(float4*)&x[4] = *(const float4*)(xm + k0 + 4);
;       *(float4*)&g[0] = *(const float4*)(gam + fq * 8 + k0); *(float4*)&g[4] = *(const float4*)(gam + fq * 8 + k0 + 4);
;       *(float4*)&s1[0] = *(const float4*)(sc + k0); *(float4*)&s1[4] = *(const float4*)(sc + k0 + 4);
;       *(float4*)&s0[0] = *(const float4*)(sh + k0); *(float4*)&s0[4] = *(const float4*)(sh + k0 + 4);
;       h8 hi, lo;
; #pragma unroll
;       for (int i = 0; i < 8; i++) {
;         float v = x[i] * rstd * g[i] * (1.f + s1[i]) + s0[i];
;         hi[i] = (half_t)v; lo[i] = (half_t)(v - (float)hi[i]);
;       }
;       *(h8*)(hxo + k0) = hi;
; #pragma unroll
;       for (int n3 = 0; n3 < 3; n3++) {
;         h8 bh = *(const h8*)(Whi + (size_t)(n3 * 16 + fr) * 1024 + k0 + fq * 8);
;         h8 bl = *(const h8*)(Wlo + (size_t)(n3 * 16 + fr) * 1024 + k0 + fq * 8);
;         acc[n3] = mfma16(hi, bh, acc[n3]); acc[n3] = mfma16(lo, bh, acc[n3]); acc[n3] = mfma16(hi, bl, acc[n3]);
;       }
;     }
	v_mfma_f32_16x16x32_f16 a[8:11], v[74:77], a[204:207], a[8:11]
	v_mfma_f32_16x16x32_f16 a[8:11], v[78:81], a[204:207], a[8:11]
	v_mfma_f32_16x16x32_f16 a[8:11], v[74:77], a[208:211], a[8:11]
	v_mfma_f32_16x16x32_f16 a[4:7], v[74:77], a[212:215], a[4:7]
	v_mfma_f32_16x16x32_f16 a[4:7], v[78:81], a[212:215], a[4:7]
	v_mfma_f32_16x16x32_f16 a[4:7], v[74:77], a[216:219], a[4:7]
	v_mfma_f32_16x16x32_f16 a[0:3], v[74:77], a[220:223], a[0:3]
	v_mfma_f32_16x16x32_f16 a[0:3], v[78:81], a[220:223], a[0:3]
	v_mfma_f32_16x16x32_f16 a[0:3], v[74:77], a[224:227], a[0:3]
	s_waitcnt vmcnt(24)
	v_accvgpr_read_b32 v0, a196
	v_accvgpr_read_b32 v1, a197
	v_accvgpr_read_b32 v2, a198
	v_accvgpr_read_b32 v3, a199
	v_accvgpr_read_b32 v4, a200
	v_accvgpr_read_b32 v5, a201
	v_accvgpr_read_b32 v6, a202
	v_accvgpr_read_b32 v7, a203
	v_pk_mul_f32 v[0:1], v[28:29], v[0:1]
	v_pk_mul_f32 v[2:3], v[28:29], v[2:3]
	v_pk_mul_f32 v[4:5], v[28:29], v[4:5]
	v_pk_mul_f32 v[6:7], v[28:29], v[6:7]
	s_waitcnt lgkmcnt(0)
	v_pk_mul_f32 v[0:1], v[0:1], v[32:33]
	v_pk_mul_f32 v[2:3], v[2:3], v[34:35]
	v_pk_mul_f32 v[4:5], v[4:5], v[36:37]
	v_pk_mul_f32 v[6:7], v[6:7], v[38:39]
	v_pk_add_f32 v[40:41], v[40:41], 1.0 op_sel_hi:[1,0]
	v_pk_add_f32 v[42:43], v[42:43], 1.0 op_sel_hi:[1,0]
	v_pk_add_f32 v[44:45], v[44:45], 1.0 op_sel_hi:[1,0]
	v_pk_add_f32 v[46:47], v[46:47], 1.0 op_sel_hi:[1,0]
	v_pk_fma_f32 v[0:1], v[0:1], v[40:41], v[58:59]
	v_pk_fma_f32 v[2:3], v[2:3], v[42:43], v[60:61]
	v_pk_fma_f32 v[4:5], v[4:5], v[44:45], v[62:63]
	v_pk_fma_f32 v[6:7], v[6:7], v[46:47], v[64:65]
	ds_read_b128 v[32:35], v102 offset:3840
	ds_read_b128 v[36:39], v102 offset:3856
	ds_read_b128 v[40:43], v102 offset:7936
	ds_read_b128 v[44:47], v102 offset:7952
	ds_read_b128 v[58:61], v102 offset:12032
	ds_read_b128 v[62:65], v102 offset:12048
	v_cvt_pk_f16_f32 v74, v0, v1
	v_cvt_pk_f16_f32 v75, v2, v3
	v_cvt_pk_f16_f32 v76, v4, v5
	v_cvt_pk_f16_f32 v77, v6, v7
	v_cvt_f32_f16_e32 v66, v74
	v_cvt_f32_f16_sdwa v67, v74 dst_sel:DWORD dst_unused:UNUSED_PAD src0_sel:WORD_1
	v_cvt_f32_f16_e32 v68, v75
	v_cvt_f32_f16_sdwa v69, v75 dst_sel:DWORD dst_unused:UNUSED_PAD src0_sel:WORD_1
	v_cvt_f32_f16_e32 v70, v76
	v_cvt_f32_f16_sdwa v71, v76 dst_sel:DWORD dst_unused:UNUSED_PAD src0_sel:WORD_1
	v_cvt_f32_f16_e32 v72, v77
	v_cvt_f32_f16_sdwa v73, v77 dst_sel:DWORD dst_unused:UNUSED_PAD src0_sel:WORD_1
	v_pk_add_f32 v[0:1], v[0:1], v[66:67] neg_lo:[0,1] neg_hi:[0,1]
	v_pk_add_f32 v[2:3], v[2:3], v[68:69] neg_lo:[0,1] neg_hi:[0,1]
	v_pk_add_f32 v[4:5], v[4:5], v[70:71] neg_lo:[0,1] neg_hi:[0,1]
	v_pk_add_f32 v[6:7], v[6:7], v[72:73] neg_lo:[0,1] neg_hi:[0,1]
	s_nop 0
	v_cvt_pk_f16_f32 v78, v0, v1
	v_cvt_pk_f16_f32 v79, v2, v3
	v_cvt_pk_f16_f32 v80, v4, v5
	v_cvt_pk_f16_f32 v81, v6, v7
	global_store_dwordx4 v[88:89], v[74:77], off offset:1856
	s_waitcnt vmcnt(18)
	v_mfma_f32_16x16x32_f16 a[8:11], v[74:77], a[228:231], a[8:11]
	v_mfma_f32_16x16x32_f16 a[8:11], v[78:81], a[228:231], a[8:11]
	v_mfma_f32_16x16x32_f16 a[8:11], v[74:77], a[232:235], a[8:11]
	v_mfma_f32_16x16x32_f16 a[4:7], v[74:77], a[236:239], a[4:7]
	v_mfma_f32_16x16x32_f16 a[4:7], v[78:81], a[236:239], a[4:7]
	v_mfma_f32_16x16x32_f16 a[4:7], v[74:77], a[240:243], a[4:7]
	v_mfma_f32_16x16x32_f16 a[0:3], v[74:77], a[244:247], a[0:3]
	v_mfma_f32_16x16x32_f16 a[0:3], v[78:81], a[244:247], a[0:3]
	v_mfma_f32_16x16x32_f16 a[0:3], v[74:77], a[248:251], a[0:3]
	s_waitcnt vmcnt(18)
	v_accvgpr_read_b32 v0, a16
	v_accvgpr_read_b32 v1, a17
	v_accvgpr_read_b32 v2, a18
	v_accvgpr_read_b32 v3, a19
	v_accvgpr_read_b32 v4, a20
	v_accvgpr_read_b32 v5, a21
	v_accvgpr_read_b32 v6, a22
	v_accvgpr_read_b32 v7, a23
	v_pk_mul_f32 v[0:1], v[28:29], v[0:1]
	v_pk_mul_f32 v[2:3], v[28:29], v[2:3]
	v_pk_mul_f32 v[4:5], v[28:29], v[4:5]
	v_pk_mul_f32 v[6:7], v[28:29], v[6:7]
	s_waitcnt lgkmcnt(0)
	v_pk_mul_f32 v[0:1], v[0:1], v[32:33]
	v_pk_mul_f32 v[2:3], v[2:3], v[34:35]
	v_pk_mul_f32 v[4:5], v[4:5], v[36:37]
	v_pk_mul_f32 v[6:7], v[6:7], v[38:39]
	v_pk_add_f32 v[40:41], v[40:41], 1.0 op_sel_hi:[1,0]
	v_pk_add_f32 v[42:43], v[42:43], 1.0 op_sel_hi:[1,0]
	v_pk_add_f32 v[44:45], v[44:45], 1.0 op_sel_hi:[1,0]
	v_pk_add_f32 v[46:47], v[46:47], 1.0 op_sel_hi:[1,0]
	v_pk_fma_f32 v[0:1], v[0:1], v[40:41], v[58:59]
	v_pk_fma_f32 v[2:3], v[2:3], v[42:43], v[60:61]
	v_pk_fma_f32 v[4:5], v[4:5], v[44:45], v[62:63]
	v_pk_fma_f32 v[6:7], v[6:7], v[46:47], v[64:65]
	ds_read_b128 v[32:35], v102 offset:3968
	ds_read_b128 v[36:39], v102 offset:3984
	ds_read_b128 v[40:43], v102 offset:8064
	ds_read_b128 v[44:47], v102 offset:8080
	ds_read_b128 v[58:61], v102 offset:12160
	ds_read_b128 v[62:65], v102 offset:12176
	v_cvt_pk_f16_f32 v74, v0, v1
	v_cvt_pk_f16_f32 v75, v2, v3
	v_cvt_pk_f16_f32 v76, v4, v5
	v_cvt_pk_f16_f32 v77, v6, v7
	v_cvt_f32_f16_e32 v66, v74
	v_cvt_f32_f16_sdwa v67, v74 dst_sel:DWORD dst_unused:UNUSED_PAD src0_sel:WORD_1
	v_cvt_f32_f16_e32 v68, v75
	v_cvt_f32_f16_sdwa v69, v75 dst_sel:DWORD dst_unused:UNUSED_PAD src0_sel:WORD_1
	v_cvt_f32_f16_e32 v70, v76
	v_cvt_f32_f16_sdwa v71, v76 dst_sel:DWORD dst_unused:UNUSED_PAD src0_sel:WORD_1
	v_cvt_f32_f16_e32 v72, v77
	v_cvt_f32_f16_sdwa v73, v77 dst_sel:DWORD dst_unused:UNUSED_PAD src0_sel:WORD_1
	v_pk_add_f32 v[0:1], v[0:1], v[66:67] neg_lo:[0,1] neg_hi:[0,1]
	v_pk_add_f32 v[2:3], v[2:3], v[68:69] neg_lo:[0,1] neg_hi:[0,1]
	v_pk_add_f32 v[4:5], v[4:5], v[70:71] neg_lo:[0,1] neg_hi:[0,1]
	v_pk_add_f32 v[6:7], v[6:7], v[72:73] neg_lo:[0,1] neg_hi:[0,1]
	s_nop 0
	v_cvt_pk_f16_f32 v78, v0, v1
	v_cvt_pk_f16_f32 v79, v2, v3
	v_cvt_pk_f16_f32 v80, v4, v5
	v_cvt_pk_f16_f32 v81, v6, v7
	global_store_dwordx4 v[88:89], v[74:77], off offset:1920
	s_waitcnt vmcnt(12)
; DI f4 mfma16(h8 a, h8 b, f4 c) { return __builtin_amdgcn_mfma_f32_16x16x32_f16(a, b, c, 0, 0, 0); }
; DI void row2_phase(const Params& P, int l, int r_begin, char* smem) {
;     ...
; #pragma unroll 4
;     for (int kk = 0; kk < 32; kk++) {
;       const int k0 = kk * 32;
;       float x[8], g[8], s1[8], s0[8];
;       *(float4*)&x[0] = *(const float4*)(xm + k0); *(float4*)&x[4] = *(const float4*)(xm + k0 + 4);
;       *(float4*)&g[0] = *(const float4*)(gam + fq * 8 + k0); *(float4*)&g[4] = *(const float4*)(gam + fq * 8 + k0 + 4);
;       *(float4*)&s1[0] = *(const float4*)(sc + k0); *(float4*)&s1[4] = *(const float4*)(sc + k0 + 4);
;       *(float4*)&s0[0] = *(const float4*)(sh + k0); *(float4*)&s0[4] = *(const float4*)(sh + k0 + 4);
;       h8 hi, lo;
; #pragma unroll
;       for (int i = 0; i < 8; i++) {
;         float v = x[i] * rstd * g[i] * (1.f + s1[i]) + s0[i];
;         hi[i] = (half_t)v; lo[i] = (half_t)(v - (float)hi[i]);
;       }
;       *(h8*)(hxo + k0) = hi;
; #pragma unroll
;       for (int n3 = 0; n3 < 3; n3++) {
;         h8 bh = *(const h8*)(Whi + (size_t)(n3 * 16 + fr) * 1024 + k0 + fq * 8);
;         h8 bl = *(const h8*)(Wlo + (size_t)(n3 * 16 + fr) * 1024 + k0 + fq * 8);
;         acc[n3] = mfma16(hi, bh, acc[n3]); acc[n3] = mfma16(lo, bh, acc[n3]); acc[n3] = mfma16(hi, bl, acc[n3]);
;       }
;     }
;     __builtin_amdgcn_wave_barrier();
; #pragma unroll
;     for (int n3 = 0; n3 < 3; n3++)
; #pragma unroll
;       for (int j = 0; j < 4; j++) lg[(fq * 4 + j) * 48 + n3 * 16 + fr] = acc[n3][j];
;     __builtin_amdgcn_wave_barrier();
;     if (lane < 16) {
;       const int r = r0 + lane;
;       const float* L = lg + lane * 48;
;       float gl[4]; int gi = 0;
; #pragma unroll
;       for (int j = 0; j < 4; j++) gl[j] = L[j] + P.b_group[l * 4 + j];
	v_mfma_f32_16x16x32_f16 a[8:11], v[74:77], a[80:83], a[8:11]
	v_mfma_f32_16x16x32_f16 a[8:11], v[78:81], a[80:83], a[8:11]
	v_mfma_f32_16x16x32_f16 a[8:11], v[74:77], a[84:87], a[8:11]
	v_mfma_f32_16x16x32_f16 a[4:7], v[74:77], a[88:91], a[4:7]
	v_mfma_f32_16x16x32_f16 a[4:7], v[78:81], a[88:91], a[4:7]
	v_mfma_f32_16x16x32_f16 a[4:7], v[74:77], a[92:95], a[4:7]
	v_mfma_f32_16x16x32_f16 a[0:3], v[74:77], a[96:99], a[0:3]
	v_mfma_f32_16x16x32_f16 a[0:3], v[78:81], a[96:99], a[0:3]
	v_mfma_f32_16x16x32_f16 a[0:3], v[74:77], a[100:103], a[0:3]
	s_waitcnt vmcnt(12)
	v_accvgpr_read_b32 v0, a24
	v_accvgpr_read_b32 v1, a25
	v_accvgpr_read_b32 v2, a26
	v_accvgpr_read_b32 v3, a27
	v_accvgpr_read_b32 v4, a28
	v_accvgpr_read_b32 v5, a29
	v_accvgpr_read_b32 v6, a30
	v_accvgpr_read_b32 v7, a31
	v_pk_mul_f32 v[0:1], v[28:29], v[0:1]
	v_pk_mul_f32 v[2:3], v[28:29], v[2:3]
	v_pk_mul_f32 v[4:5], v[28:29], v[4:5]
	v_pk_mul_f32 v[6:7], v[28:29], v[6:7]
	s_waitcnt lgkmcnt(0)
	v_pk_mul_f32 v[0:1], v[0:1], v[32:33]
	v_pk_mul_f32 v[2:3], v[2:3], v[34:35]
	v_pk_mul_f32 v[4:5], v[4:5], v[36:37]
	v_pk_mul_f32 v[6:7], v[6:7], v[38:39]
	v_pk_add_f32 v[40:41], v[40:41], 1.0 op_sel_hi:[1,0]
	v_pk_add_f32 v[42:43], v[42:43], 1.0 op_sel_hi:[1,0]
	v_pk_add_f32 v[44:45], v[44:45], 1.0 op_sel_hi:[1,0]
	v_pk_add_f32 v[46:47], v[46:47], 1.0 op_sel_hi:[1,0]
	v_pk_fma_f32 v[0:1], v[0:1], v[40:41], v[58:59]
	v_pk_fma_f32 v[2:3], v[2:3], v[42:43], v[60:61]
	v_pk_fma_f32 v[4:5], v[4:5], v[44:45], v[62:63]
	v_pk_fma_f32 v[6:7], v[6:7], v[46:47], v[64:65]
	v_cvt_pk_f16_f32 v74, v0, v1
	v_cvt_pk_f16_f32 v75, v2, v3
	v_cvt_pk_f16_f32 v76, v4, v5
	v_cvt_pk_f16_f32 v77, v6, v7
	v_cvt_f32_f16_e32 v66, v74
	v_cvt_f32_f16_sdwa v67, v74 dst_sel:DWORD dst_unused:UNUSED_PAD src0_sel:WORD_1
	v_cvt_f32_f16_e32 v68, v75
	v_cvt_f32_f16_sdwa v69, v75 dst_sel:DWORD dst_unused:UNUSED_PAD src0_sel:WORD_1
	v_cvt_f32_f16_e32 v70, v76
	v_cvt_f32_f16_sdwa v71, v76 dst_sel:DWORD dst_unused:UNUSED_PAD src0_sel:WORD_1
	v_cvt_f32_f16_e32 v72, v77
	v_cvt_f32_f16_sdwa v73, v77 dst_sel:DWORD dst_unused:UNUSED_PAD src0_sel:WORD_1
	v_pk_add_f32 v[0:1], v[0:1], v[66:67] neg_lo:[0,1] neg_hi:[0,1]
	v_pk_add_f32 v[2:3], v[2:3], v[68:69] neg_lo:[0,1] neg_hi:[0,1]
	v_pk_add_f32 v[4:5], v[4:5], v[70:71] neg_lo:[0,1] neg_hi:[0,1]
	v_pk_add_f32 v[6:7], v[6:7], v[72:73] neg_lo:[0,1] neg_hi:[0,1]
	s_nop 0
	v_cvt_pk_f16_f32 v78, v0, v1
	v_cvt_pk_f16_f32 v79, v2, v3
	v_cvt_pk_f16_f32 v80, v4, v5
	v_cvt_pk_f16_f32 v81, v6, v7
	global_store_dwordx4 v[88:89], v[74:77], off offset:1984
	s_waitcnt vmcnt(6)
	v_mfma_f32_16x16x32_f16 a[8:11], v[74:77], a[104:107], a[8:11]
	v_mfma_f32_16x16x32_f16 a[8:11], v[78:81], a[104:107], a[8:11]
	v_mfma_f32_16x16x32_f16 a[8:11], v[74:77], a[108:111], a[8:11]
	v_mfma_f32_16x16x32_f16 a[4:7], v[74:77], a[112:115], a[4:7]
	v_mfma_f32_16x16x32_f16 a[4:7], v[78:81], a[112:115], a[4:7]
	v_mfma_f32_16x16x32_f16 a[4:7], v[74:77], a[116:119], a[4:7]
	v_mfma_f32_16x16x32_f16 a[0:3], v[74:77], a[120:123], a[0:3]
	v_mfma_f32_16x16x32_f16 a[0:3], v[78:81], a[120:123], a[0:3]
	v_mfma_f32_16x16x32_f16 a[0:3], v[74:77], a[124:127], a[0:3]
	s_nop 7
	s_nop 6
	v_accvgpr_read_b32 v0, a0
	v_accvgpr_read_b32 v4, a4
	v_accvgpr_read_b32 v8, a8
	v_accvgpr_read_b32 v1, a1
	v_accvgpr_read_b32 v2, a2
	v_accvgpr_read_b32 v3, a3
	v_accvgpr_read_b32 v5, a5
	v_accvgpr_read_b32 v6, a6
	v_accvgpr_read_b32 v7, a7
	v_accvgpr_read_b32 v9, a9
	v_accvgpr_read_b32 v10, a10
	v_accvgpr_read_b32 v11, a11
	ds_write2_b32 v55, v8, v4 offset1:16
	ds_write2_b32 v55, v10, v6 offset0:96 offset1:112
	ds_write2_b32 v55, v0, v9 offset0:32 offset1:48
	ds_write2_b32 v55, v5, v1 offset0:64 offset1:80
	ds_write2_b32 v55, v2, v11 offset0:128 offset1:144
	ds_write2_b32 v55, v7, v3 offset0:160 offset1:176
	s_and_saveexec_b64 s[34:35], s[2:3]
	s_cbranch_execz .LBB0_544
	global_load_dwordx4 v[4:7], v149, s[8:9]
	ds_read_b128 v[0:3], v13
	s_mov_b32 s28, 0x3fb8aa3b
	s_mov_b32 s38, 0xc2ce8ed0
	s_mov_b32 s39, 0x42b17218
	v_mov_b32_e32 v33, 0x7f800000
	v_readlane_b32 s48, v253, 35
	v_readlane_b32 s54, v253, 41
	v_readlane_b32 s55, v253, 42
	v_readlane_b32 s49, v253, 36
	v_readlane_b32 s50, v253, 37
	v_readlane_b32 s51, v253, 38
	v_readlane_b32 s52, v253, 39
	v_readlane_b32 s53, v253, 40
	v_readlane_b32 s56, v253, 43
	v_readlane_b32 s57, v253, 44
	v_readlane_b32 s58, v253, 45
	v_readlane_b32 s59, v253, 46
	v_readlane_b32 s60, v253, 47
	v_readlane_b32 s61, v253, 48
	v_readlane_b32 s62, v253, 49
	v_readlane_b32 s63, v253, 50
	s_waitcnt vmcnt(0) lgkmcnt(0)
; DI void row2_phase(const Params& P, int l, int r_begin, char* smem) {
;     ...
;       for (int j = 0; j < 4; j++) gl[j] = L[j] + P.b_group[l * 4 + j];
;       float gm = gl[0];
; #pragma unroll
;       for (int j = 1; j < 4; j++) if (gl[j] > gm) { gm = gl[j]; gi = j; }
;       float gs = 0.f;
; #pragma unroll
;       for (int j = 0; j < 4; j++) gs += expf(gl[j] - gm);
;       const float pg = 1.f / gs;
;       float el[8];
; #pragma unroll
;       for (int j = 0; j < 8; j++) el[j] = L[4 + gi * 8 + j] + P.b_router[l * 32 + gi * 8 + j];
	v_pk_add_f32 v[0:1], v[0:1], v[4:5]
	s_nop 0
	v_cmp_gt_f32_e32 vcc, v1, v0
	v_add_f32_e32 v2, v2, v6
	v_add_f32_e32 v3, v3, v7
	v_cndmask_b32_e32 v4, v0, v1, vcc
	v_cmp_gt_f32_e64 s[0:1], v2, v4
	s_nop 1
	v_cndmask_b32_e64 v4, v4, v2, s[0:1]
	v_cmp_gt_f32_e64 s[4:5], v3, v4
	s_nop 1
	v_cndmask_b32_e64 v4, v4, v3, s[4:5]
	v_sub_f32_e32 v5, v0, v4
	v_sub_f32_e32 v0, v1, v4
	v_mul_f32_e32 v1, 0x3fb8aa3b, v0
	v_fma_f32 v6, v0, s28, -v1
	v_rndne_f32_e32 v7, v1
	v_fmac_f32_e32 v6, 0x32a5705f, v0
	v_sub_f32_e32 v1, v1, v7
	v_add_f32_e32 v1, v1, v6
	v_exp_f32_e32 v1, v1
	v_cvt_i32_f32_e32 v6, v7
	v_cmp_ngt_f32_e64 s[6:7], s38, v0
	v_ldexp_f32 v1, v1, v6
	s_nop 0
	v_cndmask_b32_e64 v1, 0, v1, s[6:7]
	v_cmp_nlt_f32_e64 s[6:7], s39, v0
	v_sub_f32_e32 v0, v2, v4
	s_nop 0
	v_cndmask_b32_e64 v21, v33, v1, s[6:7]
	v_mul_f32_e32 v1, 0x3fb8aa3b, v0
	v_fma_f32 v2, v0, s28, -v1
	v_rndne_f32_e32 v6, v1
	v_fmac_f32_e32 v2, 0x32a5705f, v0
	v_sub_f32_e32 v1, v1, v6
	v_add_f32_e32 v1, v1, v2
	v_exp_f32_e32 v1, v1
	v_cvt_i32_f32_e32 v2, v6
	v_cmp_ngt_f32_e64 s[6:7], s38, v0
	v_ldexp_f32 v1, v1, v2
	s_nop 0
	v_cndmask_b32_e64 v1, 0, v1, s[6:7]
	v_cmp_nlt_f32_e64 s[6:7], s39, v0
	v_sub_f32_e32 v0, v3, v4
	v_or_b32_e32 v4, v56, v53
	v_cndmask_b32_e64 v30, v33, v1, s[6:7]
	v_mul_f32_e32 v1, 0x3fb8aa3b, v0
	v_fma_f32 v2, v0, s28, -v1
	v_rndne_f32_e32 v3, v1
	v_fmac_f32_e32 v2, 0x32a5705f, v0
	v_sub_f32_e32 v1, v1, v3
	v_add_f32_e32 v1, v1, v2
	v_exp_f32_e32 v1, v1
	v_cvt_i32_f32_e32 v2, v3
	v_cmp_ngt_f32_e64 s[6:7], s38, v0
	v_ldexp_f32 v1, v1, v2
	s_nop 0
	v_cndmask_b32_e64 v1, 0, v1, s[6:7]
	v_cmp_nlt_f32_e64 s[6:7], s39, v0
	v_cndmask_b32_e64 v0, 0, 8, vcc
	v_cndmask_b32_e64 v0, v0, 16, s[0:1]
	v_cndmask_b32_e64 v32, v0, 24, s[4:5]
	v_cndmask_b32_e64 v31, v33, v1, s[6:7]
	v_or_b32_e32 v0, s23, v32
	v_mov_b32_e32 v1, v149
	v_lshl_add_u32 v6, v32, 2, v13
	v_lshl_add_u64 v[10:11], v[0:1], 2, s[54:55]
	ds_read_b128 v[0:3], v6 offset:16
	ds_read_b128 v[6:9], v6 offset:32
	global_load_dwordx4 v[22:25], v[10:11], off offset:16
	global_load_dwordx4 v[26:29], v[10:11], off
	v_mul_f32_e32 v10, 0x3fb8aa3b, v5
	v_fma_f32 v11, v5, s28, -v10
	v_fmac_f32_e32 v11, 0x32a5705f, v5
	v_cmp_ngt_f32_e32 vcc, s38, v5
	s_mov_b32 s6, 0xff61b1e6
	s_waitcnt vmcnt(1) lgkmcnt(0)
	v_add_f32_e32 v6, v6, v22
	v_rndne_f32_e32 v22, v10
	v_sub_f32_e32 v10, v10, v22
	v_add_f32_e32 v10, v10, v11
	v_exp_f32_e32 v10, v10
	v_cvt_i32_f32_e32 v11, v22
	s_waitcnt vmcnt(0)
; DI void row2_phase(const Params& P, int l, int r_begin, char* smem) {
;     ...
;       for (int j = 0; j < 4; j++) gl[j] = L[j] + P.b_group[l * 4 + j];
;       float gm = gl[0];
; #pragma unroll
;       for (int j = 1; j < 4; j++) if (gl[j] > gm) { gm = gl[j]; gi = j; }
;       float gs = 0.f;
; #pragma unroll
;       for (int j = 0; j < 4; j++) gs += expf(gl[j] - gm);
;       const float pg = 1.f / gs;
;       float el[8];
; #pragma unroll
;       for (int j = 0; j < 8; j++) el[j] = L[4 + gi * 8 + j] + P.b_router[l * 32 + gi * 8 + j];
;       int i0 = 0; float v0 = el[0];
; #pragma unroll
;       for (int j = 1; j < 8; j++) if (el[j] > v0) { v0 = el[j]; i0 = j; }
;       int i1 = -1; float v1 = -3.0e38f;
; #pragma unroll
;       for (int j = 0; j < 8; j++) if (j != i0 && el[j] > v1) { v1 = el[j]; i1 = j; }
;       const float ex = expf(v1 - v0);
;       const float w0 = pg / (1.f + ex), w1 = pg * ex / (1.f + ex);
;       const int e0 = gi * 8 + i0, e1 = gi * 8 + i1;
;       int p0 = atomicAdd(&P.cnt[l * 32 + e0], 1); P.list[(size_t)e0 * LCAP + p0] = 2 * r; P.listW[(size_t)e0 * LCAP + p0] = w0;
;       int p1 = atomicAdd(&P.cnt[l * 32 + e1], 1); P.list[(size_t)e1 * LCAP + p1] = 2 * r + 1; P.listW[(size_t)e1 * LCAP + p1] = w1;
	v_pk_add_f32 v[0:1], v[0:1], v[26:27]
	v_add_f32_e32 v2, v2, v28
	v_add_f32_e32 v3, v3, v29
	v_ldexp_f32 v10, v10, v11
	v_cndmask_b32_e32 v10, 0, v10, vcc
	v_cmp_nlt_f32_e32 vcc, s39, v5
	v_add_f32_e32 v7, v7, v23
	v_add_f32_e32 v8, v8, v24
	v_cndmask_b32_e32 v5, v33, v10, vcc
	v_cmp_gt_f32_e32 vcc, v1, v0
	v_add_f32_e32 v9, v9, v25
	v_cmp_nlt_f32_e64 s[6:7], s6, v0
	v_cndmask_b32_e32 v11, v0, v1, vcc
	v_cndmask_b32_e64 v10, 0, 1, vcc
	v_cmp_gt_f32_e32 vcc, v2, v11
	v_mov_b32_e32 v22, 0xff61b1e6
	v_add_f32_e32 v5, v5, v21
	v_cndmask_b32_e32 v11, v11, v2, vcc
	v_cndmask_b32_e64 v10, v10, 2, vcc
	v_cmp_gt_f32_e32 vcc, v3, v11
	v_add_f32_e32 v5, v30, v5
	v_add_f32_e32 v5, v31, v5
	v_cndmask_b32_e32 v11, v11, v3, vcc
	v_cndmask_b32_e64 v10, v10, 3, vcc
	v_cmp_gt_f32_e32 vcc, v6, v11
	s_nop 1
	v_cndmask_b32_e32 v11, v11, v6, vcc
	v_cndmask_b32_e64 v10, v10, 4, vcc
	v_cmp_gt_f32_e32 vcc, v7, v11
	s_nop 1
	v_cndmask_b32_e32 v11, v11, v7, vcc
	v_cndmask_b32_e64 v10, v10, 5, vcc
	v_cmp_gt_f32_e32 vcc, v8, v11
	s_nop 1
	v_cndmask_b32_e32 v11, v11, v8, vcc
	v_cndmask_b32_e64 v10, v10, 6, vcc
	v_cmp_ngt_f32_e64 s[0:1], v9, v11
	s_nop 1
	v_cndmask_b32_e64 v10, 7, v10, s[0:1]
	v_cmp_eq_u32_e64 s[4:5], 0, v10
	s_or_b64 s[4:5], s[4:5], s[6:7]
	v_cndmask_b32_e64 v11, v9, v11, s[0:1]
	v_cndmask_b32_e64 v0, v0, v22, s[4:5]
	v_cndmask_b32_e64 v21, 0, -1, s[4:5]
	v_cmp_ne_u32_e64 s[4:5], 1, v10
	v_cmp_gt_f32_e64 s[6:7], v1, v0
	s_and_b64 s[4:5], s[4:5], s[6:7]
	v_cndmask_b32_e64 v0, v0, v1, s[4:5]
	v_cndmask_b32_e64 v21, v21, 1, s[4:5]
	v_cmp_ne_u32_e64 s[4:5], 2, v10
	v_cmp_gt_f32_e64 s[6:7], v2, v0
	s_and_b64 s[4:5], s[4:5], s[6:7]
	v_cndmask_b32_e64 v0, v0, v2, s[4:5]
	v_cndmask_b32_e64 v1, v21, 2, s[4:5]
	v_cmp_ne_u32_e64 s[4:5], 3, v10
	v_cmp_gt_f32_e64 s[6:7], v3, v0
	s_and_b64 s[4:5], s[4:5], s[6:7]
	v_cndmask_b32_e64 v0, v0, v3, s[4:5]
	v_cndmask_b32_e64 v1, v1, 3, s[4:5]
	v_cmp_ne_u32_e64 s[4:5], 4, v10
	v_cmp_gt_f32_e64 s[6:7], v6, v0
	s_and_b64 s[4:5], s[4:5], s[6:7]
	v_cndmask_b32_e64 v0, v0, v6, s[4:5]
	v_cndmask_b32_e64 v1, v1, 4, s[4:5]
	v_cmp_ne_u32_e64 s[4:5], 5, v10
	v_cmp_gt_f32_e64 s[6:7], v7, v0
	s_and_b64 s[4:5], s[4:5], s[6:7]
	v_cndmask_b32_e64 v0, v0, v7, s[4:5]
	v_cndmask_b32_e64 v1, v1, 5, s[4:5]
	s_and_b64 s[4:5], vcc, s[0:1]
	v_cmp_ngt_f32_e32 vcc, v8, v0
	s_or_b64 vcc, s[4:5], vcc
	v_readlane_b32 s4, v255, 24
	v_cndmask_b32_e32 v0, v8, v0, vcc
	v_cndmask_b32_e32 v1, 6, v1, vcc
	v_cmp_gt_f32_e32 vcc, v9, v0
	s_and_b64 vcc, s[0:1], vcc
	v_div_scale_f32 v2, s[0:1], v5, v5, 1.0
	v_rcp_f32_e32 v3, v2
	v_cndmask_b32_e64 v1, v1, 7, vcc
	v_cndmask_b32_e32 v0, v0, v9, vcc
	v_sub_f32_e32 v0, v0, v11
	v_fma_f32 v6, -v2, v3, 1.0
	v_fmac_f32_e32 v3, v6, v3
	v_div_scale_f32 v6, vcc, 1.0, v5, 1.0
	v_mul_f32_e32 v7, v6, v3
	v_fma_f32 v8, -v2, v7, v6
	v_fmac_f32_e32 v7, v8, v3
	v_fma_f32 v2, -v2, v7, v6
	v_div_fmas_f32 v2, v2, v3, v7
	v_mul_f32_e32 v3, 0x3fb8aa3b, v0
	v_div_fixup_f32 v2, v2, v5, 1.0
	v_fma_f32 v5, v0, s28, -v3
	v_rndne_f32_e32 v6, v3
	v_fmac_f32_e32 v5, 0x32a5705f, v0
	v_sub_f32_e32 v3, v3, v6
	v_add_f32_e32 v3, v3, v5
	v_exp_f32_e32 v3, v3
	v_cvt_i32_f32_e32 v5, v6
	v_cmp_ngt_f32_e32 vcc, s38, v0
	s_mov_b32 s28, 0x21000
	v_readlane_b32 s6, v254, 0
	v_ldexp_f32 v3, v3, v5
	v_cndmask_b32_e32 v3, 0, v3, vcc
	v_cmp_nlt_f32_e32 vcc, s39, v0
	v_readlane_b32 s5, v255, 25
	v_readlane_b32 s7, v254, 1
	v_cndmask_b32_e32 v0, v33, v3, vcc
	v_add_f32_e32 v3, 1.0, v0
	v_div_scale_f32 v5, s[0:1], v3, v3, v2
	v_rcp_f32_e32 v6, v5
	v_mul_f32_e32 v0, v2, v0
	v_fma_f32 v7, -v5, v6, 1.0
	v_fmac_f32_e32 v6, v7, v6
	v_div_scale_f32 v7, vcc, v2, v3, v2
	v_mul_f32_e32 v8, v7, v6
	v_fma_f32 v9, -v5, v8, v7
	v_fmac_f32_e32 v8, v9, v6
	v_fma_f32 v5, -v5, v8, v7
	v_div_fmas_f32 v5, v5, v6, v8
	v_div_fixup_f32 v8, v5, v3, v2
	v_div_scale_f32 v2, s[0:1], v3, v3, v0
	v_rcp_f32_e32 v5, v2
	v_readlane_b32 s0, v253, 63
	v_readlane_b32 s1, v255, 0
	v_fma_f32 v6, -v2, v5, 1.0
	v_fmac_f32_e32 v5, v6, v5
	v_div_scale_f32 v6, vcc, v0, v3, v0
	v_mul_f32_e32 v7, v6, v5
	v_fma_f32 v9, -v2, v7, v6
	v_fmac_f32_e32 v7, v9, v5
	v_fma_f32 v2, -v2, v7, v6
	v_div_fmas_f32 v2, v2, v5, v7
	v_or_b32_e32 v5, v10, v32
	v_div_fixup_f32 v2, v2, v3, v0
	v_add_u32_e32 v3, v1, v32
	v_or_b32_e32 v0, s23, v5
	v_mov_b32_e32 v1, v149
	v_mov_b32_e32 v9, 1
	v_mov_b32_e32 v6, 2
	v_mov_b32_e32 v7, 0x3080
	ds_add_rtn_u32 v7, v7, v6
	v_lshlrev_b32_e32 v0, 2, v5
	v_add_u32_e32 v0, 0x3000, v0
	ds_add_rtn_u32 v0, v0, v9
	v_lshlrev_b32_e32 v1, 2, v3
	v_add_u32_e32 v1, 0x3000, v1
	ds_add_rtn_u32 v1, v1, v9
	v_lshlrev_b32_e32 v6, 1, v4
	v_or_b32_e32 v9, 1, v6
	s_waitcnt lgkmcnt(0)
	v_lshl_or_b32 v0, v0, 5, v5
	v_lshl_or_b32 v1, v1, 5, v3
	v_lshlrev_b32_e32 v7, 4, v7
	v_add_u32_e32 v7, 0x10000, v7
	ds_write_b32 v7, v0
	ds_write_b32 v7, v6 offset:4
	ds_write_b32 v7, v8 offset:8
	ds_write_b32 v7, v1 offset:16
	ds_write_b32 v7, v9 offset:20
	ds_write_b32 v7, v2 offset:24
	s_branch .LBB0_544

; DI void wait_vm0() { asm volatile("s_waitcnt vmcnt(0)" ::: "memory"); }
; DI f4 mfma16(h8 a, h8 b, f4 c) { return __builtin_amdgcn_mfma_f32_16x16x32_f16(a, b, c, 0, 0, 0); }
; DI h8 lds128(unsigned a) { h8 r; asm volatile("ds_read_b128 %0, %1" : "=v"(r) : "v"(a)); return r; }
; DI void tie(h8& x) { asm volatile("" : "+v"(x)); }
; #define WAIT_LGKM(n) asm volatile("s_waitcnt lgkmcnt(" #n ")" ::: "memory")
; DI void raw_barrier() { asm volatile("" ::: "memory"); __builtin_amdgcn_s_barrier(); asm volatile("" ::: "memory"); }
; template <bool PRE = false, class AF, class BF>
; DI void gemm256(AF aptr, BF bptr, int nk, char* smem, f4 (&acc)[8][4]) {
;     ...
;   if (!PRE) { issue(0, 0); if (nk > 1) issue(1, 1); }
;   int st = 0;
; #pragma unroll 1
;   for (int kt = 0; kt < nk; kt++) {
;     if (kt + 1 < nk) asm volatile("s_waitcnt vmcnt(12)" ::: "memory"); else wait_vm0();
;     raw_barrier();
;     if (kt + 2 < nk) issue(kt + 2, st == 0 ? 2 : st - 1);
;     const unsigned base = sbase + st * 49152;
;     st = st == 2 ? 0 : st + 1;
;     h8 a0[8], b0[4], a1[8], b1[4];
; #pragma unroll
;     for (int m = 0; m < 8; m++) a0[m] = lds128(base + offA + m * 2048);
; #pragma unroll
;     for (int n = 0; n < 4; n++) b0[n] = lds128(base + offB + n * 2048);
; #pragma unroll
;     for (int m = 0; m < 8; m++) a1[m] = lds128(base + (offA ^ 64) + m * 2048);
; #pragma unroll
;     for (int n = 0; n < 4; n++) b1[n] = lds128(base + (offB ^ 64) + n * 2048);
;     WAIT_LGKM(12);
; #pragma unroll
;     for (int m = 0; m < 8; m++) tie(a0[m]);
; #pragma unroll
;     for (int n = 0; n < 4; n++) tie(b0[n]);
; #pragma unroll
;     for (int m = 0; m < 8; m++)
; #pragma unroll
;       for (int n = 0; n < 4; n++) acc[m][n] = mfma16(a0[m], b0[n], acc[m][n]);
; DI void moe_e1_phase(const Params& P, int l, char* smem, int* tb) {
;     ...
;     gemm256<true>([&](int i) { return P.hx + (size_t)tok[i] * D + sc; },
;                   [&](int i) { return ((i & 1) ? w3 : w1) + (size_t)((i >> 1) * 32 + srow) * 1024; }, 16, smem, acc);
.LBB0_578:
	v_mov_b32_e32 v5, v172
	s_mov_b32 s5, 0x8040
	v_lshlrev_b32_e32 v7, 3, v5
	v_and_b32_e32 v9, 48, v5
	v_bitop3_b32 v7, v7, v9, s37 bitop3:0x6c
	v_lshlrev_b32_e32 v9, 7, v5
	v_and_b32_e32 v11, 0xffffc780, v9
	v_and_b32_e32 v9, 0x2780, v9
	v_or_b32_e32 v13, v7, v9
	v_or_b32_e32 v33, v7, v11
	v_or_b32_e32 v35, 0x8000, v13
	v_lshlrev_b32_e32 v37, 4, v5
	v_bitop3_b32 v39, v7, 64, v11 bitop3:0x36
	v_bitop3_b32 v41, v7, s5, v9 bitop3:0x36
	v_ashrrev_i32_e32 v19, 31, v18
	v_ashrrev_i32_e32 v17, 31, v16
	v_ashrrev_i32_e32 v15, 31, v14
	v_ashrrev_i32_e32 v13, 31, v12
	v_ashrrev_i32_e32 v11, 31, v10
	v_ashrrev_i32_e32 v9, 31, v8
	v_ashrrev_i32_e32 v7, 31, v6
	v_ashrrev_i32_e32 v5, 31, v4
	v_lshlrev_b64 v[18:19], 11, v[18:19]
	v_lshlrev_b64 v[16:17], 11, v[16:17]
	v_lshlrev_b64 v[14:15], 11, v[14:15]
	v_lshlrev_b64 v[12:13], 11, v[12:13]
	v_lshlrev_b64 v[10:11], 11, v[10:11]
	v_lshlrev_b64 v[8:9], 11, v[8:9]
	v_lshlrev_b64 v[6:7], 11, v[6:7]
	v_lshlrev_b64 v[4:5], 11, v[4:5]
	v_lshl_add_u64 v[58:59], v[2:3], 0, v[48:49]
	v_lshl_add_u64 v[60:61], v[0:1], 0, v[48:49]
	v_lshl_add_u64 v[62:63], v[54:55], 0, v[4:5]
	v_lshl_add_u64 v[64:65], v[54:55], 0, v[6:7]
	v_lshl_add_u64 v[66:67], v[54:55], 0, v[8:9]
	v_lshl_add_u64 v[68:69], v[54:55], 0, v[10:11]
	v_lshl_add_u64 v[70:71], v[54:55], 0, v[12:13]
	v_lshl_add_u64 v[72:73], v[54:55], 0, v[14:15]
	v_lshl_add_u64 v[74:75], v[54:55], 0, v[16:17]
	v_lshl_add_u64 v[76:77], v[54:55], 0, v[18:19]
	s_mov_b32 s5, 0
	s_mov_b64 s[6:7], 0
	s_mov_b32 s29, 0
	v_readfirstlane_b32 s100, v37
	s_waitcnt vmcnt(12)
	s_barrier
	s_add_u32 s101, s100, 0x18000
	s_add_u32 m0, s101, 0x0
	v_lshl_add_u64 v[14:15], v[76:77], 0, s[6:7]
	global_load_lds_dwordx4 v[14:15], off
	s_add_u32 m0, s101, 0x1000
	v_lshl_add_u64 v[14:15], v[74:75], 0, s[6:7]
	global_load_lds_dwordx4 v[14:15], off
	s_add_u32 m0, s101, 0x2000
	v_lshl_add_u64 v[14:15], v[72:73], 0, s[6:7]
	global_load_lds_dwordx4 v[14:15], off
	s_add_u32 m0, s101, 0x3000
	v_lshl_add_u64 v[14:15], v[70:71], 0, s[6:7]
	global_load_lds_dwordx4 v[14:15], off
	s_add_u32 m0, s101, 0x4000
	v_lshl_add_u64 v[14:15], v[68:69], 0, s[6:7]
	global_load_lds_dwordx4 v[14:15], off
	s_add_u32 m0, s101, 0x5000
	v_lshl_add_u64 v[14:15], v[66:67], 0, s[6:7]
	global_load_lds_dwordx4 v[14:15], off
	ds_read_b128 v[116:119], v35 offset:0
	ds_read_b128 v[120:123], v35 offset:2048
	ds_read_b128 v[124:127], v35 offset:4096
	ds_read_b128 v[128:131], v35 offset:6144
	ds_read_b128 v[84:87], v33 offset:0
	ds_read_b128 v[88:91], v33 offset:2048
	ds_read_b128 v[92:95], v33 offset:4096
	ds_read_b128 v[96:99], v33 offset:6144
	ds_read_b128 v[100:103], v33 offset:8192
	ds_read_b128 v[104:107], v33 offset:10240
	ds_read_b128 v[108:111], v33 offset:12288
	ds_read_b128 v[112:115], v33 offset:14336
	s_mul_i32 s35, s29, 0xc000
	v_add_u32_e32 v8, s35, v39
	v_add_u32_e32 v9, s35, v41
	s_add_u32 s101, s29, 2
	s_sub_u32 s34, s101, 3
	s_cmp_lt_u32 s101, 3
	s_cselect_b32 s101, s101, s34
	s_mul_i32 s101, s101, 0xc000
	s_add_u32 s101, s101, s100
	s_waitcnt lgkmcnt(0)
	v_mfma_f32_16x16x32_f16 a[0:3], v[84:87], v[116:119], 0
	ds_read_b128 a[200:203], v9 offset:0
	v_mfma_f32_16x16x32_f16 a[4:7], v[84:87], v[120:123], 0
	s_add_u32 m0, s101, 0x6000
	v_lshl_add_u64 v[14:15], v[64:65], 0, s[6:7]
	global_load_lds_dwordx4 v[14:15], off
	v_mfma_f32_16x16x32_f16 a[8:11], v[84:87], v[124:127], 0
	ds_read_b128 a[204:207], v9 offset:2048
	v_mfma_f32_16x16x32_f16 a[16:19], v[84:87], v[128:131], 0
	v_mfma_f32_16x16x32_f16 a[32:35], v[88:91], v[116:119], 0
	ds_read_b128 a[208:211], v9 offset:4096
	v_mfma_f32_16x16x32_f16 a[48:51], v[88:91], v[120:123], 0
	s_add_u32 m0, s101, 0x7000
	v_lshl_add_u64 v[14:15], v[62:63], 0, s[6:7]
	global_load_lds_dwordx4 v[14:15], off
	v_mfma_f32_16x16x32_f16 a[64:67], v[88:91], v[124:127], 0
	ds_read_b128 a[212:215], v9 offset:6144
	v_mfma_f32_16x16x32_f16 a[80:83], v[88:91], v[128:131], 0
	v_mfma_f32_16x16x32_f16 a[96:99], v[92:95], v[116:119], 0
	ds_read_b128 v[132:135], v8 offset:0
	v_mfma_f32_16x16x32_f16 a[112:115], v[92:95], v[120:123], 0
	v_lshl_add_u64 v[10:11], v[58:59], 0, s[6:7]
	s_add_u32 m0, s101, 0x8000
	v_lshl_add_u64 v[14:15], v[10:11], 0, s[74:75]
	global_load_lds_dwordx4 v[14:15], off
	v_mfma_f32_16x16x32_f16 a[124:127], v[92:95], v[124:127], 0
	ds_read_b128 v[136:139], v8 offset:2048
	v_mfma_f32_16x16x32_f16 a[120:123], v[92:95], v[128:131], 0
	v_mfma_f32_16x16x32_f16 a[116:119], v[96:99], v[116:119], 0
	ds_read_b128 v[0:3], v8 offset:4096
	v_mfma_f32_16x16x32_f16 a[108:111], v[96:99], v[120:123], 0
	v_lshl_add_u64 v[12:13], v[60:61], 0, s[6:7]
	s_add_u32 m0, s101, 0x9000
	v_lshl_add_u64 v[14:15], v[12:13], 0, s[74:75]
	global_load_lds_dwordx4 v[14:15], off
	v_mfma_f32_16x16x32_f16 a[104:107], v[96:99], v[124:127], 0
	ds_read_b128 v[4:7], v8 offset:6144
	v_mfma_f32_16x16x32_f16 a[100:103], v[96:99], v[128:131], 0
	v_mfma_f32_16x16x32_f16 a[92:95], v[100:103], v[116:119], 0
	ds_read_b128 v[144:147], v8 offset:8192
	v_mfma_f32_16x16x32_f16 a[88:91], v[100:103], v[120:123], 0
	s_add_u32 m0, s101, 0xa000
	v_lshl_add_u64 v[14:15], v[10:11], 0, s[76:77]
	global_load_lds_dwordx4 v[14:15], off
	v_mfma_f32_16x16x32_f16 a[84:87], v[100:103], v[124:127], 0
	ds_read_b128 v[140:143], v8 offset:10240
	v_mfma_f32_16x16x32_f16 a[76:79], v[100:103], v[128:131], 0
	v_mfma_f32_16x16x32_f16 a[72:75], v[104:107], v[116:119], 0
	ds_read_b128 v[150:153], v8 offset:12288
	v_mfma_f32_16x16x32_f16 a[68:71], v[104:107], v[120:123], 0
	s_add_u32 m0, s101, 0xb000
	v_lshl_add_u64 v[14:15], v[12:13], 0, s[76:77]
	global_load_lds_dwordx4 v[14:15], off
	v_mfma_f32_16x16x32_f16 a[60:63], v[104:107], v[124:127], 0
	ds_read_b128 v[154:157], v8 offset:14336
	v_mfma_f32_16x16x32_f16 a[56:59], v[104:107], v[128:131], 0
	v_mfma_f32_16x16x32_f16 a[52:55], v[108:111], v[116:119], 0
	v_mfma_f32_16x16x32_f16 a[44:47], v[108:111], v[120:123], 0
	s_add_u32 s34, s29, 1
	v_mfma_f32_16x16x32_f16 a[40:43], v[108:111], v[124:127], 0
	s_cmp_eq_u32 s34, 3
	v_mfma_f32_16x16x32_f16 a[36:39], v[108:111], v[128:131], 0
	s_cselect_b32 s34, 0, s34
	v_mfma_f32_16x16x32_f16 a[28:31], v[112:115], v[116:119], 0
	s_mul_i32 s35, s34, 0xc000
	v_mfma_f32_16x16x32_f16 a[24:27], v[112:115], v[120:123], 0
	v_add_u32_e32 v22, s35, v33
	v_mfma_f32_16x16x32_f16 a[20:23], v[112:115], v[124:127], 0
	v_add_u32_e32 v23, s35, v35
	v_mfma_f32_16x16x32_f16 a[12:15], v[112:115], v[128:131], 0
	s_branch .Lg_e1_mid

; DI void moe_e2_phase(const Params& P, int l, char* smem, int* tb) {
;     ...
;     int e = 0;
;     while (tb[e + 1] <= rt) e++;
;     const int rl = rt - tb[e], cnt = P.cnt[l * 32 + e];
;     const int* lst = P.list + (size_t)e * LCAP; const float* lstw = P.listW + (size_t)e * LCAP;
;     int aa[2][8]; float ww[2][8];
; #pragma unroll
;     for (int h = 0; h < 2; h++)
; #pragma unroll
;       for (int i = 0; i < 8; i++) {
;         const int idx = rl * 256 + wr2 * 128 + h * 64 + ((i * 64 + lane2) >> 3);
;         const int ic = min(idx, cnt - 1);
;         const int av = lst[ic]; const float wv = lstw[ic];
;         aa[h][i] = idx < cnt ? av : -1; ww[h][i] = wv;
;       }
.LBB0_612:
	s_add_i32 s84, s1, s20
	v_mov_b32_e32 v0, s2
	s_lshl_b64 s[2:3], s[84:85], 2
	v_readlane_b32 s4, v253, 63
	v_readlane_b32 s5, v255, 0
	s_add_u32 s2, s4, s2
	s_addc_u32 s3, s5, s3
	s_lshl_b32 s2, s1, 2
	s_add_i32 s2, s2, 0x24000
	v_mov_b32_e32 v33, s2
	ds_read_b32 v33, v33
	ds_read_b32 v0, v0
	v_and_b32_e32 v1, 0xffffff80, v87
	s_mul_hi_u32 s3, s1, 0x84000
	s_mul_i32 s1, s1, 0x84000
	v_readlane_b32 s4, v255, 24
	s_waitcnt lgkmcnt(0)
	v_sub_u32_e32 v0, s0, v0
	v_lshl_add_u32 v1, v0, 8, v1
	v_bfe_u32 v86, v87, 3, 3
	v_readlane_b32 s5, v255, 25
	s_add_u32 s4, s4, s1
	v_or_b32_e32 v88, v1, v86
	s_addc_u32 s5, s5, s3
	v_readlane_b32 s22, v254, 0
	v_readlane_b32 s23, v254, 1
	s_add_u32 s2, s22, s1
	s_addc_u32 s3, s23, s3
	v_or_b32_e32 v83, 8, v86
	v_or_b32_e32 v84, v1, v83
	v_or_b32_e32 v80, 16, v86
	v_or_b32_e32 v81, v1, v80
	v_or_b32_e32 v77, 24, v86
	v_or_b32_e32 v78, v1, v77
	v_or_b32_e32 v74, 32, v86
	v_or_b32_e32 v75, v1, v74
	v_or_b32_e32 v69, 40, v86
	v_or_b32_e32 v70, v1, v69
	v_or_b32_e32 v66, 48, v86
	v_or_b32_e32 v67, v1, v66
	v_or_b32_e32 v63, 56, v86
	v_or_b32_e32 v64, v1, v63
	v_or_b32_e32 v1, 64, v1
	v_or_b32_e32 v72, v1, v86
	v_or_b32_e32 v59, v1, v83
	v_or_b32_e32 v55, v1, v80
	v_or_b32_e32 v51, v1, v77
	v_or_b32_e32 v47, v1, v74
	v_or_b32_e32 v43, v1, v69
	v_or_b32_e32 v39, v1, v66
	v_or_b32_e32 v35, v1, v63
	s_mov_b32 s1, 0x8040
	s_waitcnt lgkmcnt(0)
	v_add_u32_e32 v0, -1, v33
	v_min_i32_e32 v2, v88, v0
	v_ashrrev_i32_e32 v3, 31, v2
	v_lshlrev_b64 v[2:3], 2, v[2:3]
	v_lshl_add_u64 v[4:5], s[4:5], 0, v[2:3]
	v_lshl_add_u64 v[2:3], s[2:3], 0, v[2:3]
	global_load_dword v89, v[4:5], off
	global_load_dword v62, v[2:3], off
	v_min_i32_e32 v2, v84, v0
	v_ashrrev_i32_e32 v3, 31, v2
	v_lshlrev_b64 v[2:3], 2, v[2:3]
	v_lshl_add_u64 v[4:5], s[4:5], 0, v[2:3]
	v_lshl_add_u64 v[2:3], s[2:3], 0, v[2:3]
	global_load_dword v85, v[4:5], off
	global_load_dword v60, v[2:3], off
	v_min_i32_e32 v2, v81, v0
	v_ashrrev_i32_e32 v3, 31, v2
	v_lshlrev_b64 v[2:3], 2, v[2:3]
	v_lshl_add_u64 v[4:5], s[4:5], 0, v[2:3]
	v_lshl_add_u64 v[2:3], s[2:3], 0, v[2:3]
	global_load_dword v82, v[4:5], off
	global_load_dword v58, v[2:3], off
	v_min_i32_e32 v2, v78, v0
	v_ashrrev_i32_e32 v3, 31, v2
	v_lshlrev_b64 v[2:3], 2, v[2:3]
	v_lshl_add_u64 v[4:5], s[4:5], 0, v[2:3]
	v_lshl_add_u64 v[2:3], s[2:3], 0, v[2:3]
	global_load_dword v79, v[4:5], off
	global_load_dword v56, v[2:3], off
	v_min_i32_e32 v2, v75, v0
	v_ashrrev_i32_e32 v3, 31, v2
	v_lshlrev_b64 v[2:3], 2, v[2:3]
	v_lshl_add_u64 v[4:5], s[4:5], 0, v[2:3]
	v_lshl_add_u64 v[2:3], s[2:3], 0, v[2:3]
	global_load_dword v76, v[4:5], off
	global_load_dword v54, v[2:3], off
	v_min_i32_e32 v2, v70, v0
	v_ashrrev_i32_e32 v3, 31, v2
	v_lshlrev_b64 v[2:3], 2, v[2:3]
	v_lshl_add_u64 v[4:5], s[4:5], 0, v[2:3]
	v_lshl_add_u64 v[2:3], s[2:3], 0, v[2:3]
	global_load_dword v71, v[4:5], off
	global_load_dword v52, v[2:3], off
	v_min_i32_e32 v2, v67, v0
	v_ashrrev_i32_e32 v3, 31, v2
	v_lshlrev_b64 v[2:3], 2, v[2:3]
	v_lshl_add_u64 v[4:5], s[4:5], 0, v[2:3]
	v_lshl_add_u64 v[2:3], s[2:3], 0, v[2:3]
	global_load_dword v68, v[4:5], off
	global_load_dword v50, v[2:3], off
	v_min_i32_e32 v2, v64, v0
	v_ashrrev_i32_e32 v3, 31, v2
	v_lshlrev_b64 v[2:3], 2, v[2:3]
	v_lshl_add_u64 v[4:5], s[4:5], 0, v[2:3]
	v_lshl_add_u64 v[2:3], s[2:3], 0, v[2:3]
	global_load_dword v65, v[4:5], off
	global_load_dword v48, v[2:3], off
	v_min_i32_e32 v2, v72, v0
	v_ashrrev_i32_e32 v3, 31, v2
	v_lshlrev_b64 v[2:3], 2, v[2:3]
	v_lshl_add_u64 v[4:5], s[4:5], 0, v[2:3]
	v_lshl_add_u64 v[2:3], s[2:3], 0, v[2:3]
	global_load_dword v73, v[4:5], off
	global_load_dword v46, v[2:3], off
	v_min_i32_e32 v2, v59, v0
	v_ashrrev_i32_e32 v3, 31, v2
	v_lshlrev_b64 v[2:3], 2, v[2:3]
	v_lshl_add_u64 v[4:5], s[4:5], 0, v[2:3]
	v_lshl_add_u64 v[2:3], s[2:3], 0, v[2:3]
	global_load_dword v61, v[4:5], off
	global_load_dword v44, v[2:3], off
	v_min_i32_e32 v2, v55, v0
	v_ashrrev_i32_e32 v3, 31, v2
	v_lshlrev_b64 v[2:3], 2, v[2:3]
	v_lshl_add_u64 v[4:5], s[4:5], 0, v[2:3]
	v_lshl_add_u64 v[2:3], s[2:3], 0, v[2:3]
	global_load_dword v57, v[4:5], off
	global_load_dword v42, v[2:3], off
	v_min_i32_e32 v2, v51, v0
	v_ashrrev_i32_e32 v3, 31, v2
	v_lshlrev_b64 v[2:3], 2, v[2:3]
	v_lshl_add_u64 v[4:5], s[4:5], 0, v[2:3]
	v_lshl_add_u64 v[2:3], s[2:3], 0, v[2:3]
	global_load_dword v53, v[4:5], off
	global_load_dword v40, v[2:3], off
	v_min_i32_e32 v2, v47, v0
	v_ashrrev_i32_e32 v3, 31, v2
	v_lshlrev_b64 v[2:3], 2, v[2:3]
	v_lshl_add_u64 v[4:5], s[4:5], 0, v[2:3]
	v_lshl_add_u64 v[2:3], s[2:3], 0, v[2:3]
	global_load_dword v49, v[4:5], off
	global_load_dword v38, v[2:3], off
	v_min_i32_e32 v2, v43, v0
	v_ashrrev_i32_e32 v3, 31, v2
	v_lshlrev_b64 v[2:3], 2, v[2:3]
	v_lshl_add_u64 v[4:5], s[4:5], 0, v[2:3]
	v_lshl_add_u64 v[2:3], s[2:3], 0, v[2:3]
	global_load_dword v45, v[4:5], off
	global_load_dword v36, v[2:3], off
	v_min_i32_e32 v2, v39, v0
	v_ashrrev_i32_e32 v3, 31, v2
	v_min_i32_e32 v0, v35, v0
	v_lshlrev_b64 v[2:3], 2, v[2:3]
	v_ashrrev_i32_e32 v1, 31, v0
	v_lshl_add_u64 v[4:5], s[4:5], 0, v[2:3]
	v_lshl_add_u64 v[2:3], s[2:3], 0, v[2:3]
	v_lshlrev_b64 v[0:1], 2, v[0:1]
	global_load_dword v41, v[4:5], off
	global_load_dword v34, v[2:3], off
	v_lshl_add_u64 v[2:3], s[4:5], 0, v[0:1]
	v_lshl_add_u64 v[0:1], s[2:3], 0, v[0:1]
	global_load_dword v37, v[2:3], off
	global_load_dword v32, v[0:1], off
	v_mov_b32_e32 v0, v172
	v_lshlrev_b32_e32 v1, 3, v0
	v_and_b32_e32 v2, 48, v0
	v_bitop3_b32 v1, v1, v2, s37 bitop3:0x6c
	v_lshlrev_b32_e32 v2, 7, v0
	v_and_b32_e32 v3, 0xffffc780, v2
	v_and_b32_e32 v2, 0x2780, v2
	v_or_b32_e32 v4, v1, v2
	v_or_b32_e32 v156, v1, v3
	v_or_b32_e32 v157, 0x8000, v4
	v_lshlrev_b32_e32 v158, 4, v0
	v_bitop3_b32 v159, v1, 64, v3 bitop3:0x36
	v_bitop3_b32 v160, v1, s1, v2 bitop3:0x36
	s_mov_b32 s1, 0
	s_mov_b64 s[2:3], 0
	s_mov_b32 s7, 0
	v_readfirstlane_b32 s100, v158
	s_waitcnt vmcnt(44)
	s_barrier
; DI void wait_vm0() { asm volatile("s_waitcnt vmcnt(0)" ::: "memory"); }
; DI f4 mfma16(h8 a, h8 b, f4 c) { return __builtin_amdgcn_mfma_f32_16x16x32_f16(a, b, c, 0, 0, 0); }
; DI h8 lds128(unsigned a) { h8 r; asm volatile("ds_read_b128 %0, %1" : "=v"(r) : "v"(a)); return r; }
; DI void tie(h8& x) { asm volatile("" : "+v"(x)); }
; #define WAIT_LGKM(n) asm volatile("s_waitcnt lgkmcnt(" #n ")" ::: "memory")
; DI void raw_barrier() { asm volatile("" ::: "memory"); __builtin_amdgcn_s_barrier(); asm volatile("" ::: "memory"); }
; template <bool PRE = false, class AF, class BF>
; DI void gemm256(AF aptr, BF bptr, int nk, char* smem, f4 (&acc)[8][4]) {
;     ...
;   if (!PRE) { issue(0, 0); if (nk > 1) issue(1, 1); }
;   int st = 0;
; #pragma unroll 1
;   for (int kt = 0; kt < nk; kt++) {
;     if (kt + 1 < nk) asm volatile("s_waitcnt vmcnt(12)" ::: "memory"); else wait_vm0();
;     raw_barrier();
;     if (kt + 2 < nk) issue(kt + 2, st == 0 ? 2 : st - 1);
;     const unsigned base = sbase + st * 49152;
;     st = st == 2 ? 0 : st + 1;
;     h8 a0[8], b0[4], a1[8], b1[4];
; #pragma unroll
;     for (int m = 0; m < 8; m++) a0[m] = lds128(base + offA + m * 2048);
; #pragma unroll
;     for (int n = 0; n < 4; n++) b0[n] = lds128(base + offB + n * 2048);
; #pragma unroll
;     for (int m = 0; m < 8; m++) a1[m] = lds128(base + (offA ^ 64) + m * 2048);
; #pragma unroll
;     for (int n = 0; n < 4; n++) b1[n] = lds128(base + (offB ^ 64) + n * 2048);
;     WAIT_LGKM(12);
; #pragma unroll
;     for (int m = 0; m < 8; m++) tie(a0[m]);
; #pragma unroll
;     for (int n = 0; n < 4; n++) tie(b0[n]);
; #pragma unroll
;     for (int m = 0; m < 8; m++)
; #pragma unroll
;       for (int n = 0; n < 4; n++) acc[m][n] = mfma16(a0[m], b0[n], acc[m][n]);
	s_add_u32 s101, s100, 0x18000
	v_lshl_add_u64 v[10:11], v[26:27], 0, s[2:3]
	s_add_u32 m0, s101, 0x0
	v_lshl_add_u64 v[14:15], v[10:11], 0, s[74:75]
	global_load_lds_dwordx4 v[14:15], off
	s_add_u32 m0, s101, 0x1000
	v_lshl_add_u64 v[14:15], v[10:11], 0, s[24:25]
	global_load_lds_dwordx4 v[14:15], off
	s_add_u32 m0, s101, 0x2000
	v_lshl_add_u64 v[14:15], v[10:11], 0, s[76:77]
	global_load_lds_dwordx4 v[14:15], off
	s_add_u32 m0, s101, 0x3000
	v_lshl_add_u64 v[14:15], v[10:11], 0, s[26:27]
	global_load_lds_dwordx4 v[14:15], off
	s_add_u32 m0, s101, 0x4000
	v_lshl_add_u64 v[14:15], v[10:11], 0, s[86:87]
	global_load_lds_dwordx4 v[14:15], off
	s_mov_b64 s[4:5], 0x28100
	s_add_u32 m0, s101, 0x5000
	v_lshl_add_u64 v[14:15], v[10:11], 0, s[4:5]
	global_load_lds_dwordx4 v[14:15], off
	ds_read_b128 v[122:125], v157 offset:0
	ds_read_b128 v[126:129], v157 offset:2048
	ds_read_b128 v[130:133], v157 offset:4096
	ds_read_b128 v[134:137], v157 offset:6144
	ds_read_b128 v[90:93], v156 offset:0
	ds_read_b128 v[94:97], v156 offset:2048
	ds_read_b128 v[98:101], v156 offset:4096
	ds_read_b128 v[102:105], v156 offset:6144
	ds_read_b128 v[106:109], v156 offset:8192
	ds_read_b128 v[110:113], v156 offset:10240
	ds_read_b128 v[114:117], v156 offset:12288
	ds_read_b128 v[118:121], v156 offset:14336
	s_mul_i32 s22, s7, 0xc000
	v_add_u32_e32 v8, s22, v159
	v_add_u32_e32 v9, s22, v160
	s_add_u32 s101, s7, 2
	s_sub_u32 s21, s101, 3
	s_cmp_lt_u32 s101, 3
	s_cselect_b32 s101, s101, s21
	s_mul_i32 s101, s101, 0xc000
	s_add_u32 s101, s101, s100
	s_waitcnt lgkmcnt(0)
	v_mfma_f32_16x16x32_f16 a[0:3], v[90:93], v[122:125], 0
	ds_read_b128 a[200:203], v9 offset:0
	v_mfma_f32_16x16x32_f16 a[4:7], v[90:93], v[126:129], 0
	v_lshl_add_u64 v[10:11], v[26:27], 0, s[2:3]
	s_add_u32 m0, s101, 0x6000
	v_lshl_add_u64 v[14:15], v[10:11], 0, s[80:81]
	global_load_lds_dwordx4 v[14:15], off
	v_mfma_f32_16x16x32_f16 a[8:11], v[90:93], v[130:133], 0
	ds_read_b128 a[204:207], v9 offset:2048
	v_mfma_f32_16x16x32_f16 a[16:19], v[90:93], v[134:137], 0
	v_mfma_f32_16x16x32_f16 a[32:35], v[94:97], v[122:125], 0
	ds_read_b128 a[208:211], v9 offset:4096
	v_mfma_f32_16x16x32_f16 a[48:51], v[94:97], v[126:129], 0
	s_mov_b64 s[4:5], 0x38100
	s_add_u32 m0, s101, 0x7000
	v_lshl_add_u64 v[14:15], v[10:11], 0, s[4:5]
	global_load_lds_dwordx4 v[14:15], off
	v_mfma_f32_16x16x32_f16 a[64:67], v[94:97], v[130:133], 0
	ds_read_b128 a[212:215], v9 offset:6144
	v_mfma_f32_16x16x32_f16 a[80:83], v[94:97], v[134:137], 0
	v_mfma_f32_16x16x32_f16 a[96:99], v[98:101], v[122:125], 0
	ds_read_b128 v[138:141], v8 offset:0
	v_mfma_f32_16x16x32_f16 a[112:115], v[98:101], v[126:129], 0
	v_lshl_add_u64 v[12:13], v[28:29], 0, s[2:3]
	s_add_u32 m0, s101, 0x8000
	v_lshl_add_u64 v[14:15], v[12:13], 0, s[74:75]
	global_load_lds_dwordx4 v[14:15], off
	v_mfma_f32_16x16x32_f16 a[124:127], v[98:101], v[130:133], 0
	ds_read_b128 v[142:145], v8 offset:2048
	v_mfma_f32_16x16x32_f16 a[120:123], v[98:101], v[134:137], 0
	v_mfma_f32_16x16x32_f16 a[116:119], v[102:105], v[122:125], 0
	ds_read_b128 v[0:3], v8 offset:4096
	v_mfma_f32_16x16x32_f16 a[108:111], v[102:105], v[126:129], 0
	s_add_u32 m0, s101, 0x9000
	v_lshl_add_u64 v[14:15], v[12:13], 0, s[24:25]
	global_load_lds_dwordx4 v[14:15], off
	v_mfma_f32_16x16x32_f16 a[104:107], v[102:105], v[130:133], 0
	ds_read_b128 v[4:7], v8 offset:6144
	v_mfma_f32_16x16x32_f16 a[100:103], v[102:105], v[134:137], 0
	v_mfma_f32_16x16x32_f16 a[92:95], v[106:109], v[122:125], 0
	ds_read_b128 v[152:155], v8 offset:8192
	v_mfma_f32_16x16x32_f16 a[88:91], v[106:109], v[126:129], 0
	s_add_u32 m0, s101, 0xa000
	v_lshl_add_u64 v[14:15], v[12:13], 0, s[76:77]
	global_load_lds_dwordx4 v[14:15], off
	v_mfma_f32_16x16x32_f16 a[84:87], v[106:109], v[130:133], 0
	ds_read_b128 v[162:165], v8 offset:10240
	v_mfma_f32_16x16x32_f16 a[76:79], v[106:109], v[134:137], 0
	v_mfma_f32_16x16x32_f16 a[72:75], v[110:113], v[122:125], 0
	ds_read_b128 v[166:169], v8 offset:12288
	v_mfma_f32_16x16x32_f16 a[68:71], v[110:113], v[126:129], 0
	s_add_u32 m0, s101, 0xb000
	v_lshl_add_u64 v[14:15], v[12:13], 0, s[26:27]
	global_load_lds_dwordx4 v[14:15], off
	v_mfma_f32_16x16x32_f16 a[60:63], v[110:113], v[130:133], 0
	ds_read_b128 v[180:183], v8 offset:14336
	v_mfma_f32_16x16x32_f16 a[56:59], v[110:113], v[134:137], 0
	v_mfma_f32_16x16x32_f16 a[52:55], v[114:117], v[122:125], 0
	v_mfma_f32_16x16x32_f16 a[44:47], v[114:117], v[126:129], 0
	s_add_u32 s21, s7, 1
	v_mfma_f32_16x16x32_f16 a[40:43], v[114:117], v[130:133], 0
	s_cmp_eq_u32 s21, 3
	v_mfma_f32_16x16x32_f16 a[36:39], v[114:117], v[134:137], 0
	s_cselect_b32 s21, 0, s21
	v_mfma_f32_16x16x32_f16 a[28:31], v[118:121], v[122:125], 0
	s_mul_i32 s22, s21, 0xc000
	v_mfma_f32_16x16x32_f16 a[24:27], v[118:121], v[126:129], 0
	v_add_u32_e32 v22, s22, v156
	v_mfma_f32_16x16x32_f16 a[20:23], v[118:121], v[130:133], 0
	v_add_u32_e32 v23, s22, v157
	v_mfma_f32_16x16x32_f16 a[12:15], v[118:121], v[134:137], 0
	s_branch .Lg_e2_mid
